# wave_sum butterflies (prep_dn, LN): ds_bpermute xor steps -> exact permlane32/16_swap + DPP row_ror adds
# speedup vs baseline: 1.0318x; 1.0318x over previous
.LBB0_40:
	s_nop 0
	v_mov_b32_e32 v1, v139
	v_cmp_lt_i32_e32 vcc, v179, v178
	v_ashrrev_i32_e32 v0, 5, v1
	v_and_b32_e32 v0, -2, v0
	v_add_u32_e32 v0, s5, v0
	v_lshlrev_b32_e32 v1, 2, v1
	v_and_b32_e32 v4, 0xfc, v1
	v_ashrrev_i32_e32 v1, 31, v0
	v_lshlrev_b64 v[2:3], 12, v[0:1]
	v_lshl_add_u64 v[2:3], s[14:15], 0, v[2:3]
	v_lshlrev_b32_e32 v136, 1, v4
	s_waitcnt vmcnt(8)
	v_lshl_add_u64 v[32:33], v[2:3], 0, v[136:137]
	global_load_dwordx2 v[36:37], v[32:33], off offset:2048
	global_load_dwordx2 v[38:39], v[32:33], off offset:2560
	global_load_dwordx2 v[40:41], v[32:33], off offset:3072
	global_load_dwordx2 v[42:43], v[32:33], off offset:3584
	v_add_u32_e32 v0, 1, v0
	v_ashrrev_i32_e32 v1, 31, v0
	v_lshlrev_b64 v[0:1], 12, v[0:1]
	v_lshl_add_u64 v[0:1], s[14:15], 0, v[0:1]
	v_lshl_add_u64 v[34:35], v[0:1], 0, v[136:137]
	global_load_dwordx2 v[44:45], v[34:35], off offset:2048
	global_load_dwordx2 v[46:47], v[34:35], off offset:2560
	global_load_dwordx2 v[48:49], v[34:35], off offset:3072
	global_load_dwordx2 v[50:51], v[34:35], off offset:3584
	v_cndmask_b32_e32 v52, v176, v179, vcc
	v_cmp_lt_i32_e32 vcc, v180, v178
	v_lshlrev_b32_e32 v84, 2, v52
	v_lshlrev_b32_e32 v4, 2, v4
	v_cndmask_b32_e32 v52, v176, v180, vcc
	v_cmp_lt_i32_e32 vcc, v181, v178
	v_lshlrev_b32_e32 v85, 2, v52
	global_load_dwordx4 v[24:27], v4, s[34:35]
	global_load_dwordx4 v[28:31], v4, s[96:97]
	global_load_dwordx4 v[16:19], v4, s[34:35] offset:1024
	global_load_dwordx4 v[20:23], v4, s[96:97] offset:1024
	global_load_dwordx4 v[8:11], v4, s[34:35] offset:2048
	global_load_dwordx4 v[12:15], v4, s[96:97] offset:2048
	global_load_dwordx4 v[0:3], v4, s[34:35] offset:3072
	s_nop 0
	global_load_dwordx4 v[4:7], v4, s[96:97] offset:3072
	v_cndmask_b32_e32 v52, v176, v181, vcc
	v_cmp_lt_i32_e32 vcc, v182, v178
	v_lshlrev_b32_e32 v86, 2, v52
	s_add_i32 s6, s6, s10
	v_cndmask_b32_e32 v52, v176, v182, vcc
	v_cmp_lt_i32_e32 vcc, v183, v178
	v_lshlrev_b32_e32 v87, 2, v52
	s_add_i32 s5, s5, s4
	v_cndmask_b32_e32 v52, v176, v183, vcc
	v_cmp_lt_i32_e32 vcc, v184, v178
	v_lshlrev_b32_e32 v88, 2, v52
	s_cmpk_gt_i32 s6, 0x5ff
	v_cndmask_b32_e32 v52, v176, v184, vcc
	v_lshlrev_b32_e32 v89, 2, v52
	s_waitcnt vmcnt(15)
	v_lshlrev_b32_e32 v60, 16, v36
	v_and_b32_e32 v61, 0xffff0000, v36
	s_waitcnt vmcnt(13)
	v_lshlrev_b32_e32 v54, 16, v40
	s_waitcnt vmcnt(12)
	v_lshlrev_b32_e32 v52, 16, v42
	v_and_b32_e32 v53, 0xffff0000, v42
	v_and_b32_e32 v55, 0xffff0000, v40
	v_lshlrev_b32_e32 v42, 16, v43
	v_lshlrev_b32_e32 v40, 16, v41
	v_mov_b32_e32 v56, v54
	v_mov_b32_e32 v57, v52
	v_mov_b32_e32 v58, v55
	v_mov_b32_e32 v59, v53
	v_and_b32_e32 v43, 0xffff0000, v43
	v_and_b32_e32 v41, 0xffff0000, v41
	v_pk_add_f32 v[56:57], v[56:57], v[58:59]
	v_mov_b32_e32 v58, v40
	v_mov_b32_e32 v59, v42
	v_pk_add_f32 v[56:57], v[56:57], v[58:59]
	v_mov_b32_e32 v58, v41
	v_mov_b32_e32 v59, v43
	v_pk_add_f32 v[56:57], v[56:57], v[58:59]
	v_lshlrev_b32_e32 v58, 16, v38
	v_and_b32_e32 v59, 0xffff0000, v38
	v_lshlrev_b32_e32 v38, 16, v39
	v_lshlrev_b32_e32 v36, 16, v37
	v_mov_b32_e32 v62, v60
	v_mov_b32_e32 v63, v58
	v_mov_b32_e32 v64, v61
	v_mov_b32_e32 v65, v59
	v_and_b32_e32 v39, 0xffff0000, v39
	v_and_b32_e32 v37, 0xffff0000, v37
	v_pk_add_f32 v[62:63], v[62:63], v[64:65]
	v_mov_b32_e32 v64, v36
	v_mov_b32_e32 v65, v38
	v_pk_add_f32 v[62:63], v[62:63], v[64:65]
	v_mov_b32_e32 v64, v37
	v_mov_b32_e32 v65, v39
	v_pk_add_f32 v[62:63], v[62:63], v[64:65]
	s_waitcnt vmcnt(9)
	v_lshlrev_b32_e32 v66, 16, v48
	v_add_f32_e32 v62, 0, v62
	v_add_f32_e32 v62, v62, v63
	v_add_f32_e32 v56, v62, v56
	v_add_f32_e32 v56, v56, v57
	ds_bpermute_b32 v57, v84, v56
	v_and_b32_e32 v67, 0xffff0000, v48
	v_lshlrev_b32_e32 v48, 16, v49
	v_mov_b32_e32 v68, v66
	v_mov_b32_e32 v70, v67
	s_waitcnt lgkmcnt(0)
	v_add_f32_e32 v56, v56, v57
	ds_bpermute_b32 v57, v85, v56
	v_and_b32_e32 v49, 0xffff0000, v49
	v_lshlrev_b32_e32 v72, 16, v44
	v_and_b32_e32 v73, 0xffff0000, v44
	v_lshlrev_b32_e32 v44, 16, v45
	s_waitcnt lgkmcnt(0)
	v_add_f32_e32 v56, v56, v57
	ds_bpermute_b32 v57, v86, v56
	v_mov_b32_e32 v74, v72
	v_mov_b32_e32 v76, v73
	v_and_b32_e32 v45, 0xffff0000, v45
	s_waitcnt lgkmcnt(0)
	v_add_f32_e32 v56, v56, v57
	ds_bpermute_b32 v57, v87, v56
	s_waitcnt lgkmcnt(0)
	v_add_f32_e32 v56, v56, v57
	ds_bpermute_b32 v57, v88, v56
	s_waitcnt lgkmcnt(0)
	v_add_f32_e32 v56, v56, v57
	ds_bpermute_b32 v57, v89, v56
	s_waitcnt lgkmcnt(0)
	v_add_f32_e32 v56, v56, v57
	v_mul_f32_e32 v56, 0x3a800000, v56
	v_pk_add_f32 v[60:61], v[60:61], v[56:57] op_sel_hi:[1,0] neg_lo:[0,1] neg_hi:[0,1]
	v_pk_add_f32 v[36:37], v[36:37], v[56:57] op_sel_hi:[1,0] neg_lo:[0,1] neg_hi:[0,1]
	v_pk_add_f32 v[58:59], v[58:59], v[56:57] op_sel_hi:[1,0] neg_lo:[0,1] neg_hi:[0,1]
	v_pk_add_f32 v[62:63], v[38:39], v[56:57] op_sel_hi:[1,0] neg_lo:[0,1] neg_hi:[0,1]
	v_pk_add_f32 v[54:55], v[54:55], v[56:57] op_sel_hi:[1,0] neg_lo:[0,1] neg_hi:[0,1]
	v_pk_add_f32 v[64:65], v[40:41], v[56:57] op_sel_hi:[1,0] neg_lo:[0,1] neg_hi:[0,1]
	v_pk_add_f32 v[52:53], v[52:53], v[56:57] op_sel_hi:[1,0] neg_lo:[0,1] neg_hi:[0,1]
	v_pk_add_f32 v[56:57], v[42:43], v[56:57] op_sel_hi:[1,0] neg_lo:[0,1] neg_hi:[0,1]
	s_waitcnt vmcnt(8)
	v_lshlrev_b32_e32 v42, 16, v50
	v_and_b32_e32 v43, 0xffff0000, v50
	v_lshlrev_b32_e32 v50, 16, v51
	v_mov_b32_e32 v69, v42
	v_mov_b32_e32 v71, v43
	v_and_b32_e32 v51, 0xffff0000, v51
	v_pk_add_f32 v[68:69], v[68:69], v[70:71]
	v_mov_b32_e32 v70, v48
	v_mov_b32_e32 v71, v50
	v_pk_add_f32 v[68:69], v[68:69], v[70:71]
	v_mov_b32_e32 v70, v49
	v_mov_b32_e32 v71, v51
	v_pk_add_f32 v[68:69], v[68:69], v[70:71]
	v_lshlrev_b32_e32 v70, 16, v46
	v_and_b32_e32 v71, 0xffff0000, v46
	v_lshlrev_b32_e32 v46, 16, v47
	v_mov_b32_e32 v75, v70
	v_mov_b32_e32 v77, v71
	v_and_b32_e32 v47, 0xffff0000, v47
	v_pk_add_f32 v[74:75], v[74:75], v[76:77]
	v_mov_b32_e32 v76, v44
	v_mov_b32_e32 v77, v46
	v_pk_add_f32 v[74:75], v[74:75], v[76:77]
	v_mov_b32_e32 v76, v45
	v_mov_b32_e32 v77, v47
	v_pk_add_f32 v[74:75], v[74:75], v[76:77]
	v_mov_b32_e32 v77, v61
	v_add_f32_e32 v74, 0, v74
	v_add_f32_e32 v74, v74, v75
	v_add_f32_e32 v68, v74, v68
	v_add_f32_e32 v68, v68, v69
	ds_bpermute_b32 v69, v84, v68
	v_mov_b32_e32 v75, v60
	v_pk_mul_f32 v[38:39], v[52:53], v[52:53]
	v_pk_mul_f32 v[40:41], v[56:57], v[56:57]
	s_waitcnt lgkmcnt(0)
	v_add_f32_e32 v68, v68, v69
	ds_bpermute_b32 v69, v85, v68
	s_waitcnt lgkmcnt(0)
	v_add_f32_e32 v68, v68, v69
	ds_bpermute_b32 v69, v86, v68
	s_waitcnt lgkmcnt(0)
	v_add_f32_e32 v68, v68, v69
	ds_bpermute_b32 v69, v87, v68
	s_waitcnt lgkmcnt(0)
	v_add_f32_e32 v68, v68, v69
	ds_bpermute_b32 v69, v88, v68
	s_waitcnt lgkmcnt(0)
	v_add_f32_e32 v68, v68, v69
	ds_bpermute_b32 v69, v89, v68
	s_waitcnt lgkmcnt(0)
	v_add_f32_e32 v68, v68, v69
	v_mul_f32_e32 v68, 0x3a800000, v68
	v_pk_add_f32 v[72:73], v[72:73], v[68:69] op_sel_hi:[1,0] neg_lo:[0,1] neg_hi:[0,1]
	v_pk_add_f32 v[70:71], v[70:71], v[68:69] op_sel_hi:[1,0] neg_lo:[0,1] neg_hi:[0,1]
	v_mov_b32_e32 v76, v73
	v_mov_b32_e32 v74, v72
	v_pk_mul_f32 v[76:77], v[76:77], v[76:77]
	v_pk_add_f32 v[78:79], v[46:47], v[68:69] op_sel_hi:[1,0] neg_lo:[0,1] neg_hi:[0,1]
	v_pk_fma_f32 v[74:75], v[74:75], v[74:75], v[76:77]
	v_pk_add_f32 v[76:77], v[44:45], v[68:69] op_sel_hi:[1,0] neg_lo:[0,1] neg_hi:[0,1]
	v_mov_b32_e32 v45, v36
	v_mov_b32_e32 v44, v76
	v_pk_fma_f32 v[44:45], v[44:45], v[44:45], v[74:75]
	v_mov_b32_e32 v46, v77
	v_mov_b32_e32 v47, v37
	v_pk_fma_f32 v[44:45], v[46:47], v[46:47], v[44:45]
	v_mov_b32_e32 v46, v70
	v_mov_b32_e32 v47, v58
	v_pk_fma_f32 v[44:45], v[46:47], v[46:47], v[44:45]
	v_mov_b32_e32 v46, v71
	v_mov_b32_e32 v47, v59
	v_pk_fma_f32 v[44:45], v[46:47], v[46:47], v[44:45]
	v_mov_b32_e32 v46, v78
	v_mov_b32_e32 v47, v62
	v_pk_add_f32 v[66:67], v[66:67], v[68:69] op_sel_hi:[1,0] neg_lo:[0,1] neg_hi:[0,1]
	v_pk_fma_f32 v[44:45], v[46:47], v[46:47], v[44:45]
	v_mov_b32_e32 v46, v79
	v_mov_b32_e32 v47, v63
	v_pk_fma_f32 v[44:45], v[46:47], v[46:47], v[44:45]
	v_mov_b32_e32 v46, v66
	v_mov_b32_e32 v47, v54
	v_pk_add_f32 v[80:81], v[48:49], v[68:69] op_sel_hi:[1,0] neg_lo:[0,1] neg_hi:[0,1]
	v_pk_fma_f32 v[44:45], v[46:47], v[46:47], v[44:45]
	v_mov_b32_e32 v46, v67
	v_mov_b32_e32 v47, v55
	v_pk_add_f32 v[82:83], v[42:43], v[68:69] op_sel_hi:[1,0] neg_lo:[0,1] neg_hi:[0,1]
	v_pk_fma_f32 v[44:45], v[46:47], v[46:47], v[44:45]
	v_mov_b32_e32 v46, v80
	v_mov_b32_e32 v47, v64
	v_pk_mul_f32 v[42:43], v[82:83], v[82:83]
	v_pk_fma_f32 v[44:45], v[46:47], v[46:47], v[44:45]
	v_mov_b32_e32 v46, v81
	v_mov_b32_e32 v47, v65
	v_pk_fma_f32 v[44:45], v[46:47], v[46:47], v[44:45]
	v_mov_b32_e32 v46, v42
	v_mov_b32_e32 v47, v38
	v_pk_add_f32 v[68:69], v[50:51], v[68:69] op_sel_hi:[1,0] neg_lo:[0,1] neg_hi:[0,1]
	v_pk_add_f32 v[44:45], v[46:47], v[44:45]
	v_pk_mul_f32 v[46:47], v[68:69], v[68:69]
	v_mov_b32_e32 v38, v43
	v_pk_add_f32 v[38:39], v[38:39], v[44:45]
	v_mov_b32_e32 v42, v46
	v_mov_b32_e32 v43, v40
	v_pk_add_f32 v[38:39], v[42:43], v[38:39]
	v_mov_b32_e32 v40, v47
	v_pk_add_f32 v[38:39], v[40:41], v[38:39]
	v_mov_b32_e32 v40, v38
	v_mov_b32_e32 v41, v39
	s_nop 1
	v_permlane32_swap_b32_e32 v40, v38
	v_permlane32_swap_b32_e32 v41, v39
	v_pk_add_f32 v[38:39], v[38:39], v[40:41]
	v_mov_b32_e32 v40, v38
	v_mov_b32_e32 v41, v39
	s_nop 1
	v_permlane16_swap_b32_e32 v40, v38
	v_permlane16_swap_b32_e32 v41, v39
	v_pk_add_f32 v[38:39], v[38:39], v[40:41]
	s_nop 1
	v_add_f32_dpp v38, v38, v38 row_ror:8 row_mask:0xf bank_mask:0xf
	v_add_f32_dpp v39, v39, v39 row_ror:8 row_mask:0xf bank_mask:0xf
	s_nop 0
	v_add_f32_dpp v38, v38, v38 row_ror:4 row_mask:0xf bank_mask:0xf
	v_add_f32_dpp v39, v39, v39 row_ror:4 row_mask:0xf bank_mask:0xf
	s_nop 0
	v_add_f32_dpp v38, v38, v38 row_ror:2 row_mask:0xf bank_mask:0xf
	v_add_f32_dpp v39, v39, v39 row_ror:2 row_mask:0xf bank_mask:0xf
	s_nop 0
	v_add_f32_dpp v38, v38, v38 row_ror:1 row_mask:0xf bank_mask:0xf
	v_add_f32_dpp v39, v39, v39 row_ror:1 row_mask:0xf bank_mask:0xf
	s_nop 0
	v_pk_fma_f32 v[74:75], v[38:39], s[8:9], v[138:139] op_sel_hi:[1,0,0]
	s_nop 0
	v_mul_f32_e32 v38, 0x4b800000, v75
	v_cmp_gt_f32_e64 s[0:1], s33, v75
	v_cmp_gt_f32_e32 vcc, s33, v74
	s_nop 0
	v_cndmask_b32_e64 v38, v75, v38, s[0:1]
	v_rsq_f32_e32 v38, v38
	s_nop 0
	v_mul_f32_e32 v39, 0x45800000, v38
	v_cndmask_b32_e64 v48, v38, v39, s[0:1]
	v_pk_mul_f32 v[40:41], v[60:61], v[48:49] op_sel_hi:[1,0]
	v_pk_mul_f32 v[36:37], v[36:37], v[48:49] op_sel_hi:[1,0]
	v_pk_mul_f32 v[42:43], v[62:63], v[48:49] op_sel_hi:[1,0]
	s_waitcnt vmcnt(6)
	v_pk_fma_f32 v[38:39], v[26:27], v[36:37], v[30:31]
	v_pk_fma_f32 v[36:37], v[24:25], v[40:41], v[28:29]
	v_pk_mul_f32 v[40:41], v[58:59], v[48:49] op_sel_hi:[1,0]
	v_pk_mul_f32 v[44:45], v[54:55], v[48:49] op_sel_hi:[1,0]
	v_pk_mul_f32 v[46:47], v[64:65], v[48:49] op_sel_hi:[1,0]
	v_pk_mul_f32 v[52:53], v[52:53], v[48:49] op_sel_hi:[1,0]
	v_pk_mul_f32 v[48:49], v[56:57], v[48:49] op_sel_hi:[1,0]
	s_waitcnt vmcnt(4)
	v_pk_fma_f32 v[40:41], v[16:17], v[40:41], v[20:21]
	s_waitcnt vmcnt(0)
	v_pk_fma_f32 v[50:51], v[2:3], v[48:49], v[6:7]
	v_pk_fma_f32 v[48:49], v[0:1], v[52:53], v[4:5]
	v_mul_f32_e32 v52, 0x4b800000, v74
	v_cndmask_b32_e32 v52, v74, v52, vcc
	v_rsq_f32_e32 v52, v52
	v_pk_fma_f32 v[44:45], v[8:9], v[44:45], v[12:13]
	v_pk_fma_f32 v[42:43], v[18:19], v[42:43], v[22:23]
	v_pk_fma_f32 v[46:47], v[10:11], v[46:47], v[14:15]
	v_mul_f32_e32 v53, 0x45800000, v52
	v_cndmask_b32_e32 v52, v52, v53, vcc
	v_pk_mul_f32 v[54:55], v[72:73], v[52:53] op_sel_hi:[1,0]
	v_pk_mul_f32 v[56:57], v[76:77], v[52:53] op_sel_hi:[1,0]
	v_pk_fma_f32 v[24:25], v[24:25], v[54:55], v[28:29]
	v_pk_mul_f32 v[28:29], v[70:71], v[52:53] op_sel_hi:[1,0]
	v_pk_fma_f32 v[26:27], v[26:27], v[56:57], v[30:31]
	v_pk_fma_f32 v[16:17], v[16:17], v[28:29], v[20:21]
	v_pk_mul_f32 v[20:21], v[66:67], v[52:53] op_sel_hi:[1,0]
	v_pk_mul_f32 v[30:31], v[78:79], v[52:53] op_sel_hi:[1,0]
	v_pk_fma_f32 v[8:9], v[8:9], v[20:21], v[12:13]
	v_pk_mul_f32 v[12:13], v[82:83], v[52:53] op_sel_hi:[1,0]
	v_pk_fma_f32 v[18:19], v[18:19], v[30:31], v[22:23]
	v_pk_mul_f32 v[22:23], v[80:81], v[52:53] op_sel_hi:[1,0]
	v_pk_fma_f32 v[0:1], v[0:1], v[12:13], v[4:5]
	v_lshl_add_u64 v[4:5], v[32:33], 0, v[136:137]
	v_pk_fma_f32 v[10:11], v[10:11], v[22:23], v[14:15]
	v_pk_mul_f32 v[14:15], v[68:69], v[52:53] op_sel_hi:[1,0]
	global_store_dwordx4 v[4:5], v[36:39], off
	global_store_dwordx4 v[4:5], v[40:43], off offset:1024
	global_store_dwordx4 v[4:5], v[44:47], off offset:2048
	global_store_dwordx4 v[4:5], v[48:51], off offset:3072
	v_lshl_add_u64 v[4:5], v[34:35], 0, v[136:137]
	v_pk_fma_f32 v[2:3], v[2:3], v[14:15], v[6:7]
	global_store_dwordx4 v[4:5], v[24:27], off
	global_store_dwordx4 v[4:5], v[16:19], off offset:1024
	global_store_dwordx4 v[4:5], v[8:11], off offset:2048
	global_store_dwordx4 v[4:5], v[0:3], off offset:3072
	s_cbranch_scc0 .LBB0_40

.LBB0_123:
	v_mov_b32_e32 v0, v139
	v_readlane_b32 s40, v247, 57
	v_ashrrev_i32_e32 v1, 5, v0
	v_and_b32_e32 v1, -2, v1
	v_add_u32_e32 v38, s12, v1
	v_lshlrev_b32_e32 v0, 2, v0
	v_ashrrev_i32_e32 v39, 31, v38
	v_and_b32_e32 v2, 0xfc, v0
	v_lshlrev_b64 v[0:1], 12, v[38:39]
	v_readlane_b32 s50, v246, 3
	v_readlane_b32 s51, v246, 4
	v_lshlrev_b32_e32 v136, 1, v2
	s_waitcnt vmcnt(8)
	v_add_u32_e32 v34, 1, v38
	v_lshl_add_u64 v[0:1], s[50:51], 0, v[0:1]
	v_lshl_add_u64 v[36:37], v[0:1], 0, v[136:137]
	global_load_dwordx2 v[42:43], v[36:37], off offset:2048
	global_load_dwordx2 v[44:45], v[36:37], off offset:2560
	global_load_dwordx2 v[46:47], v[36:37], off offset:3072
	global_load_dwordx2 v[48:49], v[36:37], off offset:3584
	v_ashrrev_i32_e32 v35, 31, v34
	v_lshlrev_b64 v[0:1], 12, v[34:35]
	v_lshl_add_u64 v[0:1], s[50:51], 0, v[0:1]
	v_lshl_add_u64 v[32:33], v[0:1], 0, v[136:137]
	global_load_dwordx2 v[50:51], v[32:33], off offset:2048
	global_load_dwordx2 v[52:53], v[32:33], off offset:2560
	global_load_dwordx2 v[54:55], v[32:33], off offset:3072
	global_load_dwordx2 v[56:57], v[32:33], off offset:3584
	v_cmp_lt_i32_e32 vcc, v179, v178
	v_lshlrev_b32_e32 v40, 2, v2
	global_load_dwordx4 v[24:27], v40, s[6:7]
	global_load_dwordx4 v[28:31], v40, s[8:9]
	global_load_dwordx4 v[16:19], v40, s[6:7] offset:1024
	global_load_dwordx4 v[20:23], v40, s[8:9] offset:1024
	global_load_dwordx4 v[8:11], v40, s[6:7] offset:2048
	global_load_dwordx4 v[12:15], v40, s[8:9] offset:2048
	global_load_dwordx4 v[0:3], v40, s[6:7] offset:3072
	global_load_dwordx4 v[4:7], v40, s[8:9] offset:3072
	v_cndmask_b32_e32 v35, v176, v179, vcc
	v_cmp_lt_i32_e32 vcc, v180, v178
	v_lshlrev_b32_e32 v35, 2, v35
	v_mov_b32_e32 v41, v137
	v_cndmask_b32_e32 v39, v176, v180, vcc
	v_cmp_lt_i32_e32 vcc, v181, v178
	v_lshlrev_b32_e32 v39, 2, v39
	s_add_i32 s13, s13, s90
	v_cndmask_b32_e32 v58, v176, v181, vcc
	v_cmp_lt_i32_e32 vcc, v182, v178
	v_lshlrev_b32_e32 v86, 2, v58
	s_add_i32 s12, s12, s5
	v_cndmask_b32_e32 v58, v176, v182, vcc
	v_cmp_lt_i32_e32 vcc, v183, v178
	v_lshlrev_b32_e32 v87, 2, v58
	s_cmpk_gt_i32 s13, 0xbf
	v_cndmask_b32_e32 v58, v176, v183, vcc
	v_cmp_lt_i32_e32 vcc, v184, v178
	v_lshlrev_b32_e32 v88, 2, v58
	v_readlane_b32 s41, v247, 58
	v_cndmask_b32_e32 v58, v176, v184, vcc
	v_lshlrev_b32_e32 v89, 2, v58
	v_readlane_b32 s42, v247, 59
	v_readlane_b32 s43, v247, 60
	v_readlane_b32 s44, v247, 61
	v_readlane_b32 s45, v247, 62
	v_readlane_b32 s46, v247, 63
	v_readlane_b32 s47, v246, 0
	v_readlane_b32 s48, v246, 1
	v_readlane_b32 s49, v246, 2
	v_readlane_b32 s52, v246, 5
	v_readlane_b32 s53, v246, 6
	v_readlane_b32 s54, v246, 7
	v_readlane_b32 s55, v246, 8
	s_waitcnt vmcnt(15)
	v_lshlrev_b32_e32 v68, 16, v42
	s_waitcnt vmcnt(14)
	v_lshlrev_b32_e32 v66, 16, v44
	s_waitcnt vmcnt(13)
	v_lshlrev_b32_e32 v62, 16, v46
	s_waitcnt vmcnt(12)
	v_lshlrev_b32_e32 v60, 16, v48
	v_and_b32_e32 v61, 0xffff0000, v48
	v_and_b32_e32 v63, 0xffff0000, v46
	v_lshlrev_b32_e32 v58, 16, v49
	v_and_b32_e32 v59, 0xffff0000, v49
	v_lshlrev_b32_e32 v48, 16, v47
	v_and_b32_e32 v49, 0xffff0000, v47
	v_mov_b32_e32 v46, v62
	v_mov_b32_e32 v47, v60
	v_mov_b32_e32 v64, v63
	v_mov_b32_e32 v65, v61
	v_pk_add_f32 v[46:47], v[46:47], v[64:65]
	v_mov_b32_e32 v64, v48
	v_mov_b32_e32 v65, v58
	v_pk_add_f32 v[46:47], v[46:47], v[64:65]
	v_mov_b32_e32 v64, v49
	v_mov_b32_e32 v65, v59
	v_and_b32_e32 v67, 0xffff0000, v44
	v_and_b32_e32 v69, 0xffff0000, v42
	v_pk_add_f32 v[46:47], v[46:47], v[64:65]
	v_lshlrev_b32_e32 v64, 16, v45
	v_and_b32_e32 v65, 0xffff0000, v45
	v_lshlrev_b32_e32 v44, 16, v43
	v_and_b32_e32 v45, 0xffff0000, v43
	v_mov_b32_e32 v42, v68
	v_mov_b32_e32 v43, v66
	v_mov_b32_e32 v70, v69
	v_mov_b32_e32 v71, v67
	v_pk_add_f32 v[42:43], v[42:43], v[70:71]
	v_mov_b32_e32 v70, v44
	v_mov_b32_e32 v71, v64
	v_pk_add_f32 v[42:43], v[42:43], v[70:71]
	v_mov_b32_e32 v70, v45
	v_mov_b32_e32 v71, v65
	s_waitcnt vmcnt(8)
	v_lshlrev_b32_e32 v72, 16, v56
	v_and_b32_e32 v73, 0xffff0000, v56
	v_lshlrev_b32_e32 v74, 16, v54
	v_and_b32_e32 v75, 0xffff0000, v54
	v_pk_add_f32 v[42:43], v[42:43], v[70:71]
	v_lshlrev_b32_e32 v70, 16, v57
	v_and_b32_e32 v71, 0xffff0000, v57
	v_lshlrev_b32_e32 v56, 16, v55
	v_and_b32_e32 v57, 0xffff0000, v55
	v_mov_b32_e32 v54, v74
	v_mov_b32_e32 v55, v72
	v_mov_b32_e32 v76, v75
	v_mov_b32_e32 v77, v73
	v_pk_add_f32 v[54:55], v[54:55], v[76:77]
	v_mov_b32_e32 v76, v56
	v_mov_b32_e32 v77, v70
	v_pk_add_f32 v[54:55], v[54:55], v[76:77]
	v_mov_b32_e32 v76, v57
	v_mov_b32_e32 v77, v71
	v_lshlrev_b32_e32 v78, 16, v52
	v_and_b32_e32 v79, 0xffff0000, v52
	v_lshlrev_b32_e32 v80, 16, v50
	v_and_b32_e32 v81, 0xffff0000, v50
	v_pk_add_f32 v[54:55], v[54:55], v[76:77]
	v_lshlrev_b32_e32 v76, 16, v53
	v_and_b32_e32 v77, 0xffff0000, v53
	v_lshlrev_b32_e32 v52, 16, v51
	v_and_b32_e32 v53, 0xffff0000, v51
	v_mov_b32_e32 v50, v80
	v_mov_b32_e32 v51, v78
	v_mov_b32_e32 v82, v81
	v_mov_b32_e32 v83, v79
	v_pk_add_f32 v[50:51], v[50:51], v[82:83]
	v_mov_b32_e32 v82, v52
	v_mov_b32_e32 v83, v76
	v_pk_add_f32 v[50:51], v[50:51], v[82:83]
	v_mov_b32_e32 v82, v53
	v_mov_b32_e32 v83, v77
	v_pk_add_f32 v[50:51], v[50:51], v[82:83]
	v_add_f32_e32 v42, 0, v42
	v_add_f32_e32 v50, 0, v50
	v_add_f32_e32 v42, v42, v43
	v_add_f32_e32 v50, v50, v51
	v_add_f32_e32 v42, v42, v46
	v_add_f32_e32 v50, v50, v54
	v_add_f32_e32 v42, v42, v47
	v_add_f32_e32 v50, v50, v55
	ds_bpermute_b32 v43, v35, v42
	ds_bpermute_b32 v51, v35, v50
	s_waitcnt lgkmcnt(1)
	v_add_f32_e32 v42, v42, v43
	s_waitcnt lgkmcnt(0)
	v_add_f32_e32 v50, v50, v51
	ds_bpermute_b32 v43, v39, v42
	ds_bpermute_b32 v51, v39, v50
	s_waitcnt lgkmcnt(1)
	v_add_f32_e32 v42, v42, v43
	s_waitcnt lgkmcnt(0)
	v_add_f32_e32 v50, v50, v51
	ds_bpermute_b32 v43, v86, v42
	ds_bpermute_b32 v51, v86, v50
	s_waitcnt lgkmcnt(1)
	v_add_f32_e32 v42, v42, v43
	s_waitcnt lgkmcnt(0)
	v_add_f32_e32 v50, v50, v51
	ds_bpermute_b32 v43, v87, v42
	ds_bpermute_b32 v51, v87, v50
	s_waitcnt lgkmcnt(1)
	v_add_f32_e32 v42, v42, v43
	s_waitcnt lgkmcnt(0)
	v_add_f32_e32 v50, v50, v51
	ds_bpermute_b32 v43, v88, v42
	ds_bpermute_b32 v51, v88, v50
	s_waitcnt lgkmcnt(1)
	v_add_f32_e32 v42, v42, v43
	s_waitcnt lgkmcnt(0)
	v_add_f32_e32 v50, v50, v51
	ds_bpermute_b32 v43, v89, v42
	ds_bpermute_b32 v51, v89, v50
	s_waitcnt lgkmcnt(1)
	v_add_f32_e32 v42, v42, v43
	s_waitcnt lgkmcnt(0)
	v_add_f32_e32 v50, v50, v51
	v_mul_f32_e32 v42, 0x3a800000, v42
	v_mul_f32_e32 v50, 0x3a800000, v50
	v_pk_add_f32 v[46:47], v[68:69], v[42:43] op_sel_hi:[1,0] neg_lo:[0,1] neg_hi:[0,1]
	v_pk_add_f32 v[80:81], v[80:81], v[50:51] op_sel_hi:[1,0] neg_lo:[0,1] neg_hi:[0,1]
	v_mov_b32_e32 v83, v47
	v_mov_b32_e32 v82, v81
	v_mov_b32_e32 v54, v80
	v_mov_b32_e32 v55, v46
	v_pk_mul_f32 v[82:83], v[82:83], v[82:83]
	v_pk_add_f32 v[44:45], v[44:45], v[42:43] op_sel_hi:[1,0] neg_lo:[0,1] neg_hi:[0,1]
	v_pk_fma_f32 v[54:55], v[54:55], v[54:55], v[82:83]
	v_pk_add_f32 v[82:83], v[52:53], v[50:51] op_sel_hi:[1,0] neg_lo:[0,1] neg_hi:[0,1]
	v_mov_b32_e32 v53, v44
	v_mov_b32_e32 v52, v82
	v_pk_add_f32 v[66:67], v[66:67], v[42:43] op_sel_hi:[1,0] neg_lo:[0,1] neg_hi:[0,1]
	v_pk_add_f32 v[78:79], v[78:79], v[50:51] op_sel_hi:[1,0] neg_lo:[0,1] neg_hi:[0,1]
	v_pk_fma_f32 v[52:53], v[52:53], v[52:53], v[54:55]
	v_mov_b32_e32 v54, v83
	v_mov_b32_e32 v55, v45
	v_pk_fma_f32 v[52:53], v[54:55], v[54:55], v[52:53]
	v_mov_b32_e32 v54, v78
	v_mov_b32_e32 v55, v66
	v_pk_add_f32 v[64:65], v[64:65], v[42:43] op_sel_hi:[1,0] neg_lo:[0,1] neg_hi:[0,1]
	v_pk_add_f32 v[76:77], v[76:77], v[50:51] op_sel_hi:[1,0] neg_lo:[0,1] neg_hi:[0,1]
	v_pk_fma_f32 v[52:53], v[54:55], v[54:55], v[52:53]
	v_mov_b32_e32 v54, v79
	v_mov_b32_e32 v55, v67
	v_pk_fma_f32 v[52:53], v[54:55], v[54:55], v[52:53]
	v_mov_b32_e32 v54, v76
	v_mov_b32_e32 v55, v64
	v_pk_add_f32 v[62:63], v[62:63], v[42:43] op_sel_hi:[1,0] neg_lo:[0,1] neg_hi:[0,1]
	v_pk_add_f32 v[74:75], v[74:75], v[50:51] op_sel_hi:[1,0] neg_lo:[0,1] neg_hi:[0,1]
	v_pk_fma_f32 v[52:53], v[54:55], v[54:55], v[52:53]
	v_mov_b32_e32 v54, v77
	v_mov_b32_e32 v55, v65
	v_pk_fma_f32 v[52:53], v[54:55], v[54:55], v[52:53]
	v_mov_b32_e32 v54, v74
	v_mov_b32_e32 v55, v62
	v_pk_add_f32 v[68:69], v[48:49], v[42:43] op_sel_hi:[1,0] neg_lo:[0,1] neg_hi:[0,1]
	v_pk_add_f32 v[84:85], v[56:57], v[50:51] op_sel_hi:[1,0] neg_lo:[0,1] neg_hi:[0,1]
	v_pk_fma_f32 v[52:53], v[54:55], v[54:55], v[52:53]
	v_mov_b32_e32 v54, v75
	v_mov_b32_e32 v55, v63
	v_pk_add_f32 v[60:61], v[60:61], v[42:43] op_sel_hi:[1,0] neg_lo:[0,1] neg_hi:[0,1]
	v_pk_add_f32 v[72:73], v[72:73], v[50:51] op_sel_hi:[1,0] neg_lo:[0,1] neg_hi:[0,1]
	v_pk_fma_f32 v[52:53], v[54:55], v[54:55], v[52:53]
	v_mov_b32_e32 v54, v84
	v_mov_b32_e32 v55, v68
	v_pk_mul_f32 v[48:49], v[60:61], v[60:61]
	v_pk_mul_f32 v[56:57], v[72:73], v[72:73]
	v_pk_fma_f32 v[52:53], v[54:55], v[54:55], v[52:53]
	v_mov_b32_e32 v54, v85
	v_mov_b32_e32 v55, v69
	v_pk_add_f32 v[42:43], v[58:59], v[42:43] op_sel_hi:[1,0] neg_lo:[0,1] neg_hi:[0,1]
	v_pk_fma_f32 v[52:53], v[54:55], v[54:55], v[52:53]
	v_mov_b32_e32 v54, v56
	v_mov_b32_e32 v55, v48
	v_pk_add_f32 v[70:71], v[70:71], v[50:51] op_sel_hi:[1,0] neg_lo:[0,1] neg_hi:[0,1]
	v_pk_mul_f32 v[58:59], v[42:43], v[42:43]
	v_pk_add_f32 v[52:53], v[54:55], v[52:53]
	v_pk_mul_f32 v[50:51], v[70:71], v[70:71]
	v_mov_b32_e32 v48, v57
	v_pk_add_f32 v[48:49], v[48:49], v[52:53]
	v_mov_b32_e32 v52, v50
	v_mov_b32_e32 v53, v58
	v_pk_add_f32 v[48:49], v[52:53], v[48:49]
	v_mov_b32_e32 v58, v51
	v_pk_add_f32 v[48:49], v[58:59], v[48:49]
	v_mov_b32_e32 v50, v48
	v_mov_b32_e32 v51, v49
	s_nop 1
	v_permlane32_swap_b32_e32 v50, v48
	v_permlane32_swap_b32_e32 v51, v49
	v_pk_add_f32 v[48:49], v[48:49], v[50:51]
	v_mov_b32_e32 v50, v48
	v_mov_b32_e32 v51, v49
	s_nop 1
	v_permlane16_swap_b32_e32 v50, v48
	v_permlane16_swap_b32_e32 v51, v49
	v_pk_add_f32 v[48:49], v[48:49], v[50:51]
	s_nop 1
	v_add_f32_dpp v48, v48, v48 row_ror:8 row_mask:0xf bank_mask:0xf
	v_add_f32_dpp v49, v49, v49 row_ror:8 row_mask:0xf bank_mask:0xf
	s_nop 0
	v_add_f32_dpp v48, v48, v48 row_ror:4 row_mask:0xf bank_mask:0xf
	v_add_f32_dpp v49, v49, v49 row_ror:4 row_mask:0xf bank_mask:0xf
	s_nop 0
	v_add_f32_dpp v48, v48, v48 row_ror:2 row_mask:0xf bank_mask:0xf
	v_add_f32_dpp v49, v49, v49 row_ror:2 row_mask:0xf bank_mask:0xf
	s_nop 0
	v_add_f32_dpp v48, v48, v48 row_ror:1 row_mask:0xf bank_mask:0xf
	v_add_f32_dpp v49, v49, v49 row_ror:1 row_mask:0xf bank_mask:0xf
	s_nop 0
	v_pk_fma_f32 v[58:59], v[48:49], s[20:21], v[138:139] op_sel_hi:[1,0,0]
	s_nop 0
	v_mul_f32_e32 v35, 0x4b800000, v59
	v_cmp_gt_f32_e64 s[0:1], s33, v59
	v_cmp_gt_f32_e32 vcc, s33, v58
	s_nop 0
	v_cndmask_b32_e64 v35, v59, v35, s[0:1]
	v_rsq_f32_e32 v35, v35
	s_nop 0
	v_mul_f32_e32 v39, 0x45800000, v35
	v_cndmask_b32_e64 v86, v35, v39, s[0:1]
	v_mul_f32_e32 v35, 0x4b800000, v58
	v_cndmask_b32_e32 v35, v58, v35, vcc
	v_rsq_f32_e32 v35, v35
	v_pk_mul_f32 v[44:45], v[44:45], v[86:87] op_sel_hi:[1,0]
	v_pk_mul_f32 v[46:47], v[46:47], v[86:87] op_sel_hi:[1,0]
	s_waitcnt vmcnt(6)
	v_pk_fma_f32 v[54:55], v[26:27], v[44:45], v[30:31]
	v_pk_mul_f32 v[44:45], v[66:67], v[86:87] op_sel_hi:[1,0]
	v_mul_f32_e32 v39, 0x45800000, v35
	s_waitcnt vmcnt(4)
	v_pk_fma_f32 v[52:53], v[16:17], v[44:45], v[20:21]
	v_pk_mul_f32 v[44:45], v[64:65], v[86:87] op_sel_hi:[1,0]
	v_cndmask_b32_e32 v58, v35, v39, vcc
	v_pk_fma_f32 v[50:51], v[18:19], v[44:45], v[22:23]
	v_pk_mul_f32 v[44:45], v[62:63], v[86:87] op_sel_hi:[1,0]
	v_pk_fma_f32 v[56:57], v[24:25], v[46:47], v[28:29]
	s_waitcnt vmcnt(2)
	v_pk_fma_f32 v[48:49], v[8:9], v[44:45], v[12:13]
	v_pk_mul_f32 v[44:45], v[68:69], v[86:87] op_sel_hi:[1,0]
	v_pk_mul_f32 v[42:43], v[42:43], v[86:87] op_sel_hi:[1,0]
	v_pk_fma_f32 v[46:47], v[10:11], v[44:45], v[14:15]
	v_pk_mul_f32 v[44:45], v[60:61], v[86:87] op_sel_hi:[1,0]
	v_pk_mul_f32 v[60:61], v[80:81], v[58:59] op_sel_hi:[1,0]
	s_waitcnt vmcnt(0)
	v_pk_fma_f32 v[44:45], v[0:1], v[44:45], v[4:5]
	v_pk_fma_f32 v[24:25], v[24:25], v[60:61], v[28:29]
	v_pk_mul_f32 v[28:29], v[82:83], v[58:59] op_sel_hi:[1,0]
	v_pk_fma_f32 v[42:43], v[2:3], v[42:43], v[6:7]
	v_pk_fma_f32 v[26:27], v[26:27], v[28:29], v[30:31]
	v_pk_mul_f32 v[28:29], v[78:79], v[58:59] op_sel_hi:[1,0]
	v_cmp_lt_i32_e32 vcc, s16, v38
	v_pk_fma_f32 v[16:17], v[16:17], v[28:29], v[20:21]
	v_pk_mul_f32 v[20:21], v[76:77], v[58:59] op_sel_hi:[1,0]
	s_nop 0
	v_pk_fma_f32 v[18:19], v[18:19], v[20:21], v[22:23]
	v_pk_mul_f32 v[20:21], v[74:75], v[58:59] op_sel_hi:[1,0]
	s_nop 0
	v_pk_fma_f32 v[8:9], v[8:9], v[20:21], v[12:13]
	v_pk_mul_f32 v[12:13], v[84:85], v[58:59] op_sel_hi:[1,0]
	s_nop 0
	v_pk_fma_f32 v[10:11], v[10:11], v[12:13], v[14:15]
	v_pk_mul_f32 v[12:13], v[72:73], v[58:59] op_sel_hi:[1,0]
	s_nop 0
	v_pk_fma_f32 v[0:1], v[0:1], v[12:13], v[4:5]
	v_pk_mul_f32 v[4:5], v[70:71], v[58:59] op_sel_hi:[1,0]
	s_nop 0
	v_pk_fma_f32 v[2:3], v[2:3], v[4:5], v[6:7]
	v_add_u32_e32 v4, 0xfffff000, v38
	v_lshrrev_b32_e32 v4, 12, v4
	v_add_u32_e32 v4, 1, v4
	v_cndmask_b32_e32 v4, 0, v4, vcc
	v_mov_b32_e32 v5, v137
	v_lshl_add_u64 v[4:5], v[4:5], 0, s[10:11]
	v_mov_b64_e32 v[6:7], s[56:57]
	v_mad_u64_u32 v[6:7], s[0:1], v4, s15, v[6:7]
	v_mad_i32_i24 v7, v5, s15, v7
	v_lshl_add_u64 v[4:5], v[6:7], 0, v[40:41]
	v_add_co_u32_e32 v12, vcc, s14, v4
	v_lshl_add_u64 v[70:71], v[4:5], 0, s[24:25]
	s_nop 0
	v_addc_co_u32_e32 v13, vcc, 0, v5, vcc
	v_lshl_add_u64 v[40:41], v[4:5], 0, s[18:19]
	global_load_dwordx4 v[4:7], v[12:13], off offset:-4096
	s_nop 0
	global_load_dwordx4 v[12:15], v[12:13], off
	s_nop 0
	global_load_dwordx4 v[20:23], v[40:41], off offset:1024
	global_load_dwordx4 v[28:31], v[70:71], off offset:1024
	global_load_dwordx4 v[58:61], v[40:41], off offset:2048
	global_load_dwordx4 v[62:65], v[70:71], off offset:2048
	global_load_dwordx4 v[66:69], v[40:41], off offset:3072
	s_nop 0
	global_load_dwordx4 v[70:73], v[70:71], off offset:3072
	v_cvt_pk_bf16_f32 v40, v56, v57
	v_cvt_pk_bf16_f32 v41, v54, v55
	global_store_dwordx2 v[36:37], v[40:41], off
	s_waitcnt vmcnt(7)
	v_pk_add_f32 v[12:13], v[12:13], 1.0 op_sel_hi:[1,0]
	v_pk_add_f32 v[14:15], v[14:15], 1.0 op_sel_hi:[1,0]
	v_pk_fma_f32 v[40:41], v[12:13], v[56:57], v[4:5]
	v_pk_fma_f32 v[54:55], v[14:15], v[54:55], v[6:7]
	v_cvt_pk_bf16_f32 v40, v40, v41
	v_cvt_pk_bf16_f32 v41, v54, v55
	v_mov_b64_e32 v[54:55], s[62:63]
	v_mad_i64_i32 v[38:39], s[0:1], v38, s36, v[54:55]
	v_lshl_add_u64 v[38:39], v[38:39], 0, v[136:137]
	global_store_dwordx2 v[38:39], v[40:41], off
	v_cvt_pk_bf16_f32 v40, v52, v53
	v_cvt_pk_bf16_f32 v41, v50, v51
	s_waitcnt vmcnt(6)
	v_pk_add_f32 v[28:29], v[28:29], 1.0 op_sel_hi:[1,0]
	v_pk_add_f32 v[30:31], v[30:31], 1.0 op_sel_hi:[1,0]
	global_store_dwordx2 v[36:37], v[40:41], off offset:512
	v_pk_fma_f32 v[40:41], v[28:29], v[52:53], v[20:21]
	v_pk_fma_f32 v[50:51], v[30:31], v[50:51], v[22:23]
	v_cvt_pk_bf16_f32 v40, v40, v41
	v_cvt_pk_bf16_f32 v41, v50, v51
	global_store_dwordx2 v[38:39], v[40:41], off offset:512
	v_cvt_pk_bf16_f32 v40, v48, v49
	v_cvt_pk_bf16_f32 v41, v46, v47
	global_store_dwordx2 v[36:37], v[40:41], off offset:1024
	s_waitcnt vmcnt(7)
	v_pk_add_f32 v[40:41], v[62:63], 1.0 op_sel_hi:[1,0]
	v_pk_add_f32 v[50:51], v[64:65], 1.0 op_sel_hi:[1,0]
	v_pk_fma_f32 v[48:49], v[40:41], v[48:49], v[58:59]
	v_pk_fma_f32 v[46:47], v[50:51], v[46:47], v[60:61]
	v_cvt_pk_bf16_f32 v48, v48, v49
	v_cvt_pk_bf16_f32 v49, v46, v47
	v_cvt_pk_bf16_f32 v46, v44, v45
	v_cvt_pk_bf16_f32 v47, v42, v43
	global_store_dwordx2 v[38:39], v[48:49], off offset:1024
	global_store_dwordx2 v[36:37], v[46:47], off offset:1536
	s_waitcnt vmcnt(7)
	v_pk_add_f32 v[36:37], v[70:71], 1.0 op_sel_hi:[1,0]
	v_pk_add_f32 v[46:47], v[72:73], 1.0 op_sel_hi:[1,0]
	v_pk_fma_f32 v[44:45], v[36:37], v[44:45], v[66:67]
	v_pk_fma_f32 v[42:43], v[46:47], v[42:43], v[68:69]
	v_pk_fma_f32 v[4:5], v[12:13], v[24:25], v[4:5]
	v_pk_fma_f32 v[6:7], v[14:15], v[26:27], v[6:7]
	v_cvt_pk_bf16_f32 v44, v44, v45
	v_cvt_pk_bf16_f32 v45, v42, v43
	v_cvt_pk_bf16_f32 v4, v4, v5
	v_cvt_pk_bf16_f32 v5, v6, v7
	v_mad_i64_i32 v[6:7], s[0:1], v34, s36, v[54:55]
	global_store_dwordx2 v[38:39], v[44:45], off offset:1536
	v_cvt_pk_bf16_f32 v38, v24, v25
	v_cvt_pk_bf16_f32 v39, v26, v27
	v_lshl_add_u64 v[6:7], v[6:7], 0, v[136:137]
	global_store_dwordx2 v[32:33], v[38:39], off
	global_store_dwordx2 v[6:7], v[4:5], off
	v_cvt_pk_bf16_f32 v4, v16, v17
	v_cvt_pk_bf16_f32 v5, v18, v19
	global_store_dwordx2 v[32:33], v[4:5], off offset:512
	v_pk_fma_f32 v[4:5], v[28:29], v[16:17], v[20:21]
	v_pk_fma_f32 v[12:13], v[30:31], v[18:19], v[22:23]
	v_cvt_pk_bf16_f32 v4, v4, v5
	v_cvt_pk_bf16_f32 v5, v12, v13
	global_store_dwordx2 v[6:7], v[4:5], off offset:512
	v_cvt_pk_bf16_f32 v4, v8, v9
	v_cvt_pk_bf16_f32 v5, v10, v11
	global_store_dwordx2 v[32:33], v[4:5], off offset:1024
	v_pk_fma_f32 v[4:5], v[40:41], v[8:9], v[58:59]
	v_pk_fma_f32 v[8:9], v[50:51], v[10:11], v[60:61]
	v_cvt_pk_bf16_f32 v4, v4, v5
	v_cvt_pk_bf16_f32 v5, v8, v9
	global_store_dwordx2 v[6:7], v[4:5], off offset:1024
	v_cvt_pk_bf16_f32 v4, v0, v1
	v_cvt_pk_bf16_f32 v5, v2, v3
	v_pk_fma_f32 v[0:1], v[36:37], v[0:1], v[66:67]
	v_pk_fma_f32 v[2:3], v[46:47], v[2:3], v[68:69]
	v_cvt_pk_bf16_f32 v0, v0, v1
	v_cvt_pk_bf16_f32 v1, v2, v3
	global_store_dwordx2 v[32:33], v[4:5], off offset:1536
	global_store_dwordx2 v[6:7], v[0:1], off offset:1536
	s_cbranch_scc0 .LBB0_123

.LBB0_157:
	v_mov_b32_e32 v0, v139
	v_cmp_lt_i32_e32 vcc, v179, v178
	v_ashrrev_i32_e32 v1, 5, v0
	v_and_b32_e32 v1, -2, v1
	v_add_u32_e32 v38, s9, v1
	v_lshlrev_b32_e32 v0, 2, v0
	v_ashrrev_i32_e32 v39, 31, v38
	v_and_b32_e32 v2, 0xfc, v0
	v_lshlrev_b64 v[0:1], 12, v[38:39]
	v_lshl_add_u64 v[0:1], s[46:47], 0, v[0:1]
	v_lshlrev_b32_e32 v136, 1, v2
	v_lshl_add_u64 v[36:37], v[0:1], 0, v[136:137]
	global_load_dwordx2 v[42:43], v[36:37], off offset:2048
	global_load_dwordx2 v[44:45], v[36:37], off offset:2560
	global_load_dwordx2 v[46:47], v[36:37], off offset:3072
	global_load_dwordx2 v[48:49], v[36:37], off offset:3584
	s_waitcnt vmcnt(12)
	v_add_u32_e32 v34, 1, v38
	v_ashrrev_i32_e32 v35, 31, v34
	v_lshlrev_b64 v[0:1], 12, v[34:35]
	v_lshl_add_u64 v[0:1], s[46:47], 0, v[0:1]
	v_lshl_add_u64 v[32:33], v[0:1], 0, v[136:137]
	global_load_dwordx2 v[50:51], v[32:33], off offset:2048
	global_load_dwordx2 v[52:53], v[32:33], off offset:2560
	global_load_dwordx2 v[54:55], v[32:33], off offset:3072
	global_load_dwordx2 v[56:57], v[32:33], off offset:3584
	v_cndmask_b32_e32 v35, v176, v179, vcc
	v_cmp_lt_i32_e32 vcc, v180, v178
	v_lshlrev_b32_e32 v35, 2, v35
	v_lshlrev_b32_e32 v40, 2, v2
	v_cndmask_b32_e32 v39, v176, v180, vcc
	v_cmp_lt_i32_e32 vcc, v181, v178
	v_lshlrev_b32_e32 v39, 2, v39
	global_load_dwordx4 v[24:27], v40, s[4:5]
	global_load_dwordx4 v[28:31], v40, s[6:7]
	global_load_dwordx4 v[16:19], v40, s[4:5] offset:1024
	global_load_dwordx4 v[20:23], v40, s[6:7] offset:1024
	global_load_dwordx4 v[8:11], v40, s[4:5] offset:2048
	global_load_dwordx4 v[12:15], v40, s[6:7] offset:2048
	global_load_dwordx4 v[0:3], v40, s[4:5] offset:3072
	global_load_dwordx4 v[4:7], v40, s[6:7] offset:3072
	v_cndmask_b32_e32 v58, v176, v181, vcc
	v_cmp_lt_i32_e32 vcc, v182, v178
	v_lshlrev_b32_e32 v86, 2, v58
	v_mov_b32_e32 v41, v137
	v_cndmask_b32_e32 v58, v176, v182, vcc
	v_cmp_lt_i32_e32 vcc, v183, v178
	v_lshlrev_b32_e32 v87, 2, v58
	s_add_i32 s10, s10, s20
	v_cndmask_b32_e32 v58, v176, v183, vcc
	v_cmp_lt_i32_e32 vcc, v184, v178
	v_lshlrev_b32_e32 v88, 2, v58
	s_add_i32 s9, s9, s8
	v_cndmask_b32_e32 v58, v176, v184, vcc
	v_lshlrev_b32_e32 v89, 2, v58
	s_cmpk_gt_i32 s10, 0x5ff
	s_waitcnt vmcnt(15)
	v_lshlrev_b32_e32 v68, 16, v42
	s_waitcnt vmcnt(14)
	v_lshlrev_b32_e32 v66, 16, v44
	s_waitcnt vmcnt(13)
	v_lshlrev_b32_e32 v62, 16, v46
	s_waitcnt vmcnt(12)
	v_lshlrev_b32_e32 v60, 16, v48
	v_and_b32_e32 v61, 0xffff0000, v48
	v_and_b32_e32 v63, 0xffff0000, v46
	v_lshlrev_b32_e32 v58, 16, v49
	v_and_b32_e32 v59, 0xffff0000, v49
	v_lshlrev_b32_e32 v48, 16, v47
	v_and_b32_e32 v49, 0xffff0000, v47
	v_mov_b32_e32 v46, v62
	v_mov_b32_e32 v47, v60
	v_mov_b32_e32 v64, v63
	v_mov_b32_e32 v65, v61
	v_pk_add_f32 v[46:47], v[46:47], v[64:65]
	v_mov_b32_e32 v64, v48
	v_mov_b32_e32 v65, v58
	v_pk_add_f32 v[46:47], v[46:47], v[64:65]
	v_mov_b32_e32 v64, v49
	v_mov_b32_e32 v65, v59
	v_and_b32_e32 v67, 0xffff0000, v44
	v_and_b32_e32 v69, 0xffff0000, v42
	v_pk_add_f32 v[46:47], v[46:47], v[64:65]
	v_lshlrev_b32_e32 v64, 16, v45
	v_and_b32_e32 v65, 0xffff0000, v45
	v_lshlrev_b32_e32 v44, 16, v43
	v_and_b32_e32 v45, 0xffff0000, v43
	v_mov_b32_e32 v42, v68
	v_mov_b32_e32 v43, v66
	v_mov_b32_e32 v70, v69
	v_mov_b32_e32 v71, v67
	v_pk_add_f32 v[42:43], v[42:43], v[70:71]
	v_mov_b32_e32 v70, v44
	v_mov_b32_e32 v71, v64
	v_pk_add_f32 v[42:43], v[42:43], v[70:71]
	v_mov_b32_e32 v70, v45
	v_mov_b32_e32 v71, v65
	s_waitcnt vmcnt(8)
	v_lshlrev_b32_e32 v72, 16, v56
	v_and_b32_e32 v73, 0xffff0000, v56
	v_lshlrev_b32_e32 v74, 16, v54
	v_and_b32_e32 v75, 0xffff0000, v54
	v_pk_add_f32 v[42:43], v[42:43], v[70:71]
	v_lshlrev_b32_e32 v70, 16, v57
	v_and_b32_e32 v71, 0xffff0000, v57
	v_lshlrev_b32_e32 v56, 16, v55
	v_and_b32_e32 v57, 0xffff0000, v55
	v_mov_b32_e32 v54, v74
	v_mov_b32_e32 v55, v72
	v_mov_b32_e32 v76, v75
	v_mov_b32_e32 v77, v73
	v_pk_add_f32 v[54:55], v[54:55], v[76:77]
	v_mov_b32_e32 v76, v56
	v_mov_b32_e32 v77, v70
	v_pk_add_f32 v[54:55], v[54:55], v[76:77]
	v_mov_b32_e32 v76, v57
	v_mov_b32_e32 v77, v71
	v_lshlrev_b32_e32 v78, 16, v52
	v_and_b32_e32 v79, 0xffff0000, v52
	v_lshlrev_b32_e32 v80, 16, v50
	v_and_b32_e32 v81, 0xffff0000, v50
	v_pk_add_f32 v[54:55], v[54:55], v[76:77]
	v_lshlrev_b32_e32 v76, 16, v53
	v_and_b32_e32 v77, 0xffff0000, v53
	v_lshlrev_b32_e32 v52, 16, v51
	v_and_b32_e32 v53, 0xffff0000, v51
	v_mov_b32_e32 v50, v80
	v_mov_b32_e32 v51, v78
	v_mov_b32_e32 v82, v81
	v_mov_b32_e32 v83, v79
	v_pk_add_f32 v[50:51], v[50:51], v[82:83]
	v_mov_b32_e32 v82, v52
	v_mov_b32_e32 v83, v76
	v_pk_add_f32 v[50:51], v[50:51], v[82:83]
	v_mov_b32_e32 v82, v53
	v_mov_b32_e32 v83, v77
	v_pk_add_f32 v[50:51], v[50:51], v[82:83]
	v_add_f32_e32 v42, 0, v42
	v_add_f32_e32 v50, 0, v50
	v_add_f32_e32 v42, v42, v43
	v_add_f32_e32 v50, v50, v51
	v_add_f32_e32 v42, v42, v46
	v_add_f32_e32 v50, v50, v54
	v_add_f32_e32 v42, v42, v47
	v_add_f32_e32 v50, v50, v55
	ds_bpermute_b32 v43, v35, v42
	ds_bpermute_b32 v51, v35, v50
	s_waitcnt lgkmcnt(1)
	v_add_f32_e32 v42, v42, v43
	s_waitcnt lgkmcnt(0)
	v_add_f32_e32 v50, v50, v51
	ds_bpermute_b32 v43, v39, v42
	ds_bpermute_b32 v51, v39, v50
	s_waitcnt lgkmcnt(1)
	v_add_f32_e32 v42, v42, v43
	s_waitcnt lgkmcnt(0)
	v_add_f32_e32 v50, v50, v51
	ds_bpermute_b32 v43, v86, v42
	ds_bpermute_b32 v51, v86, v50
	s_waitcnt lgkmcnt(1)
	v_add_f32_e32 v42, v42, v43
	s_waitcnt lgkmcnt(0)
	v_add_f32_e32 v50, v50, v51
	ds_bpermute_b32 v43, v87, v42
	ds_bpermute_b32 v51, v87, v50
	s_waitcnt lgkmcnt(1)
	v_add_f32_e32 v42, v42, v43
	s_waitcnt lgkmcnt(0)
	v_add_f32_e32 v50, v50, v51
	ds_bpermute_b32 v43, v88, v42
	ds_bpermute_b32 v51, v88, v50
	s_waitcnt lgkmcnt(1)
	v_add_f32_e32 v42, v42, v43
	s_waitcnt lgkmcnt(0)
	v_add_f32_e32 v50, v50, v51
	ds_bpermute_b32 v43, v89, v42
	ds_bpermute_b32 v51, v89, v50
	s_waitcnt lgkmcnt(1)
	v_add_f32_e32 v42, v42, v43
	s_waitcnt lgkmcnt(0)
	v_add_f32_e32 v50, v50, v51
	v_mul_f32_e32 v42, 0x3a800000, v42
	v_mul_f32_e32 v50, 0x3a800000, v50
	v_pk_add_f32 v[46:47], v[68:69], v[42:43] op_sel_hi:[1,0] neg_lo:[0,1] neg_hi:[0,1]
	v_pk_add_f32 v[80:81], v[80:81], v[50:51] op_sel_hi:[1,0] neg_lo:[0,1] neg_hi:[0,1]
	v_mov_b32_e32 v83, v47
	v_mov_b32_e32 v82, v81
	v_mov_b32_e32 v54, v80
	v_mov_b32_e32 v55, v46
	v_pk_mul_f32 v[82:83], v[82:83], v[82:83]
	v_pk_add_f32 v[44:45], v[44:45], v[42:43] op_sel_hi:[1,0] neg_lo:[0,1] neg_hi:[0,1]
	v_pk_fma_f32 v[54:55], v[54:55], v[54:55], v[82:83]
	v_pk_add_f32 v[82:83], v[52:53], v[50:51] op_sel_hi:[1,0] neg_lo:[0,1] neg_hi:[0,1]
	v_mov_b32_e32 v53, v44
	v_mov_b32_e32 v52, v82
	v_pk_add_f32 v[66:67], v[66:67], v[42:43] op_sel_hi:[1,0] neg_lo:[0,1] neg_hi:[0,1]
	v_pk_add_f32 v[78:79], v[78:79], v[50:51] op_sel_hi:[1,0] neg_lo:[0,1] neg_hi:[0,1]
	v_pk_fma_f32 v[52:53], v[52:53], v[52:53], v[54:55]
	v_mov_b32_e32 v54, v83
	v_mov_b32_e32 v55, v45
	v_pk_fma_f32 v[52:53], v[54:55], v[54:55], v[52:53]
	v_mov_b32_e32 v54, v78
	v_mov_b32_e32 v55, v66
	v_pk_add_f32 v[64:65], v[64:65], v[42:43] op_sel_hi:[1,0] neg_lo:[0,1] neg_hi:[0,1]
	v_pk_add_f32 v[76:77], v[76:77], v[50:51] op_sel_hi:[1,0] neg_lo:[0,1] neg_hi:[0,1]
	v_pk_fma_f32 v[52:53], v[54:55], v[54:55], v[52:53]
	v_mov_b32_e32 v54, v79
	v_mov_b32_e32 v55, v67
	v_pk_fma_f32 v[52:53], v[54:55], v[54:55], v[52:53]
	v_mov_b32_e32 v54, v76
	v_mov_b32_e32 v55, v64
	v_pk_add_f32 v[62:63], v[62:63], v[42:43] op_sel_hi:[1,0] neg_lo:[0,1] neg_hi:[0,1]
	v_pk_add_f32 v[74:75], v[74:75], v[50:51] op_sel_hi:[1,0] neg_lo:[0,1] neg_hi:[0,1]
	v_pk_fma_f32 v[52:53], v[54:55], v[54:55], v[52:53]
	v_mov_b32_e32 v54, v77
	v_mov_b32_e32 v55, v65
	v_pk_fma_f32 v[52:53], v[54:55], v[54:55], v[52:53]
	v_mov_b32_e32 v54, v74
	v_mov_b32_e32 v55, v62
	v_pk_add_f32 v[68:69], v[48:49], v[42:43] op_sel_hi:[1,0] neg_lo:[0,1] neg_hi:[0,1]
	v_pk_add_f32 v[84:85], v[56:57], v[50:51] op_sel_hi:[1,0] neg_lo:[0,1] neg_hi:[0,1]
	v_pk_fma_f32 v[52:53], v[54:55], v[54:55], v[52:53]
	v_mov_b32_e32 v54, v75
	v_mov_b32_e32 v55, v63
	v_pk_add_f32 v[60:61], v[60:61], v[42:43] op_sel_hi:[1,0] neg_lo:[0,1] neg_hi:[0,1]
	v_pk_add_f32 v[72:73], v[72:73], v[50:51] op_sel_hi:[1,0] neg_lo:[0,1] neg_hi:[0,1]
	v_pk_fma_f32 v[52:53], v[54:55], v[54:55], v[52:53]
	v_mov_b32_e32 v54, v84
	v_mov_b32_e32 v55, v68
	v_pk_mul_f32 v[48:49], v[60:61], v[60:61]
	v_pk_mul_f32 v[56:57], v[72:73], v[72:73]
	v_pk_fma_f32 v[52:53], v[54:55], v[54:55], v[52:53]
	v_mov_b32_e32 v54, v85
	v_mov_b32_e32 v55, v69
	v_pk_add_f32 v[42:43], v[58:59], v[42:43] op_sel_hi:[1,0] neg_lo:[0,1] neg_hi:[0,1]
	v_pk_fma_f32 v[52:53], v[54:55], v[54:55], v[52:53]
	v_mov_b32_e32 v54, v56
	v_mov_b32_e32 v55, v48
	v_pk_add_f32 v[70:71], v[70:71], v[50:51] op_sel_hi:[1,0] neg_lo:[0,1] neg_hi:[0,1]
	v_pk_mul_f32 v[58:59], v[42:43], v[42:43]
	v_pk_add_f32 v[52:53], v[54:55], v[52:53]
	v_pk_mul_f32 v[50:51], v[70:71], v[70:71]
	v_mov_b32_e32 v48, v57
	v_pk_add_f32 v[48:49], v[48:49], v[52:53]
	v_mov_b32_e32 v52, v50
	v_mov_b32_e32 v53, v58
	v_pk_add_f32 v[48:49], v[52:53], v[48:49]
	v_mov_b32_e32 v58, v51
	v_pk_add_f32 v[48:49], v[58:59], v[48:49]
	v_mov_b32_e32 v50, v48
	v_mov_b32_e32 v51, v49
	s_nop 1
	v_permlane32_swap_b32_e32 v50, v48
	v_permlane32_swap_b32_e32 v51, v49
	v_pk_add_f32 v[48:49], v[48:49], v[50:51]
	v_mov_b32_e32 v50, v48
	v_mov_b32_e32 v51, v49
	s_nop 1
	v_permlane16_swap_b32_e32 v50, v48
	v_permlane16_swap_b32_e32 v51, v49
	v_pk_add_f32 v[48:49], v[48:49], v[50:51]
	s_nop 1
	v_add_f32_dpp v48, v48, v48 row_ror:8 row_mask:0xf bank_mask:0xf
	v_add_f32_dpp v49, v49, v49 row_ror:8 row_mask:0xf bank_mask:0xf
	s_nop 0
	v_add_f32_dpp v48, v48, v48 row_ror:4 row_mask:0xf bank_mask:0xf
	v_add_f32_dpp v49, v49, v49 row_ror:4 row_mask:0xf bank_mask:0xf
	s_nop 0
	v_add_f32_dpp v48, v48, v48 row_ror:2 row_mask:0xf bank_mask:0xf
	v_add_f32_dpp v49, v49, v49 row_ror:2 row_mask:0xf bank_mask:0xf
	s_nop 0
	v_add_f32_dpp v48, v48, v48 row_ror:1 row_mask:0xf bank_mask:0xf
	v_add_f32_dpp v49, v49, v49 row_ror:1 row_mask:0xf bank_mask:0xf
	s_nop 0
	v_pk_fma_f32 v[58:59], v[48:49], s[16:17], v[138:139] op_sel_hi:[1,0,0]
	s_nop 0
	v_mul_f32_e32 v35, 0x4b800000, v59
	v_cmp_gt_f32_e64 s[0:1], s33, v59
	v_cmp_gt_f32_e32 vcc, s33, v58
	s_nop 0
	v_cndmask_b32_e64 v35, v59, v35, s[0:1]
	v_rsq_f32_e32 v35, v35
	s_nop 0
	v_mul_f32_e32 v39, 0x45800000, v35
	v_cndmask_b32_e64 v86, v35, v39, s[0:1]
	v_mul_f32_e32 v35, 0x4b800000, v58
	v_cndmask_b32_e32 v35, v58, v35, vcc
	v_rsq_f32_e32 v35, v35
	v_pk_mul_f32 v[44:45], v[44:45], v[86:87] op_sel_hi:[1,0]
	v_pk_mul_f32 v[46:47], v[46:47], v[86:87] op_sel_hi:[1,0]
	s_waitcnt vmcnt(6)
	v_pk_fma_f32 v[54:55], v[26:27], v[44:45], v[30:31]
	v_pk_mul_f32 v[44:45], v[66:67], v[86:87] op_sel_hi:[1,0]
	v_mul_f32_e32 v39, 0x45800000, v35
	s_waitcnt vmcnt(4)
	v_pk_fma_f32 v[52:53], v[16:17], v[44:45], v[20:21]
	v_pk_mul_f32 v[44:45], v[64:65], v[86:87] op_sel_hi:[1,0]
	v_cndmask_b32_e32 v58, v35, v39, vcc
	v_pk_fma_f32 v[50:51], v[18:19], v[44:45], v[22:23]
	v_pk_mul_f32 v[44:45], v[62:63], v[86:87] op_sel_hi:[1,0]
	v_pk_fma_f32 v[56:57], v[24:25], v[46:47], v[28:29]
	s_waitcnt vmcnt(2)
	v_pk_fma_f32 v[48:49], v[8:9], v[44:45], v[12:13]
	v_pk_mul_f32 v[44:45], v[68:69], v[86:87] op_sel_hi:[1,0]
	v_pk_mul_f32 v[42:43], v[42:43], v[86:87] op_sel_hi:[1,0]
	v_pk_fma_f32 v[46:47], v[10:11], v[44:45], v[14:15]
	v_pk_mul_f32 v[44:45], v[60:61], v[86:87] op_sel_hi:[1,0]
	v_pk_mul_f32 v[60:61], v[80:81], v[58:59] op_sel_hi:[1,0]
	s_waitcnt vmcnt(0)
	v_pk_fma_f32 v[44:45], v[0:1], v[44:45], v[4:5]
	v_pk_fma_f32 v[24:25], v[24:25], v[60:61], v[28:29]
	v_pk_mul_f32 v[28:29], v[82:83], v[58:59] op_sel_hi:[1,0]
	v_pk_fma_f32 v[42:43], v[2:3], v[42:43], v[6:7]
	v_pk_fma_f32 v[26:27], v[26:27], v[28:29], v[30:31]
	v_pk_mul_f32 v[28:29], v[78:79], v[58:59] op_sel_hi:[1,0]
	v_cmp_lt_i32_e32 vcc, s13, v38
	v_pk_fma_f32 v[16:17], v[16:17], v[28:29], v[20:21]
	v_pk_mul_f32 v[20:21], v[76:77], v[58:59] op_sel_hi:[1,0]
	s_nop 0
	v_pk_fma_f32 v[18:19], v[18:19], v[20:21], v[22:23]
	v_pk_mul_f32 v[20:21], v[74:75], v[58:59] op_sel_hi:[1,0]
	s_nop 0
	v_pk_fma_f32 v[8:9], v[8:9], v[20:21], v[12:13]
	v_pk_mul_f32 v[12:13], v[84:85], v[58:59] op_sel_hi:[1,0]
	s_nop 0
	v_pk_fma_f32 v[10:11], v[10:11], v[12:13], v[14:15]
	v_pk_mul_f32 v[12:13], v[72:73], v[58:59] op_sel_hi:[1,0]
	s_nop 0
	v_pk_fma_f32 v[0:1], v[0:1], v[12:13], v[4:5]
	v_pk_mul_f32 v[4:5], v[70:71], v[58:59] op_sel_hi:[1,0]
	s_nop 0
	v_pk_fma_f32 v[2:3], v[2:3], v[4:5], v[6:7]
	v_add_u32_e32 v4, 0xfffff000, v38
	v_lshrrev_b32_e32 v4, 12, v4
	v_add_u32_e32 v4, 1, v4
	v_cndmask_b32_e32 v4, 0, v4, vcc
	v_mov_b32_e32 v5, v137
	v_lshl_add_u64 v[4:5], v[4:5], 0, s[2:3]
	v_mov_b64_e32 v[6:7], s[56:57]
	v_mad_u64_u32 v[6:7], s[0:1], v4, s12, v[6:7]
	v_mad_i32_i24 v7, v5, s12, v7
	v_lshl_add_u64 v[4:5], v[6:7], 0, v[40:41]
	v_add_co_u32_e32 v12, vcc, s11, v4
	v_lshl_add_u64 v[70:71], v[4:5], 0, s[18:19]
	s_nop 0
	v_addc_co_u32_e32 v13, vcc, 0, v5, vcc
	v_lshl_add_u64 v[40:41], v[4:5], 0, s[14:15]
	global_load_dwordx4 v[4:7], v[12:13], off offset:-4096
	s_nop 0
	global_load_dwordx4 v[12:15], v[12:13], off
	s_nop 0
	global_load_dwordx4 v[20:23], v[40:41], off offset:1024
	global_load_dwordx4 v[28:31], v[70:71], off offset:1024
	global_load_dwordx4 v[58:61], v[40:41], off offset:2048
	global_load_dwordx4 v[62:65], v[70:71], off offset:2048
	global_load_dwordx4 v[66:69], v[40:41], off offset:3072
	s_nop 0
	global_load_dwordx4 v[70:73], v[70:71], off offset:3072
	v_cvt_pk_bf16_f32 v40, v56, v57
	v_cvt_pk_bf16_f32 v41, v54, v55
	global_store_dwordx2 v[36:37], v[40:41], off
	s_waitcnt vmcnt(7)
	v_pk_add_f32 v[12:13], v[12:13], 1.0 op_sel_hi:[1,0]
	v_pk_add_f32 v[14:15], v[14:15], 1.0 op_sel_hi:[1,0]
	v_pk_fma_f32 v[40:41], v[12:13], v[56:57], v[4:5]
	v_pk_fma_f32 v[54:55], v[14:15], v[54:55], v[6:7]
	v_cvt_pk_bf16_f32 v40, v40, v41
	v_cvt_pk_bf16_f32 v41, v54, v55
	v_mov_b64_e32 v[54:55], s[62:63]
	v_mad_i64_i32 v[38:39], s[0:1], v38, s36, v[54:55]
	v_lshl_add_u64 v[38:39], v[38:39], 0, v[136:137]
	global_store_dwordx2 v[38:39], v[40:41], off
	v_cvt_pk_bf16_f32 v40, v52, v53
	v_cvt_pk_bf16_f32 v41, v50, v51
	s_waitcnt vmcnt(6)
	v_pk_add_f32 v[28:29], v[28:29], 1.0 op_sel_hi:[1,0]
	v_pk_add_f32 v[30:31], v[30:31], 1.0 op_sel_hi:[1,0]
	global_store_dwordx2 v[36:37], v[40:41], off offset:512
	v_pk_fma_f32 v[40:41], v[28:29], v[52:53], v[20:21]
	v_pk_fma_f32 v[50:51], v[30:31], v[50:51], v[22:23]
	v_cvt_pk_bf16_f32 v40, v40, v41
	v_cvt_pk_bf16_f32 v41, v50, v51
	global_store_dwordx2 v[38:39], v[40:41], off offset:512
	v_cvt_pk_bf16_f32 v40, v48, v49
	v_cvt_pk_bf16_f32 v41, v46, v47
	global_store_dwordx2 v[36:37], v[40:41], off offset:1024
	s_waitcnt vmcnt(7)
	v_pk_add_f32 v[40:41], v[62:63], 1.0 op_sel_hi:[1,0]
	v_pk_add_f32 v[50:51], v[64:65], 1.0 op_sel_hi:[1,0]
	v_pk_fma_f32 v[48:49], v[40:41], v[48:49], v[58:59]
	v_pk_fma_f32 v[46:47], v[50:51], v[46:47], v[60:61]
	v_cvt_pk_bf16_f32 v48, v48, v49
	v_cvt_pk_bf16_f32 v49, v46, v47
	v_cvt_pk_bf16_f32 v46, v44, v45
	v_cvt_pk_bf16_f32 v47, v42, v43
	global_store_dwordx2 v[38:39], v[48:49], off offset:1024
	global_store_dwordx2 v[36:37], v[46:47], off offset:1536
	s_waitcnt vmcnt(7)
	v_pk_add_f32 v[36:37], v[70:71], 1.0 op_sel_hi:[1,0]
	v_pk_add_f32 v[46:47], v[72:73], 1.0 op_sel_hi:[1,0]
	v_pk_fma_f32 v[44:45], v[36:37], v[44:45], v[66:67]
	v_pk_fma_f32 v[42:43], v[46:47], v[42:43], v[68:69]
	v_pk_fma_f32 v[4:5], v[12:13], v[24:25], v[4:5]
	v_pk_fma_f32 v[6:7], v[14:15], v[26:27], v[6:7]
	v_cvt_pk_bf16_f32 v44, v44, v45
	v_cvt_pk_bf16_f32 v45, v42, v43
	v_cvt_pk_bf16_f32 v4, v4, v5
	v_cvt_pk_bf16_f32 v5, v6, v7
	v_mad_i64_i32 v[6:7], s[0:1], v34, s36, v[54:55]
	global_store_dwordx2 v[38:39], v[44:45], off offset:1536
	v_cvt_pk_bf16_f32 v38, v24, v25
	v_cvt_pk_bf16_f32 v39, v26, v27
	v_lshl_add_u64 v[6:7], v[6:7], 0, v[136:137]
	global_store_dwordx2 v[32:33], v[38:39], off
	global_store_dwordx2 v[6:7], v[4:5], off
	v_cvt_pk_bf16_f32 v4, v16, v17
	v_cvt_pk_bf16_f32 v5, v18, v19
	global_store_dwordx2 v[32:33], v[4:5], off offset:512
	v_pk_fma_f32 v[4:5], v[28:29], v[16:17], v[20:21]
	v_pk_fma_f32 v[12:13], v[30:31], v[18:19], v[22:23]
	v_cvt_pk_bf16_f32 v4, v4, v5
	v_cvt_pk_bf16_f32 v5, v12, v13
	global_store_dwordx2 v[6:7], v[4:5], off offset:512
	v_cvt_pk_bf16_f32 v4, v8, v9
	v_cvt_pk_bf16_f32 v5, v10, v11
	global_store_dwordx2 v[32:33], v[4:5], off offset:1024
	v_pk_fma_f32 v[4:5], v[40:41], v[8:9], v[58:59]
	v_pk_fma_f32 v[8:9], v[50:51], v[10:11], v[60:61]
	v_cvt_pk_bf16_f32 v4, v4, v5
	v_cvt_pk_bf16_f32 v5, v8, v9
	global_store_dwordx2 v[6:7], v[4:5], off offset:1024
	v_cvt_pk_bf16_f32 v4, v0, v1
	v_cvt_pk_bf16_f32 v5, v2, v3
	v_pk_fma_f32 v[0:1], v[36:37], v[0:1], v[66:67]
	v_pk_fma_f32 v[2:3], v[46:47], v[2:3], v[68:69]
	v_cvt_pk_bf16_f32 v0, v0, v1
	v_cvt_pk_bf16_f32 v1, v2, v3
	global_store_dwordx2 v[32:33], v[4:5], off offset:1536
	global_store_dwordx2 v[6:7], v[0:1], off offset:1536
	s_cbranch_scc0 .LBB0_157

.LBB0_980:
	s_or_b64 exec, exec, s[0:1]
	v_lshlrev_b32_e32 v12, 16, v15
	v_cndmask_b32_e64 v15, 0, v12, s[66:67]
	v_lshlrev_b32_e32 v12, 16, v14
	v_cndmask_b32_e64 v14, 0, v12, s[66:67]
	v_lshlrev_b32_e32 v12, 16, v98
	v_cndmask_b32_e64 v98, 0, v12, s[66:67]
	v_mul_f32_e32 v12, v18, v8
	v_mul_f32_e32 v8, v21, v100
	v_fmac_f32_e32 v8, v20, v99
	v_fmac_f32_e32 v8, v22, v98
	v_mul_f32_e32 v13, v16, v9
	v_mul_f32_e32 v9, 0xbfb8aa3b, v8
	v_exp_f32_e32 v9, v9
	v_mul_f32_e32 v103, v17, v11
	s_waitcnt vmcnt(35)
	v_mul_f32_e32 v102, v19, v10
	v_pk_add_f32 v[12:13], v[12:13], v[102:103]
	v_add_f32_e32 v9, 1.0, v9
	v_div_scale_f32 v99, s[0:1], v9, v9, v8
	s_waitcnt vmcnt(34)
	v_rcp_f32_e32 v101, v99
	v_pk_fma_f32 v[12:13], v[2:3], v[14:15], v[12:13]
	s_lshl_b64 s[0:1], s[14:15], 8
	v_fma_f32 v104, -v99, v101, 1.0
	v_fmac_f32_e32 v101, v104, v101
	v_div_scale_f32 v104, vcc, v8, v9, v8
	v_mul_f32_e32 v105, v104, v101
	v_fma_f32 v106, -v99, v105, v104
	v_fmac_f32_e32 v105, v106, v101
	v_fma_f32 v99, -v99, v105, v104
	v_div_fmas_f32 v99, v99, v101, v105
	v_mul_f32_e32 v101, 0xbfb8aa3b, v13
	v_exp_f32_e32 v103, v101
	v_mul_f32_e32 v101, 0xbfb8aa3b, v12
	v_exp_f32_e32 v102, v101
	v_div_fixup_f32 v99, v99, v9, v8
	v_lshl_add_u64 v[8:9], s[0:1], 0, v[0:1]
	v_lshlrev_b64 v[104:105], 1, v[8:9]
	v_pk_add_f32 v[102:103], v[102:103], 1.0 op_sel_hi:[1,0]
	v_lshl_add_u64 v[106:107], s[78:79], 0, v[104:105]
	v_div_scale_f32 v101, s[0:1], v103, v103, v13
	v_rcp_f32_e32 v108, v101
	s_nop 0
	v_fma_f32 v109, -v101, v108, 1.0
	v_fmac_f32_e32 v108, v109, v108
	v_div_scale_f32 v109, vcc, v13, v103, v13
	v_mul_f32_e32 v110, v109, v108
	v_fma_f32 v111, -v101, v110, v109
	v_fmac_f32_e32 v110, v111, v108
	v_fma_f32 v101, -v101, v110, v109
	v_div_fmas_f32 v101, v101, v108, v110
	v_div_fixup_f32 v13, v101, v103, v13
	v_div_scale_f32 v101, s[0:1], v102, v102, v12
	v_rcp_f32_e32 v103, v101
	s_nop 0
	v_fma_f32 v108, -v101, v103, 1.0
	v_fmac_f32_e32 v103, v108, v103
	v_div_scale_f32 v108, vcc, v12, v102, v12
	v_mul_f32_e32 v109, v108, v103
	v_fma_f32 v110, -v101, v109, v108
	v_fmac_f32_e32 v109, v110, v103
	v_fma_f32 v101, -v101, v109, v108
	v_div_fmas_f32 v101, v101, v103, v109
	v_div_fixup_f32 v12, v101, v102, v12
	v_pk_mul_f32 v[102:103], v[12:13], v[12:13]
	v_cmp_gt_u32_e64 s[98:99], 32, v176
	v_mov_b32_e32 v108, v102
	v_mov_b32_e32 v109, v103
	s_nop 1
	v_permlane32_swap_b32_e32 v108, v102
	v_permlane32_swap_b32_e32 v109, v103
	v_cndmask_b32_e64 v108, v108, v102, s[98:99]
	v_cndmask_b32_e64 v109, v109, v103, s[98:99]
	v_pk_fma_f32 v[102:103], v[12:13], v[12:13], v[108:109]
	v_mov_b32_e32 v108, v102
	v_mov_b32_e32 v109, v103
	s_nop 1
	v_permlane16_swap_b32_e32 v108, v102
	v_permlane16_swap_b32_e32 v109, v103
	v_pk_add_f32 v[102:103], v[102:103], v[108:109]
	s_nop 1
	v_add_f32_dpp v102, v102, v102 row_ror:8 row_mask:0xf bank_mask:0xf
	v_add_f32_dpp v103, v103, v103 row_ror:8 row_mask:0xf bank_mask:0xf
	s_nop 0
	v_add_f32_dpp v102, v102, v102 row_ror:4 row_mask:0xf bank_mask:0xf
	v_add_f32_dpp v103, v103, v103 row_ror:4 row_mask:0xf bank_mask:0xf
	s_nop 0
	v_add_f32_dpp v102, v102, v102 row_ror:2 row_mask:0xf bank_mask:0xf
	v_add_f32_dpp v103, v103, v103 row_ror:2 row_mask:0xf bank_mask:0xf
	s_nop 0
	v_add_f32_dpp v102, v102, v102 row_ror:1 row_mask:0xf bank_mask:0xf
	v_add_f32_dpp v103, v103, v103 row_ror:1 row_mask:0xf bank_mask:0xf
	s_nop 0
	v_pk_add_f32 v[102:103], v[102:103], s[22:23] op_sel_hi:[1,0]
	s_nop 0
	v_mul_f32_e32 v101, 0x4b800000, v103
	v_cmp_gt_f32_e64 s[0:1], s33, v103
	v_cmp_gt_f32_e32 vcc, s33, v102
	s_nop 0
	v_cndmask_b32_e64 v101, v103, v101, s[0:1]
	v_rsq_f32_e32 v101, v101
	v_cvt_pk_bf16_f32 v99, v99, s0
	v_mul_f32_e32 v103, 0x45800000, v101
	v_cndmask_b32_e64 v101, v101, v103, s[0:1]
	v_mul_f32_e32 v13, v13, v101
	v_mul_f32_e32 v13, 0x3e000000, v13
	v_cvt_pk_bf16_f32 v13, v13, s0
	global_store_short v[106:107], v13, off
	v_mul_f32_e32 v13, 0x4b800000, v102
	v_cndmask_b32_e32 v13, v102, v13, vcc
	v_rsq_f32_e32 v13, v13
	s_nop 0
	v_mul_f32_e32 v101, 0x45800000, v13
	v_cndmask_b32_e32 v13, v13, v101, vcc
	v_mul_f32_e32 v12, v12, v13
	v_cvt_pk_bf16_f32 v101, v12, s0
	v_lshl_add_u64 v[12:13], s[80:81], 0, v[104:105]
	global_store_short v[12:13], v101, off
	v_lshl_add_u64 v[12:13], s[82:83], 0, v[104:105]
	global_store_short v[12:13], v99, off
	s_and_saveexec_b64 s[0:1], s[38:39]
	s_cbranch_execz .LBB0_984
	s_waitcnt vmcnt(36)
	v_lshlrev_b32_e32 v12, 16, v97
	v_mul_f32_e32 v12, 0xbfb8aa3b, v12
	v_exp_f32_e32 v12, v12
	v_mad_i64_i32 v[8:9], s[14:15], s14, v199, v[8:9]
	s_waitcnt vmcnt(35)
	v_lshlrev_b32_e32 v96, 16, v96
	v_add_f32_e32 v12, 1.0, v12
	v_div_scale_f32 v13, s[16:17], v12, v12, 1.0
	v_rcp_f32_e32 v97, v13
	v_div_scale_f32 v99, vcc, 1.0, v12, 1.0
	s_mov_b32 s14, 0x41a00000
	v_fma_f32 v101, -v13, v97, 1.0
	v_fmac_f32_e32 v97, v101, v97
	v_mul_f32_e32 v101, v99, v97
	v_fma_f32 v102, -v13, v101, v99
	v_fmac_f32_e32 v101, v102, v97
	v_fma_f32 v13, -v13, v101, v99
	v_div_fmas_f32 v13, v13, v97, v101
	v_div_fixup_f32 v97, v13, v12, 1.0
	v_lshl_add_u64 v[12:13], v[8:9], 2, s[84:85]
	global_store_dword v[12:13], v97, off
	v_add_f32_e32 v12, v24, v96
	v_cmp_nlt_f32_e32 vcc, s14, v12
	s_and_saveexec_b64 s[14:15], vcc
	s_cbranch_execz .LBB0_983
	v_mul_f32_e32 v12, 0x3fb8aa3b, v12
	v_exp_f32_e32 v99, v12
	s_mov_b32 s16, 0x3f2aaaab
	v_add_f32_e32 v96, 1.0, v99
	v_frexp_mant_f32_e32 v101, v96
	v_cvt_f64_f32_e32 v[12:13], v96
	v_frexp_exp_i32_f64_e32 v12, v[12:13]
	v_cmp_gt_f32_e32 vcc, s16, v101
	v_add_f32_e32 v97, -1.0, v96
	v_sub_f32_e32 v102, v97, v96
	v_subbrev_co_u32_e32 v101, vcc, 0, v12, vcc
	v_sub_u32_e32 v12, 0, v101
	v_sub_f32_e32 v97, v99, v97
	v_add_f32_e32 v102, 1.0, v102
	v_ldexp_f32 v13, v96, v12
	v_add_f32_e32 v97, v97, v102
	v_add_f32_e32 v96, -1.0, v13
	v_add_f32_e32 v102, 1.0, v13
	v_ldexp_f32 v12, v97, v12
	v_add_f32_e32 v97, 1.0, v96
	v_add_f32_e32 v103, -1.0, v102
	v_sub_f32_e32 v97, v13, v97
	v_sub_f32_e32 v13, v13, v103
	v_add_f32_e32 v97, v12, v97
	v_add_f32_e32 v12, v12, v13
	v_add_f32_e32 v106, v102, v12
	v_rcp_f32_e32 v108, v106
	v_sub_f32_e32 v13, v106, v102
	v_sub_f32_e32 v107, v12, v13
	v_add_f32_e32 v13, v96, v97
	v_mul_f32_e32 v110, v13, v108
	v_sub_f32_e32 v12, v13, v96
	v_mul_f32_e32 v96, v106, v110
	v_fma_f32 v102, v110, v106, -v96
	v_fmac_f32_e32 v102, v110, v107
	v_sub_f32_e32 v109, v97, v12
	v_add_f32_e32 v12, v96, v102
	v_sub_f32_e32 v97, v13, v12
	v_pk_add_f32 v[104:105], v[12:13], v[96:97] neg_lo:[0,1] neg_hi:[0,1]
	v_mov_b32_e32 v103, v12
	v_pk_add_f32 v[12:13], v[104:105], v[102:103] neg_lo:[0,1] neg_hi:[0,1]
	s_mov_b32 s16, 0x3f317218
	v_add_f32_e32 v13, v109, v13
	v_add_f32_e32 v12, v12, v13
	v_add_f32_e32 v13, v97, v12
	v_mul_f32_e32 v109, v108, v13
	v_mul_f32_e32 v96, v106, v109
	v_fma_f32 v102, v109, v106, -v96
	v_fmac_f32_e32 v102, v109, v107
	v_sub_f32_e32 v97, v97, v13
	v_add_f32_e32 v106, v12, v97
	v_add_f32_e32 v12, v96, v102
	v_sub_f32_e32 v97, v13, v12
	v_pk_add_f32 v[104:105], v[12:13], v[96:97] neg_lo:[0,1] neg_hi:[0,1]
	v_mov_b32_e32 v103, v12
	v_pk_add_f32 v[12:13], v[104:105], v[102:103] neg_lo:[0,1] neg_hi:[0,1]
	v_cmp_neq_f32_e32 vcc, s36, v99
	v_add_f32_e32 v13, v106, v13
	v_add_f32_e32 v12, v12, v13
	v_add_f32_e32 v13, v110, v109
	v_add_f32_e32 v12, v97, v12
	v_sub_f32_e32 v96, v13, v110
	v_mul_f32_e32 v12, v108, v12
	v_sub_f32_e32 v96, v109, v96
	v_add_f32_e32 v96, v96, v12
	v_add_f32_e32 v102, v13, v96
	v_mul_f32_e32 v103, v102, v102
	v_fmamk_f32 v12, v103, 0x3e9b6dac, v172
	v_fmaak_f32 v143, v103, v12, 0x3f2aaada
	v_cvt_f32_i32_e32 v12, v101
	v_sub_f32_e32 v13, v102, v13
	v_sub_f32_e32 v13, v96, v13
	v_ldexp_f32 v101, v13, 1
	v_mul_f32_e32 v13, v102, v103
	v_ldexp_f32 v97, v102, 1
	v_pk_mul_f32 v[102:103], v[12:13], v[142:143]
	s_nop 0
	v_fma_f32 v96, v12, s16, -v102
	v_fmac_f32_e32 v96, 0xb102e308, v12
	v_pk_add_f32 v[12:13], v[102:103], v[96:97]
	v_mov_b32_e32 v104, v102
	v_sub_f32_e32 v97, v13, v97
	v_sub_f32_e32 v97, v103, v97
	v_add_f32_e32 v105, v101, v97
	v_pk_add_f32 v[102:103], v[12:13], v[102:103] neg_lo:[0,1] neg_hi:[0,1]
	v_pk_add_f32 v[106:107], v[12:13], v[104:105]
	v_mov_b32_e32 v97, v12
	v_mov_b32_e32 v103, v107
	v_pk_add_f32 v[108:109], v[96:97], v[102:103] neg_lo:[0,1] neg_hi:[0,1]
	v_pk_add_f32 v[96:97], v[96:97], v[102:103]
	v_mov_b32_e32 v104, v105
	v_pk_add_f32 v[102:103], v[96:97], v[12:13] op_sel:[1,0] op_sel_hi:[0,1] neg_lo:[0,1] neg_hi:[0,1]
	v_pk_add_f32 v[110:111], v[106:107], v[102:103] op_sel_hi:[1,0] neg_lo:[0,1] neg_hi:[0,1]
	v_mov_b32_e32 v106, v107
	v_mov_b32_e32 v107, v97
	v_pk_mov_b32 v[102:103], v[12:13], v[102:103] op_sel:[1,0]
	v_mov_b32_e32 v105, v12
	v_pk_add_f32 v[102:103], v[106:107], v[102:103] neg_lo:[0,1] neg_hi:[0,1]
	v_mov_b32_e32 v110, v108
	v_pk_add_f32 v[12:13], v[104:105], v[102:103] neg_lo:[0,1] neg_hi:[0,1]
	v_mov_b32_e32 v109, v97
	v_pk_add_f32 v[102:103], v[110:111], v[12:13]
	s_mov_b32 s16, 0x33800000
	v_pk_add_f32 v[104:105], v[102:103], v[102:103] op_sel:[0,1] op_sel_hi:[1,0]
	s_nop 0
	v_pk_add_f32 v[96:97], v[96:97], v[104:105] op_sel:[1,0] op_sel_hi:[0,1]
	v_mov_b32_e32 v103, v96
	v_pk_add_f32 v[106:107], v[102:103], v[108:109] neg_lo:[0,1] neg_hi:[0,1]
	v_mov_b32_e32 v13, v104
	v_sub_f32_e32 v97, v102, v106
	v_pk_add_f32 v[12:13], v[12:13], v[106:107] neg_lo:[0,1] neg_hi:[0,1]
	v_sub_f32_e32 v97, v108, v97
	v_add_f32_e32 v12, v12, v97
	v_add_f32_e32 v12, v12, v13
	v_add_f32_e32 v12, v96, v12
	v_cndmask_b32_e32 v12, v185, v12, vcc
	v_cmp_ngt_f32_e32 vcc, -1.0, v99
	s_nop 1
	v_cndmask_b32_e32 v12, v196, v12, vcc
	v_cmp_neq_f32_e32 vcc, -1.0, v99
	s_nop 1
	v_cndmask_b32_e32 v12, v197, v12, vcc
	v_cmp_lt_f32_e64 vcc, |v99|, s16
	s_nop 1
	v_cndmask_b32_e32 v12, v12, v99, vcc

.LBB0_984:
	s_or_b64 exec, exec, s[0:1]
	v_lshlrev_b32_e32 v8, 16, v93
	v_cndmask_b32_e64 v13, 0, v8, s[64:65]
	v_lshlrev_b32_e32 v8, 16, v95
	v_cndmask_b32_e64 v12, 0, v8, s[64:65]
	v_lshlrev_b32_e32 v8, 16, v94
	v_cndmask_b32_e64 v93, 0, v8, s[64:65]
	v_mul_f32_e32 v8, v21, v98
	v_fmac_f32_e32 v8, v20, v100
	v_fmac_f32_e32 v8, v22, v93
	v_mul_f32_e32 v9, 0xbfb8aa3b, v8
	v_exp_f32_e32 v9, v9
	v_mul_f32_e32 v11, v16, v11
	v_mul_f32_e32 v95, v17, v15
	v_mul_f32_e32 v10, v18, v10
	v_add_f32_e32 v9, 1.0, v9
	s_waitcnt vmcnt(35)
	v_div_scale_f32 v96, s[0:1], v9, v9, v8
	v_rcp_f32_e32 v97, v96
	v_mul_f32_e32 v94, v19, v14
	v_pk_add_f32 v[10:11], v[10:11], v[94:95]
	s_lshl_b64 s[0:1], s[12:13], 8
	v_pk_fma_f32 v[10:11], v[2:3], v[12:13], v[10:11]
	v_fma_f32 v99, -v96, v97, 1.0
	v_mul_f32_e32 v94, 0xbfb8aa3b, v11
	v_fmac_f32_e32 v97, v99, v97
	v_div_scale_f32 v99, vcc, v8, v9, v8
	v_exp_f32_e32 v95, v94
	v_mul_f32_e32 v94, 0xbfb8aa3b, v10
	v_mul_f32_e32 v100, v99, v97
	v_exp_f32_e32 v94, v94
	v_fma_f32 v101, -v96, v100, v99
	v_fmac_f32_e32 v100, v101, v97
	v_fma_f32 v96, -v96, v100, v99
	v_div_fmas_f32 v96, v96, v97, v100
	v_pk_add_f32 v[94:95], v[94:95], 1.0 op_sel_hi:[1,0]
	v_div_fixup_f32 v99, v96, v9, v8
	v_lshl_add_u64 v[8:9], s[0:1], 0, v[0:1]
	v_div_scale_f32 v102, s[0:1], v95, v95, v11
	v_rcp_f32_e32 v103, v102
	v_lshlrev_b64 v[96:97], 1, v[8:9]
	v_lshl_add_u64 v[100:101], s[78:79], 0, v[96:97]
	v_fma_f32 v104, -v102, v103, 1.0
	v_fmac_f32_e32 v103, v104, v103
	v_div_scale_f32 v104, vcc, v11, v95, v11
	v_mul_f32_e32 v105, v104, v103
	v_fma_f32 v106, -v102, v105, v104
	v_fmac_f32_e32 v105, v106, v103
	v_fma_f32 v102, -v102, v105, v104
	v_div_fmas_f32 v102, v102, v103, v105
	v_div_fixup_f32 v11, v102, v95, v11
	v_div_scale_f32 v95, s[0:1], v94, v94, v10
	v_rcp_f32_e32 v102, v95
	s_nop 0
	v_fma_f32 v103, -v95, v102, 1.0
	v_fmac_f32_e32 v102, v103, v102
	v_div_scale_f32 v103, vcc, v10, v94, v10
	v_mul_f32_e32 v104, v103, v102
	v_fma_f32 v105, -v95, v104, v103
	v_fmac_f32_e32 v104, v105, v102
	v_fma_f32 v95, -v95, v104, v103
	v_div_fmas_f32 v95, v95, v102, v104
	v_div_fixup_f32 v10, v95, v94, v10
	v_pk_mul_f32 v[94:95], v[10:11], v[10:11]
	v_cmp_gt_u32_e64 s[98:99], 32, v176
	v_mov_b32_e32 v102, v94
	v_mov_b32_e32 v103, v95
	s_nop 1
	v_permlane32_swap_b32_e32 v102, v94
	v_permlane32_swap_b32_e32 v103, v95
	v_cndmask_b32_e64 v102, v102, v94, s[98:99]
	v_cndmask_b32_e64 v103, v103, v95, s[98:99]
	v_pk_fma_f32 v[94:95], v[10:11], v[10:11], v[102:103]
	v_mov_b32_e32 v102, v94
	v_mov_b32_e32 v103, v95
	s_nop 1
	v_permlane16_swap_b32_e32 v102, v94
	v_permlane16_swap_b32_e32 v103, v95
	v_pk_add_f32 v[94:95], v[94:95], v[102:103]
	s_nop 1
	v_add_f32_dpp v94, v94, v94 row_ror:8 row_mask:0xf bank_mask:0xf
	v_add_f32_dpp v95, v95, v95 row_ror:8 row_mask:0xf bank_mask:0xf
	s_nop 0
	v_add_f32_dpp v94, v94, v94 row_ror:4 row_mask:0xf bank_mask:0xf
	v_add_f32_dpp v95, v95, v95 row_ror:4 row_mask:0xf bank_mask:0xf
	s_nop 0
	v_add_f32_dpp v94, v94, v94 row_ror:2 row_mask:0xf bank_mask:0xf
	v_add_f32_dpp v95, v95, v95 row_ror:2 row_mask:0xf bank_mask:0xf
	s_nop 0
	v_add_f32_dpp v94, v94, v94 row_ror:1 row_mask:0xf bank_mask:0xf
	v_add_f32_dpp v95, v95, v95 row_ror:1 row_mask:0xf bank_mask:0xf
	s_nop 0
	v_pk_add_f32 v[94:95], v[94:95], s[22:23] op_sel_hi:[1,0]
	s_nop 0
	v_mul_f32_e32 v102, 0x4b800000, v95
	v_cmp_gt_f32_e64 s[0:1], s33, v95
	v_cmp_gt_f32_e32 vcc, s33, v94
	s_nop 0
	v_cndmask_b32_e64 v95, v95, v102, s[0:1]
	v_rsq_f32_e32 v95, v95
	s_nop 0
	v_mul_f32_e32 v102, 0x45800000, v95
	v_cndmask_b32_e64 v95, v95, v102, s[0:1]
	v_mul_f32_e32 v11, v11, v95
	v_mul_f32_e32 v11, 0x3e000000, v11
	v_cvt_pk_bf16_f32 v11, v11, s0
	global_store_short v[100:101], v11, off
	v_mul_f32_e32 v11, 0x4b800000, v94
	v_cndmask_b32_e32 v11, v94, v11, vcc
	v_rsq_f32_e32 v11, v11
	s_nop 0
	v_mul_f32_e32 v94, 0x45800000, v11
	v_cndmask_b32_e32 v11, v11, v94, vcc
	v_mul_f32_e32 v10, v10, v11
	v_cvt_pk_bf16_f32 v94, v10, s0
	v_lshl_add_u64 v[10:11], s[80:81], 0, v[96:97]
	global_store_short v[10:11], v94, off
	v_cvt_pk_bf16_f32 v94, v99, s0
	v_lshl_add_u64 v[10:11], s[82:83], 0, v[96:97]
	global_store_short v[10:11], v94, off
	s_and_saveexec_b64 s[0:1], s[38:39]
	s_cbranch_execz .LBB0_988
	s_waitcnt vmcnt(37)
	v_lshlrev_b32_e32 v10, 16, v92
	v_mul_f32_e32 v10, 0xbfb8aa3b, v10
	v_exp_f32_e32 v10, v10
	v_mad_i64_i32 v[8:9], s[12:13], s12, v199, v[8:9]
	s_waitcnt vmcnt(36)
	v_lshlrev_b32_e32 v91, 16, v91
	v_add_f32_e32 v10, 1.0, v10
	v_div_scale_f32 v11, s[14:15], v10, v10, 1.0
	v_rcp_f32_e32 v92, v11
	v_div_scale_f32 v94, vcc, 1.0, v10, 1.0
	s_mov_b32 s12, 0x41a00000
	v_fma_f32 v95, -v11, v92, 1.0
	v_fmac_f32_e32 v92, v95, v92
	v_mul_f32_e32 v95, v94, v92
	v_fma_f32 v96, -v11, v95, v94
	v_fmac_f32_e32 v95, v96, v92
	v_fma_f32 v11, -v11, v95, v94
	v_div_fmas_f32 v11, v11, v92, v95
	v_div_fixup_f32 v92, v11, v10, 1.0
	v_lshl_add_u64 v[10:11], v[8:9], 2, s[84:85]
	global_store_dword v[10:11], v92, off
	v_add_f32_e32 v10, v24, v91
	v_cmp_nlt_f32_e32 vcc, s12, v10
	s_and_saveexec_b64 s[12:13], vcc
	s_cbranch_execz .LBB0_987
	v_mul_f32_e32 v10, 0x3fb8aa3b, v10
	v_exp_f32_e32 v91, v10
	s_mov_b32 s14, 0x3f2aaaab
	v_add_f32_e32 v92, 1.0, v91
	v_frexp_mant_f32_e32 v95, v92
	v_cvt_f64_f32_e32 v[10:11], v92
	v_frexp_exp_i32_f64_e32 v10, v[10:11]
	v_cmp_gt_f32_e32 vcc, s14, v95
	v_add_f32_e32 v94, -1.0, v92
	v_sub_f32_e32 v96, v94, v92
	v_subbrev_co_u32_e32 v99, vcc, 0, v10, vcc
	v_sub_u32_e32 v10, 0, v99
	v_sub_f32_e32 v94, v91, v94
	v_add_f32_e32 v96, 1.0, v96
	v_ldexp_f32 v11, v92, v10
	v_add_f32_e32 v94, v94, v96
	v_add_f32_e32 v92, -1.0, v11
	v_add_f32_e32 v95, 1.0, v11
	v_ldexp_f32 v10, v94, v10
	v_add_f32_e32 v94, 1.0, v92
	v_add_f32_e32 v96, -1.0, v95
	v_sub_f32_e32 v94, v11, v94
	v_sub_f32_e32 v11, v11, v96
	v_add_f32_e32 v94, v10, v94
	v_add_f32_e32 v10, v10, v11
	v_add_f32_e32 v102, v95, v10
	v_rcp_f32_e32 v104, v102
	v_sub_f32_e32 v11, v102, v95
	v_sub_f32_e32 v103, v10, v11
	v_add_f32_e32 v11, v92, v94
	v_sub_f32_e32 v10, v11, v92
	v_mul_f32_e32 v105, v11, v104
	v_sub_f32_e32 v92, v94, v10
	v_mul_f32_e32 v94, v102, v105
	v_fma_f32 v96, v105, v102, -v94
	v_fmac_f32_e32 v96, v105, v103
	v_add_f32_e32 v10, v94, v96
	v_sub_f32_e32 v95, v11, v10
	v_pk_add_f32 v[100:101], v[10:11], v[94:95] neg_lo:[0,1] neg_hi:[0,1]
	v_mov_b32_e32 v97, v10
	v_pk_add_f32 v[10:11], v[100:101], v[96:97] neg_lo:[0,1] neg_hi:[0,1]
	s_mov_b32 s14, 0x3f317218
	v_add_f32_e32 v11, v92, v11
	v_add_f32_e32 v10, v10, v11
	v_add_f32_e32 v11, v95, v10
	v_mul_f32_e32 v92, v104, v11
	v_mul_f32_e32 v94, v102, v92
	v_fma_f32 v96, v92, v102, -v94
	v_fmac_f32_e32 v96, v92, v103
	v_sub_f32_e32 v95, v95, v11
	v_add_f32_e32 v102, v10, v95
	v_add_f32_e32 v10, v94, v96
	v_sub_f32_e32 v95, v11, v10
	v_pk_add_f32 v[100:101], v[10:11], v[94:95] neg_lo:[0,1] neg_hi:[0,1]
	v_mov_b32_e32 v97, v10
	v_pk_add_f32 v[10:11], v[100:101], v[96:97] neg_lo:[0,1] neg_hi:[0,1]
	v_cmp_neq_f32_e32 vcc, s36, v91
	v_add_f32_e32 v11, v102, v11
	v_add_f32_e32 v10, v10, v11
	v_add_f32_e32 v11, v105, v92
	v_add_f32_e32 v10, v95, v10
	v_sub_f32_e32 v94, v11, v105
	v_mul_f32_e32 v10, v104, v10
	v_sub_f32_e32 v92, v92, v94
	v_add_f32_e32 v92, v92, v10
	v_add_f32_e32 v94, v11, v92
	v_mul_f32_e32 v96, v94, v94
	v_fmamk_f32 v10, v96, 0x3e9b6dac, v172
	v_fmaak_f32 v143, v96, v10, 0x3f2aaada
	v_cvt_f32_i32_e32 v10, v99
	v_sub_f32_e32 v11, v94, v11
	v_sub_f32_e32 v11, v92, v11
	v_ldexp_f32 v92, v11, 1
	v_mul_f32_e32 v11, v94, v96
	v_pk_mul_f32 v[96:97], v[10:11], v[142:143]
	v_ldexp_f32 v95, v94, 1
	v_fma_f32 v94, v10, s14, -v96
	v_fmac_f32_e32 v94, 0xb102e308, v10
	v_pk_add_f32 v[10:11], v[96:97], v[94:95]
	v_mov_b32_e32 v100, v96
	v_sub_f32_e32 v95, v11, v95
	v_sub_f32_e32 v95, v97, v95
	v_add_f32_e32 v101, v92, v95
	v_pk_add_f32 v[96:97], v[10:11], v[96:97] neg_lo:[0,1] neg_hi:[0,1]
	v_pk_add_f32 v[102:103], v[10:11], v[100:101]
	v_mov_b32_e32 v95, v10
	v_mov_b32_e32 v97, v103
	v_pk_add_f32 v[104:105], v[94:95], v[96:97] neg_lo:[0,1] neg_hi:[0,1]
	v_pk_add_f32 v[94:95], v[94:95], v[96:97]
	v_mov_b32_e32 v100, v101
	v_pk_add_f32 v[96:97], v[94:95], v[10:11] op_sel:[1,0] op_sel_hi:[0,1] neg_lo:[0,1] neg_hi:[0,1]
	v_pk_add_f32 v[106:107], v[102:103], v[96:97] op_sel_hi:[1,0] neg_lo:[0,1] neg_hi:[0,1]
	v_mov_b32_e32 v102, v103
	v_mov_b32_e32 v103, v95
	v_pk_mov_b32 v[96:97], v[10:11], v[96:97] op_sel:[1,0]
	v_mov_b32_e32 v101, v10
	v_pk_add_f32 v[96:97], v[102:103], v[96:97] neg_lo:[0,1] neg_hi:[0,1]
	v_mov_b32_e32 v106, v104
	v_pk_add_f32 v[10:11], v[100:101], v[96:97] neg_lo:[0,1] neg_hi:[0,1]
	v_mov_b32_e32 v105, v95
	v_pk_add_f32 v[96:97], v[106:107], v[10:11]
	s_mov_b32 s14, 0x33800000
	v_pk_add_f32 v[100:101], v[96:97], v[96:97] op_sel:[0,1] op_sel_hi:[1,0]
	s_nop 0
	v_pk_add_f32 v[94:95], v[94:95], v[100:101] op_sel:[1,0] op_sel_hi:[0,1]
	v_mov_b32_e32 v97, v94
	v_pk_add_f32 v[102:103], v[96:97], v[104:105] neg_lo:[0,1] neg_hi:[0,1]
	v_mov_b32_e32 v11, v100
	v_sub_f32_e32 v92, v96, v102
	v_pk_add_f32 v[10:11], v[10:11], v[102:103] neg_lo:[0,1] neg_hi:[0,1]
	v_sub_f32_e32 v92, v104, v92
	v_add_f32_e32 v10, v10, v92
	v_add_f32_e32 v10, v10, v11
	v_add_f32_e32 v10, v94, v10
	v_cndmask_b32_e32 v10, v185, v10, vcc
	v_cmp_ngt_f32_e32 vcc, -1.0, v91
	s_nop 1
	v_cndmask_b32_e32 v10, v196, v10, vcc
	v_cmp_neq_f32_e32 vcc, -1.0, v91
	s_nop 1
	v_cndmask_b32_e32 v10, v197, v10, vcc
	v_cmp_lt_f32_e64 vcc, |v91|, s14
	s_nop 1
	v_cndmask_b32_e32 v10, v10, v91, vcc

.LBB0_988:
	s_or_b64 exec, exec, s[0:1]
	v_lshlrev_b32_e32 v8, 16, v90
	v_cndmask_b32_e64 v11, 0, v8, s[62:63]
	v_lshlrev_b32_e32 v8, 16, v89
	v_cndmask_b32_e64 v10, 0, v8, s[62:63]
	v_lshlrev_b32_e32 v8, 16, v88
	v_cndmask_b32_e64 v88, 0, v8, s[62:63]
	v_mul_f32_e32 v8, v21, v93
	v_fmac_f32_e32 v8, v20, v98
	v_fmac_f32_e32 v8, v22, v88
	v_mul_f32_e32 v9, 0xbfb8aa3b, v8
	v_exp_f32_e32 v9, v9
	v_mul_f32_e32 v15, v16, v15
	s_waitcnt vmcnt(36)
	v_mul_f32_e32 v91, v17, v13
	v_mul_f32_e32 v14, v18, v14
	v_add_f32_e32 v9, 1.0, v9
	v_div_scale_f32 v89, s[0:1], v9, v9, v8
	v_rcp_f32_e32 v92, v89
	v_mul_f32_e32 v90, v19, v12
	v_pk_add_f32 v[14:15], v[14:15], v[90:91]
	s_lshl_b64 s[0:1], s[10:11], 8
	v_pk_fma_f32 v[14:15], v[2:3], v[10:11], v[14:15]
	v_fma_f32 v94, -v89, v92, 1.0
	v_mul_f32_e32 v90, 0xbfb8aa3b, v15
	v_fmac_f32_e32 v92, v94, v92
	v_div_scale_f32 v94, vcc, v8, v9, v8
	v_exp_f32_e32 v91, v90
	v_mul_f32_e32 v90, 0xbfb8aa3b, v14
	v_mul_f32_e32 v95, v94, v92
	v_exp_f32_e32 v90, v90
	v_fma_f32 v96, -v89, v95, v94
	v_fmac_f32_e32 v95, v96, v92
	v_fma_f32 v89, -v89, v95, v94
	v_div_fmas_f32 v89, v89, v92, v95
	v_pk_add_f32 v[90:91], v[90:91], 1.0 op_sel_hi:[1,0]
	v_div_fixup_f32 v89, v89, v9, v8
	v_lshl_add_u64 v[8:9], s[0:1], 0, v[0:1]
	v_div_scale_f32 v92, s[0:1], v91, v91, v15
	v_rcp_f32_e32 v98, v92
	v_lshlrev_b64 v[94:95], 1, v[8:9]
	v_lshl_add_u64 v[96:97], s[78:79], 0, v[94:95]
	v_fma_f32 v99, -v92, v98, 1.0
	v_fmac_f32_e32 v98, v99, v98
	v_div_scale_f32 v99, vcc, v15, v91, v15
	v_mul_f32_e32 v100, v99, v98
	v_fma_f32 v101, -v92, v100, v99
	v_fmac_f32_e32 v100, v101, v98
	v_fma_f32 v92, -v92, v100, v99
	v_div_fmas_f32 v92, v92, v98, v100
	v_div_fixup_f32 v15, v92, v91, v15
	v_div_scale_f32 v91, s[0:1], v90, v90, v14
	v_rcp_f32_e32 v92, v91
	s_nop 0
	v_fma_f32 v98, -v91, v92, 1.0
	v_fmac_f32_e32 v92, v98, v92
	v_div_scale_f32 v98, vcc, v14, v90, v14
	v_mul_f32_e32 v99, v98, v92
	v_fma_f32 v100, -v91, v99, v98
	v_fmac_f32_e32 v99, v100, v92
	v_fma_f32 v91, -v91, v99, v98
	v_div_fmas_f32 v91, v91, v92, v99
	v_div_fixup_f32 v14, v91, v90, v14
	v_pk_mul_f32 v[90:91], v[14:15], v[14:15]
	v_cmp_gt_u32_e64 s[98:99], 32, v176
	v_mov_b32_e32 v98, v90
	v_mov_b32_e32 v99, v91
	s_nop 1
	v_permlane32_swap_b32_e32 v98, v90
	v_permlane32_swap_b32_e32 v99, v91
	v_cndmask_b32_e64 v98, v98, v90, s[98:99]
	v_cndmask_b32_e64 v99, v99, v91, s[98:99]
	v_pk_fma_f32 v[90:91], v[14:15], v[14:15], v[98:99]
	v_mov_b32_e32 v98, v90
	v_mov_b32_e32 v99, v91
	s_nop 1
	v_permlane16_swap_b32_e32 v98, v90
	v_permlane16_swap_b32_e32 v99, v91
	v_pk_add_f32 v[90:91], v[90:91], v[98:99]
	s_nop 1
	v_add_f32_dpp v90, v90, v90 row_ror:8 row_mask:0xf bank_mask:0xf
	v_add_f32_dpp v91, v91, v91 row_ror:8 row_mask:0xf bank_mask:0xf
	s_nop 0
	v_add_f32_dpp v90, v90, v90 row_ror:4 row_mask:0xf bank_mask:0xf
	v_add_f32_dpp v91, v91, v91 row_ror:4 row_mask:0xf bank_mask:0xf
	s_nop 0
	v_add_f32_dpp v90, v90, v90 row_ror:2 row_mask:0xf bank_mask:0xf
	v_add_f32_dpp v91, v91, v91 row_ror:2 row_mask:0xf bank_mask:0xf
	s_nop 0
	v_add_f32_dpp v90, v90, v90 row_ror:1 row_mask:0xf bank_mask:0xf
	v_add_f32_dpp v91, v91, v91 row_ror:1 row_mask:0xf bank_mask:0xf
	s_nop 0
	v_pk_add_f32 v[90:91], v[90:91], s[22:23] op_sel_hi:[1,0]
	s_nop 0
	v_mul_f32_e32 v92, 0x4b800000, v91
	v_cmp_gt_f32_e64 s[0:1], s33, v91
	v_cmp_gt_f32_e32 vcc, s33, v90
	s_nop 0
	v_cndmask_b32_e64 v91, v91, v92, s[0:1]
	v_rsq_f32_e32 v91, v91
	v_cvt_pk_bf16_f32 v89, v89, s0
	v_mul_f32_e32 v92, 0x45800000, v91
	v_cndmask_b32_e64 v91, v91, v92, s[0:1]
	v_mul_f32_e32 v15, v15, v91
	v_mul_f32_e32 v15, 0x3e000000, v15
	v_cvt_pk_bf16_f32 v15, v15, s0
	global_store_short v[96:97], v15, off
	v_mul_f32_e32 v15, 0x4b800000, v90
	v_cndmask_b32_e32 v15, v90, v15, vcc
	v_rsq_f32_e32 v15, v15
	s_nop 0
	v_mul_f32_e32 v90, 0x45800000, v15
	v_cndmask_b32_e32 v15, v15, v90, vcc
	v_mul_f32_e32 v14, v14, v15
	v_cvt_pk_bf16_f32 v90, v14, s0
	v_lshl_add_u64 v[14:15], s[80:81], 0, v[94:95]
	global_store_short v[14:15], v90, off
	v_lshl_add_u64 v[14:15], s[82:83], 0, v[94:95]
	global_store_short v[14:15], v89, off
	s_and_saveexec_b64 s[0:1], s[38:39]
	s_cbranch_execz .LBB0_992
	s_waitcnt vmcnt(38)
	v_lshlrev_b32_e32 v14, 16, v87
	v_mul_f32_e32 v14, 0xbfb8aa3b, v14
	v_exp_f32_e32 v14, v14
	v_mad_i64_i32 v[8:9], s[10:11], s10, v199, v[8:9]
	s_waitcnt vmcnt(37)
	v_lshlrev_b32_e32 v86, 16, v86
	v_add_f32_e32 v14, 1.0, v14
	v_div_scale_f32 v15, s[12:13], v14, v14, 1.0
	v_rcp_f32_e32 v87, v15
	v_div_scale_f32 v89, vcc, 1.0, v14, 1.0
	s_mov_b32 s10, 0x41a00000
	v_fma_f32 v90, -v15, v87, 1.0
	v_fmac_f32_e32 v87, v90, v87
	v_mul_f32_e32 v90, v89, v87
	v_fma_f32 v91, -v15, v90, v89
	v_fmac_f32_e32 v90, v91, v87
	v_fma_f32 v15, -v15, v90, v89
	v_div_fmas_f32 v15, v15, v87, v90
	v_div_fixup_f32 v87, v15, v14, 1.0
	v_lshl_add_u64 v[14:15], v[8:9], 2, s[84:85]
	global_store_dword v[14:15], v87, off
	v_add_f32_e32 v14, v24, v86
	v_cmp_nlt_f32_e32 vcc, s10, v14
	s_and_saveexec_b64 s[10:11], vcc
	s_cbranch_execz .LBB0_991
	v_mul_f32_e32 v14, 0x3fb8aa3b, v14
	v_exp_f32_e32 v89, v14
	s_mov_b32 s12, 0x3f2aaaab
	v_add_f32_e32 v86, 1.0, v89
	v_frexp_mant_f32_e32 v90, v86
	v_cvt_f64_f32_e32 v[14:15], v86
	v_frexp_exp_i32_f64_e32 v14, v[14:15]
	v_cmp_gt_f32_e32 vcc, s12, v90
	v_add_f32_e32 v87, -1.0, v86
	v_sub_f32_e32 v91, v87, v86
	v_subbrev_co_u32_e32 v92, vcc, 0, v14, vcc
	v_sub_u32_e32 v14, 0, v92
	v_sub_f32_e32 v87, v89, v87
	v_add_f32_e32 v91, 1.0, v91
	v_ldexp_f32 v15, v86, v14
	v_add_f32_e32 v87, v87, v91
	v_add_f32_e32 v86, -1.0, v15
	v_add_f32_e32 v90, 1.0, v15
	v_ldexp_f32 v14, v87, v14
	v_add_f32_e32 v87, 1.0, v86
	v_add_f32_e32 v91, -1.0, v90
	v_sub_f32_e32 v87, v15, v87
	v_sub_f32_e32 v15, v15, v91
	v_add_f32_e32 v87, v14, v87
	v_add_f32_e32 v14, v14, v15
	v_add_f32_e32 v96, v90, v14
	v_rcp_f32_e32 v98, v96
	v_sub_f32_e32 v15, v96, v90
	v_sub_f32_e32 v97, v14, v15
	v_add_f32_e32 v15, v86, v87
	v_mul_f32_e32 v100, v15, v98
	v_sub_f32_e32 v14, v15, v86
	v_mul_f32_e32 v86, v96, v100
	v_fma_f32 v90, v100, v96, -v86
	v_fmac_f32_e32 v90, v100, v97
	v_sub_f32_e32 v99, v87, v14
	v_add_f32_e32 v14, v86, v90
	v_sub_f32_e32 v87, v15, v14
	v_pk_add_f32 v[94:95], v[14:15], v[86:87] neg_lo:[0,1] neg_hi:[0,1]
	v_mov_b32_e32 v91, v14
	v_pk_add_f32 v[14:15], v[94:95], v[90:91] neg_lo:[0,1] neg_hi:[0,1]
	s_mov_b32 s12, 0x3f317218
	v_add_f32_e32 v15, v99, v15
	v_add_f32_e32 v14, v14, v15
	v_add_f32_e32 v15, v87, v14
	v_mul_f32_e32 v99, v98, v15
	v_mul_f32_e32 v86, v96, v99
	v_fma_f32 v90, v99, v96, -v86
	v_fmac_f32_e32 v90, v99, v97
	v_sub_f32_e32 v87, v87, v15
	v_add_f32_e32 v96, v14, v87
	v_add_f32_e32 v14, v86, v90
	v_sub_f32_e32 v87, v15, v14
	v_pk_add_f32 v[94:95], v[14:15], v[86:87] neg_lo:[0,1] neg_hi:[0,1]
	v_mov_b32_e32 v91, v14
	v_pk_add_f32 v[14:15], v[94:95], v[90:91] neg_lo:[0,1] neg_hi:[0,1]
	v_cmp_neq_f32_e32 vcc, s36, v89
	v_add_f32_e32 v15, v96, v15
	v_add_f32_e32 v14, v14, v15
	v_add_f32_e32 v15, v100, v99
	v_add_f32_e32 v14, v87, v14
	v_sub_f32_e32 v86, v15, v100
	v_mul_f32_e32 v14, v98, v14
	v_sub_f32_e32 v86, v99, v86
	v_add_f32_e32 v86, v86, v14
	v_add_f32_e32 v90, v15, v86
	v_mul_f32_e32 v91, v90, v90
	v_fmamk_f32 v14, v91, 0x3e9b6dac, v172
	v_fmaak_f32 v143, v91, v14, 0x3f2aaada
	v_cvt_f32_i32_e32 v14, v92
	v_sub_f32_e32 v15, v90, v15
	v_sub_f32_e32 v15, v86, v15
	v_ldexp_f32 v92, v15, 1
	v_mul_f32_e32 v15, v90, v91
	v_ldexp_f32 v87, v90, 1
	v_pk_mul_f32 v[90:91], v[14:15], v[142:143]
	s_nop 0
	v_fma_f32 v86, v14, s12, -v90
	v_fmac_f32_e32 v86, 0xb102e308, v14
	v_pk_add_f32 v[14:15], v[90:91], v[86:87]
	v_mov_b32_e32 v94, v90
	v_sub_f32_e32 v87, v15, v87
	v_sub_f32_e32 v87, v91, v87
	v_add_f32_e32 v95, v92, v87
	v_pk_add_f32 v[90:91], v[14:15], v[90:91] neg_lo:[0,1] neg_hi:[0,1]
	v_pk_add_f32 v[96:97], v[14:15], v[94:95]
	v_mov_b32_e32 v87, v14
	v_mov_b32_e32 v91, v97
	v_pk_add_f32 v[98:99], v[86:87], v[90:91] neg_lo:[0,1] neg_hi:[0,1]
	v_pk_add_f32 v[86:87], v[86:87], v[90:91]
	v_mov_b32_e32 v94, v95
	v_pk_add_f32 v[90:91], v[86:87], v[14:15] op_sel:[1,0] op_sel_hi:[0,1] neg_lo:[0,1] neg_hi:[0,1]
	v_pk_add_f32 v[100:101], v[96:97], v[90:91] op_sel_hi:[1,0] neg_lo:[0,1] neg_hi:[0,1]
	v_mov_b32_e32 v96, v97
	v_mov_b32_e32 v97, v87
	v_pk_mov_b32 v[90:91], v[14:15], v[90:91] op_sel:[1,0]
	v_mov_b32_e32 v95, v14
	v_pk_add_f32 v[90:91], v[96:97], v[90:91] neg_lo:[0,1] neg_hi:[0,1]
	v_mov_b32_e32 v100, v98
	v_pk_add_f32 v[14:15], v[94:95], v[90:91] neg_lo:[0,1] neg_hi:[0,1]
	v_mov_b32_e32 v99, v87
	v_pk_add_f32 v[90:91], v[100:101], v[14:15]
	s_mov_b32 s12, 0x33800000
	v_pk_add_f32 v[94:95], v[90:91], v[90:91] op_sel:[0,1] op_sel_hi:[1,0]
	s_nop 0
	v_pk_add_f32 v[86:87], v[86:87], v[94:95] op_sel:[1,0] op_sel_hi:[0,1]
	v_mov_b32_e32 v91, v86
	v_pk_add_f32 v[96:97], v[90:91], v[98:99] neg_lo:[0,1] neg_hi:[0,1]
	v_mov_b32_e32 v15, v94
	v_sub_f32_e32 v87, v90, v96
	v_pk_add_f32 v[14:15], v[14:15], v[96:97] neg_lo:[0,1] neg_hi:[0,1]
	v_sub_f32_e32 v87, v98, v87
	v_add_f32_e32 v14, v14, v87
	v_add_f32_e32 v14, v14, v15
	v_add_f32_e32 v14, v86, v14
	v_cndmask_b32_e32 v14, v185, v14, vcc
	v_cmp_ngt_f32_e32 vcc, -1.0, v89
	s_nop 1
	v_cndmask_b32_e32 v14, v196, v14, vcc
	v_cmp_neq_f32_e32 vcc, -1.0, v89
	s_nop 1
	v_cndmask_b32_e32 v14, v197, v14, vcc
	v_cmp_lt_f32_e64 vcc, |v89|, s12
	s_nop 1
	v_cndmask_b32_e32 v14, v14, v89, vcc

.LBB0_992:
	s_or_b64 exec, exec, s[0:1]
	v_lshlrev_b32_e32 v8, 16, v85
	v_cndmask_b32_e64 v9, 0, v8, s[60:61]
	v_lshlrev_b32_e32 v8, 16, v84
	v_lshlrev_b32_e32 v14, 16, v83
	v_mul_f32_e32 v84, v18, v12
	v_mul_f32_e32 v12, v21, v88
	v_cndmask_b32_e64 v14, 0, v14, s[60:61]
	v_fmac_f32_e32 v12, v20, v93
	v_fmac_f32_e32 v12, v22, v14
	v_mul_f32_e32 v85, v16, v13
	v_mul_f32_e32 v13, 0xbfb8aa3b, v12
	v_exp_f32_e32 v13, v13
	s_waitcnt vmcnt(38)
	v_mul_f32_e32 v87, v17, v11
	s_waitcnt vmcnt(37)
	v_mul_f32_e32 v86, v19, v10
	v_cndmask_b32_e64 v8, 0, v8, s[60:61]
	v_add_f32_e32 v13, 1.0, v13
	v_div_scale_f32 v15, s[0:1], v13, v13, v12
	v_rcp_f32_e32 v83, v15
	v_pk_add_f32 v[84:85], v[84:85], v[86:87]
	s_lshl_b64 s[0:1], s[8:9], 8
	v_pk_fma_f32 v[84:85], v[2:3], v[8:9], v[84:85]
	v_fma_f32 v89, -v15, v83, 1.0
	v_fmac_f32_e32 v83, v89, v83
	v_div_scale_f32 v89, vcc, v12, v13, v12
	v_mul_f32_e32 v90, v89, v83
	v_fma_f32 v91, -v15, v90, v89
	v_fmac_f32_e32 v90, v91, v83
	v_fma_f32 v15, -v15, v90, v89
	v_div_fmas_f32 v15, v15, v83, v90
	v_mul_f32_e32 v83, 0xbfb8aa3b, v85
	v_exp_f32_e32 v87, v83
	v_mul_f32_e32 v83, 0xbfb8aa3b, v84
	v_exp_f32_e32 v86, v83
	v_div_fixup_f32 v15, v15, v13, v12
	v_lshl_add_u64 v[12:13], s[0:1], 0, v[0:1]
	v_lshlrev_b64 v[90:91], 1, v[12:13]
	v_pk_add_f32 v[86:87], v[86:87], 1.0 op_sel_hi:[1,0]
	v_lshl_add_u64 v[92:93], s[78:79], 0, v[90:91]
	v_div_scale_f32 v83, s[0:1], v87, v87, v85
	v_rcp_f32_e32 v89, v83
	s_nop 0
	v_fma_f32 v94, -v83, v89, 1.0
	v_fmac_f32_e32 v89, v94, v89
	v_div_scale_f32 v94, vcc, v85, v87, v85
	v_mul_f32_e32 v95, v94, v89
	v_fma_f32 v96, -v83, v95, v94
	v_fmac_f32_e32 v95, v96, v89
	v_fma_f32 v83, -v83, v95, v94
	v_div_fmas_f32 v83, v83, v89, v95
	v_div_fixup_f32 v85, v83, v87, v85
	v_div_scale_f32 v83, s[0:1], v86, v86, v84
	v_rcp_f32_e32 v87, v83
	s_nop 0
	v_fma_f32 v89, -v83, v87, 1.0
	v_fmac_f32_e32 v87, v89, v87
	v_div_scale_f32 v89, vcc, v84, v86, v84
	v_mul_f32_e32 v94, v89, v87
	v_fma_f32 v95, -v83, v94, v89
	v_fmac_f32_e32 v94, v95, v87
	v_fma_f32 v83, -v83, v94, v89
	v_div_fmas_f32 v83, v83, v87, v94
	v_div_fixup_f32 v84, v83, v86, v84
	v_pk_mul_f32 v[86:87], v[84:85], v[84:85]
	v_cmp_gt_u32_e64 s[98:99], 32, v176
	v_mov_b32_e32 v94, v86
	v_mov_b32_e32 v95, v87
	s_nop 1
	v_permlane32_swap_b32_e32 v94, v86
	v_permlane32_swap_b32_e32 v95, v87
	v_cndmask_b32_e64 v94, v94, v86, s[98:99]
	v_cndmask_b32_e64 v95, v95, v87, s[98:99]
	v_pk_fma_f32 v[86:87], v[84:85], v[84:85], v[94:95]
	v_mov_b32_e32 v94, v86
	v_mov_b32_e32 v95, v87
	s_nop 1
	v_permlane16_swap_b32_e32 v94, v86
	v_permlane16_swap_b32_e32 v95, v87
	v_pk_add_f32 v[86:87], v[86:87], v[94:95]
	s_nop 1
	v_add_f32_dpp v86, v86, v86 row_ror:8 row_mask:0xf bank_mask:0xf
	v_add_f32_dpp v87, v87, v87 row_ror:8 row_mask:0xf bank_mask:0xf
	s_nop 0
	v_add_f32_dpp v86, v86, v86 row_ror:4 row_mask:0xf bank_mask:0xf
	v_add_f32_dpp v87, v87, v87 row_ror:4 row_mask:0xf bank_mask:0xf
	s_nop 0
	v_add_f32_dpp v86, v86, v86 row_ror:2 row_mask:0xf bank_mask:0xf
	v_add_f32_dpp v87, v87, v87 row_ror:2 row_mask:0xf bank_mask:0xf
	s_nop 0
	v_add_f32_dpp v86, v86, v86 row_ror:1 row_mask:0xf bank_mask:0xf
	v_add_f32_dpp v87, v87, v87 row_ror:1 row_mask:0xf bank_mask:0xf
	s_nop 0
	v_pk_add_f32 v[86:87], v[86:87], s[22:23] op_sel_hi:[1,0]
	s_nop 0
	v_mul_f32_e32 v83, 0x4b800000, v87
	v_cmp_gt_f32_e64 s[0:1], s33, v87
	v_cmp_gt_f32_e32 vcc, s33, v86
	s_nop 0
	v_cndmask_b32_e64 v83, v87, v83, s[0:1]
	v_rsq_f32_e32 v83, v83
	v_cvt_pk_bf16_f32 v15, v15, s0
	v_mul_f32_e32 v87, 0x45800000, v83
	v_cndmask_b32_e64 v83, v83, v87, s[0:1]
	v_mul_f32_e32 v83, v85, v83
	v_mul_f32_e32 v83, 0x3e000000, v83
	v_cvt_pk_bf16_f32 v83, v83, s0
	global_store_short v[92:93], v83, off
	v_mul_f32_e32 v83, 0x4b800000, v86
	v_cndmask_b32_e32 v83, v86, v83, vcc
	v_rsq_f32_e32 v83, v83
	s_nop 0
	v_mul_f32_e32 v85, 0x45800000, v83
	v_cndmask_b32_e32 v83, v83, v85, vcc
	v_mul_f32_e32 v83, v84, v83
	v_cvt_pk_bf16_f32 v83, v83, s0
	v_lshl_add_u64 v[84:85], s[80:81], 0, v[90:91]
	global_store_short v[84:85], v83, off
	v_lshl_add_u64 v[84:85], s[82:83], 0, v[90:91]
	global_store_short v[84:85], v15, off
	s_and_saveexec_b64 s[0:1], s[38:39]
	s_cbranch_execz .LBB0_996
	s_waitcnt vmcnt(39)
	v_lshlrev_b32_e32 v15, 16, v82
	v_mul_f32_e32 v15, 0xbfb8aa3b, v15
	v_exp_f32_e32 v15, v15
	v_mad_i64_i32 v[12:13], s[8:9], s8, v199, v[12:13]
	s_waitcnt vmcnt(38)
	v_lshlrev_b32_e32 v81, 16, v81
	v_add_f32_e32 v15, 1.0, v15
	v_div_scale_f32 v82, s[10:11], v15, v15, 1.0
	v_rcp_f32_e32 v83, v82
	v_div_scale_f32 v84, vcc, 1.0, v15, 1.0
	s_mov_b32 s8, 0x41a00000
	v_fma_f32 v85, -v82, v83, 1.0
	v_fmac_f32_e32 v83, v85, v83
	v_mul_f32_e32 v85, v84, v83
	v_fma_f32 v86, -v82, v85, v84
	v_fmac_f32_e32 v85, v86, v83
	v_fma_f32 v82, -v82, v85, v84
	v_div_fmas_f32 v82, v82, v83, v85
	v_div_fixup_f32 v15, v82, v15, 1.0
	v_lshl_add_u64 v[82:83], v[12:13], 2, s[84:85]
	global_store_dword v[82:83], v15, off
	v_add_f32_e32 v15, v24, v81
	v_cmp_nlt_f32_e32 vcc, s8, v15
	s_and_saveexec_b64 s[8:9], vcc
	s_cbranch_execz .LBB0_995
	v_mul_f32_e32 v15, 0x3fb8aa3b, v15
	v_exp_f32_e32 v15, v15
	s_mov_b32 s10, 0x3f2aaaab
	v_add_f32_e32 v81, 1.0, v15
	v_frexp_mant_f32_e32 v85, v81
	v_cvt_f64_f32_e32 v[82:83], v81
	v_add_f32_e32 v84, -1.0, v81
	v_frexp_exp_i32_f64_e32 v82, v[82:83]
	v_cmp_gt_f32_e32 vcc, s10, v85
	v_sub_f32_e32 v86, v84, v81
	v_sub_f32_e32 v84, v15, v84
	v_subbrev_co_u32_e32 v89, vcc, 0, v82, vcc
	v_add_f32_e32 v86, 1.0, v86
	v_sub_u32_e32 v82, 0, v89
	v_add_f32_e32 v84, v84, v86
	v_ldexp_f32 v81, v81, v82
	v_ldexp_f32 v82, v84, v82
	v_add_f32_e32 v84, -1.0, v81
	v_add_f32_e32 v83, 1.0, v84
	v_sub_f32_e32 v83, v81, v83
	v_add_f32_e32 v85, v82, v83
	v_add_f32_e32 v83, 1.0, v81
	v_add_f32_e32 v86, -1.0, v83
	v_sub_f32_e32 v81, v81, v86
	v_add_f32_e32 v81, v82, v81
	v_add_f32_e32 v92, v83, v81
	v_rcp_f32_e32 v93, v92
	v_sub_f32_e32 v82, v92, v83
	v_add_f32_e32 v83, v84, v85
	v_sub_f32_e32 v81, v81, v82
	v_mul_f32_e32 v95, v83, v93
	v_sub_f32_e32 v82, v83, v84
	v_mul_f32_e32 v84, v92, v95
	v_fma_f32 v86, v95, v92, -v84
	v_fmac_f32_e32 v86, v95, v81
	v_sub_f32_e32 v94, v85, v82
	v_add_f32_e32 v82, v84, v86
	v_sub_f32_e32 v85, v83, v82
	v_pk_add_f32 v[90:91], v[82:83], v[84:85] neg_lo:[0,1] neg_hi:[0,1]
	v_mov_b32_e32 v87, v82
	v_pk_add_f32 v[82:83], v[90:91], v[86:87] neg_lo:[0,1] neg_hi:[0,1]
	s_mov_b32 s10, 0x3f317218
	v_add_f32_e32 v83, v94, v83
	v_add_f32_e32 v82, v82, v83
	v_add_f32_e32 v83, v85, v82
	v_mul_f32_e32 v94, v93, v83
	v_mul_f32_e32 v84, v92, v94
	v_fma_f32 v86, v94, v92, -v84
	v_fmac_f32_e32 v86, v94, v81
	v_sub_f32_e32 v81, v85, v83
	v_add_f32_e32 v81, v82, v81
	v_add_f32_e32 v82, v84, v86
	v_sub_f32_e32 v85, v83, v82
	v_pk_add_f32 v[90:91], v[82:83], v[84:85] neg_lo:[0,1] neg_hi:[0,1]
	v_mov_b32_e32 v87, v82
	v_pk_add_f32 v[82:83], v[90:91], v[86:87] neg_lo:[0,1] neg_hi:[0,1]
	v_cmp_neq_f32_e32 vcc, s36, v15
	v_add_f32_e32 v81, v81, v83
	v_add_f32_e32 v81, v82, v81
	v_add_f32_e32 v83, v95, v94
	v_add_f32_e32 v81, v85, v81
	v_sub_f32_e32 v82, v83, v95
	v_mul_f32_e32 v81, v93, v81
	v_sub_f32_e32 v82, v94, v82
	v_add_f32_e32 v81, v82, v81
	v_add_f32_e32 v84, v83, v81
	v_mul_f32_e32 v86, v84, v84
	v_fmamk_f32 v82, v86, 0x3e9b6dac, v172
	v_fmaak_f32 v143, v86, v82, 0x3f2aaada
	v_cvt_f32_i32_e32 v82, v89
	v_sub_f32_e32 v83, v84, v83
	v_sub_f32_e32 v81, v81, v83
	v_mul_f32_e32 v83, v84, v86
	v_pk_mul_f32 v[86:87], v[82:83], v[142:143]
	v_ldexp_f32 v85, v84, 1
	v_fma_f32 v84, v82, s10, -v86
	v_fmac_f32_e32 v84, 0xb102e308, v82
	v_pk_add_f32 v[82:83], v[86:87], v[84:85]
	v_ldexp_f32 v81, v81, 1
	v_sub_f32_e32 v85, v83, v85
	v_sub_f32_e32 v85, v87, v85
	v_add_f32_e32 v91, v81, v85
	v_mov_b32_e32 v90, v86
	v_pk_add_f32 v[86:87], v[82:83], v[86:87] neg_lo:[0,1] neg_hi:[0,1]
	v_pk_add_f32 v[92:93], v[82:83], v[90:91]
	v_mov_b32_e32 v85, v82
	v_mov_b32_e32 v87, v93
	v_pk_add_f32 v[94:95], v[84:85], v[86:87] neg_lo:[0,1] neg_hi:[0,1]
	v_pk_add_f32 v[84:85], v[84:85], v[86:87]
	v_mov_b32_e32 v90, v91
	v_pk_add_f32 v[86:87], v[84:85], v[82:83] op_sel:[1,0] op_sel_hi:[0,1] neg_lo:[0,1] neg_hi:[0,1]
	v_pk_add_f32 v[96:97], v[92:93], v[86:87] op_sel_hi:[1,0] neg_lo:[0,1] neg_hi:[0,1]
	v_mov_b32_e32 v92, v93
	v_mov_b32_e32 v93, v85
	v_pk_mov_b32 v[86:87], v[82:83], v[86:87] op_sel:[1,0]
	v_mov_b32_e32 v91, v82
	v_pk_add_f32 v[86:87], v[92:93], v[86:87] neg_lo:[0,1] neg_hi:[0,1]
	v_mov_b32_e32 v96, v94
	v_pk_add_f32 v[82:83], v[90:91], v[86:87] neg_lo:[0,1] neg_hi:[0,1]
	v_mov_b32_e32 v95, v85
	v_pk_add_f32 v[86:87], v[96:97], v[82:83]
	s_mov_b32 s10, 0x33800000
	v_pk_add_f32 v[90:91], v[86:87], v[86:87] op_sel:[0,1] op_sel_hi:[1,0]
	s_nop 0
	v_pk_add_f32 v[84:85], v[84:85], v[90:91] op_sel:[1,0] op_sel_hi:[0,1]
	v_mov_b32_e32 v87, v84
	v_pk_add_f32 v[92:93], v[86:87], v[94:95] neg_lo:[0,1] neg_hi:[0,1]
	v_mov_b32_e32 v83, v90
	v_sub_f32_e32 v81, v86, v92
	v_pk_add_f32 v[82:83], v[82:83], v[92:93] neg_lo:[0,1] neg_hi:[0,1]
	v_sub_f32_e32 v81, v94, v81
	v_add_f32_e32 v81, v82, v81
	v_add_f32_e32 v81, v81, v83
	v_add_f32_e32 v81, v84, v81
	v_cndmask_b32_e32 v81, v185, v81, vcc
	v_cmp_ngt_f32_e32 vcc, -1.0, v15
	s_nop 1
	v_cndmask_b32_e32 v81, v196, v81, vcc
	v_cmp_neq_f32_e32 vcc, -1.0, v15
	s_nop 1
	v_cndmask_b32_e32 v81, v197, v81, vcc
	v_cmp_lt_f32_e64 vcc, |v15|, s10
	s_nop 1
	v_cndmask_b32_e32 v15, v81, v15, vcc

.LBB0_996:
	s_or_b64 exec, exec, s[0:1]
	v_lshlrev_b32_e32 v12, 16, v80
	v_lshlrev_b32_e32 v15, 16, v78
	v_mul_f32_e32 v80, v18, v10
	v_mul_f32_e32 v10, v21, v14
	v_cndmask_b32_e64 v78, 0, v15, s[58:59]
	v_fmac_f32_e32 v10, v20, v88
	v_fmac_f32_e32 v10, v22, v78
	s_waitcnt vmcnt(38)
	v_mul_f32_e32 v81, v16, v11
	v_mul_f32_e32 v11, 0xbfb8aa3b, v10
	v_exp_f32_e32 v11, v11
	v_cndmask_b32_e64 v13, 0, v12, s[58:59]
	v_lshlrev_b32_e32 v12, 16, v79
	v_mul_f32_e32 v83, v17, v9
	v_add_f32_e32 v11, 1.0, v11
	v_div_scale_f32 v15, s[0:1], v11, v11, v10
	v_rcp_f32_e32 v79, v15
	v_mul_f32_e32 v82, v19, v8
	v_cndmask_b32_e64 v12, 0, v12, s[58:59]
	v_pk_add_f32 v[80:81], v[80:81], v[82:83]
	v_fma_f32 v84, -v15, v79, 1.0
	v_fmac_f32_e32 v79, v84, v79
	v_div_scale_f32 v84, vcc, v10, v11, v10
	v_mul_f32_e32 v85, v84, v79
	v_fma_f32 v86, -v15, v85, v84
	v_fmac_f32_e32 v85, v86, v79
	v_fma_f32 v15, -v15, v85, v84
	v_pk_fma_f32 v[80:81], v[2:3], v[12:13], v[80:81]
	v_div_fmas_f32 v15, v15, v79, v85
	v_mul_f32_e32 v79, 0xbfb8aa3b, v81
	v_exp_f32_e32 v83, v79
	v_mul_f32_e32 v79, 0xbfb8aa3b, v80
	v_exp_f32_e32 v82, v79
	s_lshl_b64 s[0:1], s[6:7], 8
	v_div_fixup_f32 v15, v15, v11, v10
	v_lshl_add_u64 v[10:11], s[0:1], 0, v[0:1]
	v_pk_add_f32 v[82:83], v[82:83], 1.0 op_sel_hi:[1,0]
	v_lshlrev_b64 v[84:85], 1, v[10:11]
	v_div_scale_f32 v79, s[0:1], v83, v83, v81
	v_rcp_f32_e32 v88, v79
	v_lshl_add_u64 v[86:87], s[78:79], 0, v[84:85]
	v_fma_f32 v89, -v79, v88, 1.0
	v_fmac_f32_e32 v88, v89, v88
	v_div_scale_f32 v89, vcc, v81, v83, v81
	v_mul_f32_e32 v90, v89, v88
	v_fma_f32 v91, -v79, v90, v89
	v_fmac_f32_e32 v90, v91, v88
	v_fma_f32 v79, -v79, v90, v89
	v_div_fmas_f32 v79, v79, v88, v90
	v_div_fixup_f32 v81, v79, v83, v81
	v_div_scale_f32 v79, s[0:1], v82, v82, v80
	v_rcp_f32_e32 v83, v79
	s_nop 0
	v_fma_f32 v88, -v79, v83, 1.0
	v_fmac_f32_e32 v83, v88, v83
	v_div_scale_f32 v88, vcc, v80, v82, v80
	v_mul_f32_e32 v89, v88, v83
	v_fma_f32 v90, -v79, v89, v88
	v_fmac_f32_e32 v89, v90, v83
	v_fma_f32 v79, -v79, v89, v88
	v_div_fmas_f32 v79, v79, v83, v89
	v_div_fixup_f32 v80, v79, v82, v80
	v_pk_mul_f32 v[82:83], v[80:81], v[80:81]
	v_cmp_gt_u32_e64 s[98:99], 32, v176
	v_mov_b32_e32 v88, v82
	v_mov_b32_e32 v89, v83
	s_nop 1
	v_permlane32_swap_b32_e32 v88, v82
	v_permlane32_swap_b32_e32 v89, v83
	v_cndmask_b32_e64 v88, v88, v82, s[98:99]
	v_cndmask_b32_e64 v89, v89, v83, s[98:99]
	v_pk_fma_f32 v[82:83], v[80:81], v[80:81], v[88:89]
	v_mov_b32_e32 v88, v82
	v_mov_b32_e32 v89, v83
	s_nop 1
	v_permlane16_swap_b32_e32 v88, v82
	v_permlane16_swap_b32_e32 v89, v83
	v_pk_add_f32 v[82:83], v[82:83], v[88:89]
	s_nop 1
	v_add_f32_dpp v82, v82, v82 row_ror:8 row_mask:0xf bank_mask:0xf
	v_add_f32_dpp v83, v83, v83 row_ror:8 row_mask:0xf bank_mask:0xf
	s_nop 0
	v_add_f32_dpp v82, v82, v82 row_ror:4 row_mask:0xf bank_mask:0xf
	v_add_f32_dpp v83, v83, v83 row_ror:4 row_mask:0xf bank_mask:0xf
	s_nop 0
	v_add_f32_dpp v82, v82, v82 row_ror:2 row_mask:0xf bank_mask:0xf
	v_add_f32_dpp v83, v83, v83 row_ror:2 row_mask:0xf bank_mask:0xf
	s_nop 0
	v_add_f32_dpp v82, v82, v82 row_ror:1 row_mask:0xf bank_mask:0xf
	v_add_f32_dpp v83, v83, v83 row_ror:1 row_mask:0xf bank_mask:0xf
	s_nop 0
	v_pk_add_f32 v[82:83], v[82:83], s[22:23] op_sel_hi:[1,0]
	s_nop 0
	v_mul_f32_e32 v79, 0x4b800000, v83
	v_cmp_gt_f32_e64 s[0:1], s33, v83
	v_cmp_gt_f32_e32 vcc, s33, v82
	s_nop 0
	v_cndmask_b32_e64 v79, v83, v79, s[0:1]
	v_rsq_f32_e32 v79, v79
	v_cvt_pk_bf16_f32 v15, v15, s0
	v_mul_f32_e32 v83, 0x45800000, v79
	v_cndmask_b32_e64 v79, v79, v83, s[0:1]
	v_mul_f32_e32 v79, v81, v79
	v_mul_f32_e32 v79, 0x3e000000, v79
	v_cvt_pk_bf16_f32 v79, v79, s0
	global_store_short v[86:87], v79, off
	v_mul_f32_e32 v79, 0x4b800000, v82
	v_cndmask_b32_e32 v79, v82, v79, vcc
	v_rsq_f32_e32 v79, v79
	s_nop 0
	v_mul_f32_e32 v81, 0x45800000, v79
	v_cndmask_b32_e32 v79, v79, v81, vcc
	v_mul_f32_e32 v79, v80, v79
	v_cvt_pk_bf16_f32 v79, v79, s0
	v_lshl_add_u64 v[80:81], s[80:81], 0, v[84:85]
	global_store_short v[80:81], v79, off
	v_lshl_add_u64 v[80:81], s[82:83], 0, v[84:85]
	global_store_short v[80:81], v15, off
	s_and_saveexec_b64 s[0:1], s[38:39]
	s_cbranch_execz .LBB0_1000
	s_waitcnt vmcnt(40)
	v_lshlrev_b32_e32 v15, 16, v77
	v_mul_f32_e32 v15, 0xbfb8aa3b, v15
	v_exp_f32_e32 v15, v15
	s_waitcnt vmcnt(39)
	v_lshlrev_b32_e32 v80, 16, v76
	v_mad_i64_i32 v[10:11], s[6:7], s6, v199, v[10:11]
	v_add_f32_e32 v15, 1.0, v15
	v_div_scale_f32 v77, s[8:9], v15, v15, 1.0
	v_rcp_f32_e32 v79, v77
	v_div_scale_f32 v76, vcc, 1.0, v15, 1.0
	s_mov_b32 s6, 0x41a00000
	v_fma_f32 v81, -v77, v79, 1.0
	v_fmac_f32_e32 v79, v81, v79
	v_mul_f32_e32 v81, v76, v79
	v_fma_f32 v82, -v77, v81, v76
	v_fmac_f32_e32 v81, v82, v79
	v_fma_f32 v76, -v77, v81, v76
	v_div_fmas_f32 v76, v76, v79, v81
	v_div_fixup_f32 v15, v76, v15, 1.0
	v_lshl_add_u64 v[76:77], v[10:11], 2, s[84:85]
	global_store_dword v[76:77], v15, off
	v_add_f32_e32 v15, v24, v80
	v_cmp_nlt_f32_e32 vcc, s6, v15
	s_and_saveexec_b64 s[6:7], vcc
	s_cbranch_execz .LBB0_999
	v_mul_f32_e32 v15, 0x3fb8aa3b, v15
	v_exp_f32_e32 v15, v15
	s_mov_b32 s8, 0x3f2aaaab
	v_add_f32_e32 v79, 1.0, v15
	v_frexp_mant_f32_e32 v81, v79
	v_cvt_f64_f32_e32 v[76:77], v79
	v_frexp_exp_i32_f64_e32 v76, v[76:77]
	v_cmp_gt_f32_e32 vcc, s8, v81
	v_add_f32_e32 v80, -1.0, v79
	v_sub_f32_e32 v82, v80, v79
	v_subbrev_co_u32_e32 v86, vcc, 0, v76, vcc
	v_sub_u32_e32 v76, 0, v86
	v_sub_f32_e32 v80, v15, v80
	v_add_f32_e32 v82, 1.0, v82
	v_ldexp_f32 v77, v79, v76
	v_add_f32_e32 v80, v80, v82
	v_add_f32_e32 v79, -1.0, v77
	v_add_f32_e32 v81, 1.0, v77
	v_ldexp_f32 v76, v80, v76
	v_add_f32_e32 v80, 1.0, v79
	v_add_f32_e32 v82, -1.0, v81
	v_sub_f32_e32 v80, v77, v80
	v_sub_f32_e32 v77, v77, v82
	v_add_f32_e32 v80, v76, v80
	v_add_f32_e32 v76, v76, v77
	v_add_f32_e32 v87, v81, v76
	v_rcp_f32_e32 v89, v87
	v_sub_f32_e32 v77, v87, v81
	v_sub_f32_e32 v88, v76, v77
	v_add_f32_e32 v77, v79, v80
	v_sub_f32_e32 v76, v77, v79
	v_mul_f32_e32 v90, v77, v89
	v_sub_f32_e32 v79, v80, v76
	v_mul_f32_e32 v80, v87, v90
	v_fma_f32 v82, v90, v87, -v80
	v_fmac_f32_e32 v82, v90, v88
	v_add_f32_e32 v76, v80, v82
	v_sub_f32_e32 v81, v77, v76
	v_pk_add_f32 v[84:85], v[76:77], v[80:81] neg_lo:[0,1] neg_hi:[0,1]
	v_mov_b32_e32 v83, v76
	v_pk_add_f32 v[76:77], v[84:85], v[82:83] neg_lo:[0,1] neg_hi:[0,1]
	s_mov_b32 s8, 0x3f317218
	v_add_f32_e32 v77, v79, v77
	v_add_f32_e32 v76, v76, v77
	v_add_f32_e32 v77, v81, v76
	v_mul_f32_e32 v79, v89, v77
	v_mul_f32_e32 v80, v87, v79
	v_fma_f32 v82, v79, v87, -v80
	v_fmac_f32_e32 v82, v79, v88
	v_sub_f32_e32 v81, v81, v77
	v_add_f32_e32 v87, v76, v81
	v_add_f32_e32 v76, v80, v82
	v_sub_f32_e32 v81, v77, v76
	v_pk_add_f32 v[84:85], v[76:77], v[80:81] neg_lo:[0,1] neg_hi:[0,1]
	v_mov_b32_e32 v83, v76
	v_pk_add_f32 v[76:77], v[84:85], v[82:83] neg_lo:[0,1] neg_hi:[0,1]
	v_cmp_neq_f32_e32 vcc, s36, v15
	v_add_f32_e32 v77, v87, v77
	v_add_f32_e32 v76, v76, v77
	v_add_f32_e32 v77, v90, v79
	v_add_f32_e32 v76, v81, v76
	v_sub_f32_e32 v80, v77, v90
	v_mul_f32_e32 v76, v89, v76
	v_sub_f32_e32 v79, v79, v80
	v_add_f32_e32 v79, v79, v76
	v_add_f32_e32 v80, v77, v79
	v_mul_f32_e32 v82, v80, v80
	v_fmamk_f32 v76, v82, 0x3e9b6dac, v172
	v_fmaak_f32 v143, v82, v76, 0x3f2aaada
	v_cvt_f32_i32_e32 v76, v86
	v_sub_f32_e32 v77, v80, v77
	v_sub_f32_e32 v77, v79, v77
	v_ldexp_f32 v79, v77, 1
	v_mul_f32_e32 v77, v80, v82
	v_pk_mul_f32 v[82:83], v[76:77], v[142:143]
	v_ldexp_f32 v81, v80, 1
	v_fma_f32 v80, v76, s8, -v82
	v_fmac_f32_e32 v80, 0xb102e308, v76
	v_pk_add_f32 v[76:77], v[82:83], v[80:81]
	v_mov_b32_e32 v84, v82
	v_sub_f32_e32 v81, v77, v81
	v_sub_f32_e32 v81, v83, v81
	v_add_f32_e32 v85, v79, v81
	v_pk_add_f32 v[82:83], v[76:77], v[82:83] neg_lo:[0,1] neg_hi:[0,1]
	v_pk_add_f32 v[86:87], v[76:77], v[84:85]
	v_mov_b32_e32 v81, v76
	v_mov_b32_e32 v83, v87
	v_pk_add_f32 v[88:89], v[80:81], v[82:83] neg_lo:[0,1] neg_hi:[0,1]
	v_pk_add_f32 v[80:81], v[80:81], v[82:83]
	v_mov_b32_e32 v84, v85
	v_pk_add_f32 v[82:83], v[80:81], v[76:77] op_sel:[1,0] op_sel_hi:[0,1] neg_lo:[0,1] neg_hi:[0,1]
	v_pk_add_f32 v[90:91], v[86:87], v[82:83] op_sel_hi:[1,0] neg_lo:[0,1] neg_hi:[0,1]
	v_mov_b32_e32 v86, v87
	v_mov_b32_e32 v87, v81
	v_pk_mov_b32 v[82:83], v[76:77], v[82:83] op_sel:[1,0]
	v_mov_b32_e32 v85, v76
	v_pk_add_f32 v[82:83], v[86:87], v[82:83] neg_lo:[0,1] neg_hi:[0,1]
	v_mov_b32_e32 v90, v88
	v_pk_add_f32 v[76:77], v[84:85], v[82:83] neg_lo:[0,1] neg_hi:[0,1]
	v_mov_b32_e32 v89, v81
	v_pk_add_f32 v[82:83], v[90:91], v[76:77]
	s_mov_b32 s8, 0x33800000
	v_pk_add_f32 v[84:85], v[82:83], v[82:83] op_sel:[0,1] op_sel_hi:[1,0]
	s_nop 0
	v_pk_add_f32 v[80:81], v[80:81], v[84:85] op_sel:[1,0] op_sel_hi:[0,1]
	v_mov_b32_e32 v83, v80
	v_pk_add_f32 v[86:87], v[82:83], v[88:89] neg_lo:[0,1] neg_hi:[0,1]
	v_mov_b32_e32 v77, v84
	v_sub_f32_e32 v79, v82, v86
	v_pk_add_f32 v[76:77], v[76:77], v[86:87] neg_lo:[0,1] neg_hi:[0,1]
	v_sub_f32_e32 v79, v88, v79
	v_add_f32_e32 v76, v76, v79
	v_add_f32_e32 v76, v76, v77
	v_add_f32_e32 v76, v80, v76
	v_cndmask_b32_e32 v76, v185, v76, vcc
	v_cmp_ngt_f32_e32 vcc, -1.0, v15
	s_nop 1
	v_cndmask_b32_e32 v76, v196, v76, vcc
	v_cmp_neq_f32_e32 vcc, -1.0, v15
	s_nop 1
	v_cndmask_b32_e32 v76, v197, v76, vcc
	v_cmp_lt_f32_e64 vcc, |v15|, s8
	s_nop 1
	v_cndmask_b32_e32 v15, v76, v15, vcc

.LBB0_1004:
	s_or_b64 exec, exec, s[0:1]
	v_lshlrev_b32_e32 v8, 16, v69
	v_cndmask_b32_e64 v9, 0, v8, s[54:55]
	v_lshlrev_b32_e32 v8, 16, v68
	v_lshlrev_b32_e32 v14, 16, v70
	v_mul_f32_e32 v68, v18, v12
	v_mul_f32_e32 v12, v21, v74
	v_cndmask_b32_e64 v15, 0, v14, s[54:55]
	v_fmac_f32_e32 v12, v20, v78
	v_fmac_f32_e32 v12, v22, v15
	v_mul_f32_e32 v69, v16, v13
	v_mul_f32_e32 v13, 0xbfb8aa3b, v12
	v_exp_f32_e32 v13, v13
	s_waitcnt vmcnt(40)
	v_mul_f32_e32 v71, v17, v11
	v_mul_f32_e32 v70, v19, v10
	v_cndmask_b32_e64 v8, 0, v8, s[54:55]
	v_add_f32_e32 v13, 1.0, v13
	v_div_scale_f32 v14, s[0:1], v13, v13, v12
	v_rcp_f32_e32 v72, v14
	v_pk_add_f32 v[68:69], v[68:69], v[70:71]
	s_lshl_b64 s[0:1], s[92:93], 8
	v_pk_fma_f32 v[68:69], v[2:3], v[8:9], v[68:69]
	v_fma_f32 v73, -v14, v72, 1.0
	v_mul_f32_e32 v70, 0xbfb8aa3b, v69
	v_fmac_f32_e32 v72, v73, v72
	v_div_scale_f32 v73, vcc, v12, v13, v12
	v_exp_f32_e32 v71, v70
	v_mul_f32_e32 v70, 0xbfb8aa3b, v68
	v_mul_f32_e32 v75, v73, v72
	v_exp_f32_e32 v70, v70
	v_fma_f32 v76, -v14, v75, v73
	v_fmac_f32_e32 v75, v76, v72
	v_fma_f32 v14, -v14, v75, v73
	v_div_fmas_f32 v14, v14, v72, v75
	v_pk_add_f32 v[70:71], v[70:71], 1.0 op_sel_hi:[1,0]
	v_div_fixup_f32 v14, v14, v13, v12
	v_lshl_add_u64 v[12:13], s[0:1], 0, v[0:1]
	v_div_scale_f32 v75, s[0:1], v71, v71, v69
	v_rcp_f32_e32 v78, v75
	v_lshlrev_b64 v[72:73], 1, v[12:13]
	v_lshl_add_u64 v[76:77], s[78:79], 0, v[72:73]
	v_fma_f32 v79, -v75, v78, 1.0
	v_fmac_f32_e32 v78, v79, v78
	v_div_scale_f32 v79, vcc, v69, v71, v69
	v_mul_f32_e32 v80, v79, v78
	v_fma_f32 v81, -v75, v80, v79
	v_fmac_f32_e32 v80, v81, v78
	v_fma_f32 v75, -v75, v80, v79
	v_div_fmas_f32 v75, v75, v78, v80
	v_div_fixup_f32 v69, v75, v71, v69
	v_div_scale_f32 v71, s[0:1], v70, v70, v68
	v_rcp_f32_e32 v75, v71
	s_nop 0
	v_fma_f32 v78, -v71, v75, 1.0
	v_fmac_f32_e32 v75, v78, v75
	v_div_scale_f32 v78, vcc, v68, v70, v68
	v_mul_f32_e32 v79, v78, v75
	v_fma_f32 v80, -v71, v79, v78
	v_fmac_f32_e32 v79, v80, v75
	v_fma_f32 v71, -v71, v79, v78
	v_div_fmas_f32 v71, v71, v75, v79
	v_div_fixup_f32 v68, v71, v70, v68
	v_pk_mul_f32 v[70:71], v[68:69], v[68:69]
	v_cmp_gt_u32_e64 s[98:99], 32, v176
	v_mov_b32_e32 v78, v70
	v_mov_b32_e32 v79, v71
	s_nop 1
	v_permlane32_swap_b32_e32 v78, v70
	v_permlane32_swap_b32_e32 v79, v71
	v_cndmask_b32_e64 v78, v78, v70, s[98:99]
	v_cndmask_b32_e64 v79, v79, v71, s[98:99]
	v_pk_fma_f32 v[70:71], v[68:69], v[68:69], v[78:79]
	v_mov_b32_e32 v78, v70
	v_mov_b32_e32 v79, v71
	s_nop 1
	v_permlane16_swap_b32_e32 v78, v70
	v_permlane16_swap_b32_e32 v79, v71
	v_pk_add_f32 v[70:71], v[70:71], v[78:79]
	s_nop 1
	v_add_f32_dpp v70, v70, v70 row_ror:8 row_mask:0xf bank_mask:0xf
	v_add_f32_dpp v71, v71, v71 row_ror:8 row_mask:0xf bank_mask:0xf
	s_nop 0
	v_add_f32_dpp v70, v70, v70 row_ror:4 row_mask:0xf bank_mask:0xf
	v_add_f32_dpp v71, v71, v71 row_ror:4 row_mask:0xf bank_mask:0xf
	s_nop 0
	v_add_f32_dpp v70, v70, v70 row_ror:2 row_mask:0xf bank_mask:0xf
	v_add_f32_dpp v71, v71, v71 row_ror:2 row_mask:0xf bank_mask:0xf
	s_nop 0
	v_add_f32_dpp v70, v70, v70 row_ror:1 row_mask:0xf bank_mask:0xf
	v_add_f32_dpp v71, v71, v71 row_ror:1 row_mask:0xf bank_mask:0xf
	s_nop 0
	v_pk_add_f32 v[70:71], v[70:71], s[22:23] op_sel_hi:[1,0]
	s_nop 0
	v_mul_f32_e32 v75, 0x4b800000, v71
	v_cmp_gt_f32_e64 s[0:1], s33, v71
	v_cmp_gt_f32_e32 vcc, s33, v70
	s_nop 0
	v_cndmask_b32_e64 v71, v71, v75, s[0:1]
	v_rsq_f32_e32 v71, v71
	v_cvt_pk_bf16_f32 v14, v14, s0
	v_mul_f32_e32 v75, 0x45800000, v71
	v_cndmask_b32_e64 v71, v71, v75, s[0:1]
	v_mul_f32_e32 v69, v69, v71
	v_mul_f32_e32 v69, 0x3e000000, v69
	v_cvt_pk_bf16_f32 v69, v69, s0
	global_store_short v[76:77], v69, off
	v_mul_f32_e32 v69, 0x4b800000, v70
	v_cndmask_b32_e32 v69, v70, v69, vcc
	v_rsq_f32_e32 v69, v69
	s_nop 0
	v_mul_f32_e32 v70, 0x45800000, v69
	v_cndmask_b32_e32 v69, v69, v70, vcc
	v_mul_f32_e32 v68, v68, v69
	v_cvt_pk_bf16_f32 v70, v68, s0
	v_lshl_add_u64 v[68:69], s[80:81], 0, v[72:73]
	global_store_short v[68:69], v70, off
	v_lshl_add_u64 v[68:69], s[82:83], 0, v[72:73]
	global_store_short v[68:69], v14, off
	s_and_saveexec_b64 s[0:1], s[38:39]
	s_cbranch_execz .LBB0_1008
	s_waitcnt vmcnt(42)
	v_lshlrev_b32_e32 v14, 16, v67
	v_mul_f32_e32 v14, 0xbfb8aa3b, v14
	v_exp_f32_e32 v14, v14
	s_waitcnt vmcnt(41)
	v_lshlrev_b32_e32 v69, 16, v66
	v_mad_i64_i32 v[12:13], s[4:5], s92, v199, v[12:13]
	v_add_f32_e32 v14, 1.0, v14
	v_div_scale_f32 v67, s[4:5], v14, v14, 1.0
	v_rcp_f32_e32 v68, v67
	v_div_scale_f32 v66, vcc, 1.0, v14, 1.0
	s_mov_b32 s4, 0x41a00000
	v_fma_f32 v70, -v67, v68, 1.0
	v_fmac_f32_e32 v68, v70, v68
	v_mul_f32_e32 v70, v66, v68
	v_fma_f32 v71, -v67, v70, v66
	v_fmac_f32_e32 v70, v71, v68
	v_fma_f32 v66, -v67, v70, v66
	v_div_fmas_f32 v66, v66, v68, v70
	v_div_fixup_f32 v14, v66, v14, 1.0
	v_lshl_add_u64 v[66:67], v[12:13], 2, s[84:85]
	global_store_dword v[66:67], v14, off
	v_add_f32_e32 v14, v24, v69
	v_cmp_nlt_f32_e32 vcc, s4, v14
	s_and_saveexec_b64 s[4:5], vcc
	s_cbranch_execz .LBB0_1007
	v_mul_f32_e32 v14, 0x3fb8aa3b, v14
	v_exp_f32_e32 v14, v14
	s_mov_b32 s6, 0x3f2aaaab
	v_add_f32_e32 v68, 1.0, v14
	v_frexp_mant_f32_e32 v70, v68
	v_cvt_f64_f32_e32 v[66:67], v68
	v_frexp_exp_i32_f64_e32 v66, v[66:67]
	v_cmp_gt_f32_e32 vcc, s6, v70
	v_add_f32_e32 v69, -1.0, v68
	v_sub_f32_e32 v71, v69, v68
	v_subbrev_co_u32_e32 v75, vcc, 0, v66, vcc
	v_sub_u32_e32 v66, 0, v75
	v_sub_f32_e32 v69, v14, v69
	v_add_f32_e32 v71, 1.0, v71
	v_ldexp_f32 v67, v68, v66
	v_add_f32_e32 v69, v69, v71
	v_add_f32_e32 v68, -1.0, v67
	v_add_f32_e32 v70, 1.0, v67
	v_ldexp_f32 v66, v69, v66
	v_add_f32_e32 v69, 1.0, v68
	v_add_f32_e32 v71, -1.0, v70
	v_sub_f32_e32 v69, v67, v69
	v_sub_f32_e32 v67, v67, v71
	v_add_f32_e32 v69, v66, v69
	v_add_f32_e32 v66, v66, v67
	v_add_f32_e32 v76, v70, v66
	v_rcp_f32_e32 v78, v76
	v_sub_f32_e32 v67, v76, v70
	v_sub_f32_e32 v77, v66, v67
	v_add_f32_e32 v67, v68, v69
	v_mul_f32_e32 v80, v67, v78
	v_sub_f32_e32 v66, v67, v68
	v_mul_f32_e32 v68, v76, v80
	v_fma_f32 v70, v80, v76, -v68
	v_fmac_f32_e32 v70, v80, v77
	v_sub_f32_e32 v79, v69, v66
	v_add_f32_e32 v66, v68, v70
	v_sub_f32_e32 v69, v67, v66
	v_pk_add_f32 v[72:73], v[66:67], v[68:69] neg_lo:[0,1] neg_hi:[0,1]
	v_mov_b32_e32 v71, v66
	v_pk_add_f32 v[66:67], v[72:73], v[70:71] neg_lo:[0,1] neg_hi:[0,1]
	s_mov_b32 s6, 0x3f317218
	v_add_f32_e32 v67, v79, v67
	v_add_f32_e32 v66, v66, v67
	v_add_f32_e32 v67, v69, v66
	v_mul_f32_e32 v79, v78, v67
	v_mul_f32_e32 v68, v76, v79
	v_fma_f32 v70, v79, v76, -v68
	v_fmac_f32_e32 v70, v79, v77
	v_sub_f32_e32 v69, v69, v67
	v_add_f32_e32 v76, v66, v69
	v_add_f32_e32 v66, v68, v70
	v_sub_f32_e32 v69, v67, v66
	v_pk_add_f32 v[72:73], v[66:67], v[68:69] neg_lo:[0,1] neg_hi:[0,1]
	v_mov_b32_e32 v71, v66
	v_pk_add_f32 v[66:67], v[72:73], v[70:71] neg_lo:[0,1] neg_hi:[0,1]
	v_cmp_neq_f32_e32 vcc, s36, v14
	v_add_f32_e32 v67, v76, v67
	v_add_f32_e32 v66, v66, v67
	v_add_f32_e32 v67, v80, v79
	v_add_f32_e32 v66, v69, v66
	v_sub_f32_e32 v68, v67, v80
	v_mul_f32_e32 v66, v78, v66
	v_sub_f32_e32 v68, v79, v68
	v_add_f32_e32 v68, v68, v66
	v_add_f32_e32 v70, v67, v68
	v_mul_f32_e32 v71, v70, v70
	v_fmamk_f32 v66, v71, 0x3e9b6dac, v172
	v_fmaak_f32 v143, v71, v66, 0x3f2aaada
	v_cvt_f32_i32_e32 v66, v75
	v_sub_f32_e32 v67, v70, v67
	v_sub_f32_e32 v67, v68, v67
	v_ldexp_f32 v72, v67, 1
	v_mul_f32_e32 v67, v70, v71
	v_ldexp_f32 v69, v70, 1
	v_pk_mul_f32 v[70:71], v[66:67], v[142:143]
	s_nop 0
	v_fma_f32 v68, v66, s6, -v70
	v_fmac_f32_e32 v68, 0xb102e308, v66
	v_pk_add_f32 v[66:67], v[70:71], v[68:69]
	s_mov_b32 s6, 0x33800000
	v_sub_f32_e32 v69, v67, v69
	v_sub_f32_e32 v69, v71, v69
	v_add_f32_e32 v73, v72, v69
	v_mov_b32_e32 v72, v70
	v_pk_add_f32 v[70:71], v[66:67], v[70:71] neg_lo:[0,1] neg_hi:[0,1]
	v_pk_add_f32 v[76:77], v[66:67], v[72:73]
	v_mov_b32_e32 v69, v66
	v_mov_b32_e32 v71, v77
	v_pk_add_f32 v[78:79], v[68:69], v[70:71] neg_lo:[0,1] neg_hi:[0,1]
	v_pk_add_f32 v[68:69], v[68:69], v[70:71]
	v_mov_b32_e32 v72, v73
	v_pk_add_f32 v[70:71], v[68:69], v[66:67] op_sel:[1,0] op_sel_hi:[0,1] neg_lo:[0,1] neg_hi:[0,1]
	v_pk_add_f32 v[80:81], v[76:77], v[70:71] op_sel_hi:[1,0] neg_lo:[0,1] neg_hi:[0,1]
	v_mov_b32_e32 v76, v77
	v_mov_b32_e32 v77, v69
	v_pk_mov_b32 v[70:71], v[66:67], v[70:71] op_sel:[1,0]
	v_mov_b32_e32 v73, v66
	v_pk_add_f32 v[70:71], v[76:77], v[70:71] neg_lo:[0,1] neg_hi:[0,1]
	v_mov_b32_e32 v80, v78
	v_pk_add_f32 v[66:67], v[72:73], v[70:71] neg_lo:[0,1] neg_hi:[0,1]
	v_mov_b32_e32 v79, v69
	v_pk_add_f32 v[70:71], v[80:81], v[66:67]
	s_nop 0
	v_pk_add_f32 v[72:73], v[70:71], v[70:71] op_sel:[0,1] op_sel_hi:[1,0]
	s_nop 0
	v_pk_add_f32 v[68:69], v[68:69], v[72:73] op_sel:[1,0] op_sel_hi:[0,1]
	v_mov_b32_e32 v71, v68
	v_pk_add_f32 v[76:77], v[70:71], v[78:79] neg_lo:[0,1] neg_hi:[0,1]
	v_mov_b32_e32 v67, v72
	v_sub_f32_e32 v69, v70, v76
	v_pk_add_f32 v[66:67], v[66:67], v[76:77] neg_lo:[0,1] neg_hi:[0,1]
	v_sub_f32_e32 v69, v78, v69
	v_add_f32_e32 v66, v66, v69
	v_add_f32_e32 v66, v66, v67
	v_add_f32_e32 v66, v68, v66
	v_cndmask_b32_e32 v66, v185, v66, vcc
	v_cmp_ngt_f32_e32 vcc, -1.0, v14
	s_nop 1
	v_cndmask_b32_e32 v66, v196, v66, vcc
	v_cmp_neq_f32_e32 vcc, -1.0, v14
	s_nop 1
	v_cndmask_b32_e32 v66, v197, v66, vcc
	v_cmp_lt_f32_e64 vcc, |v14|, s6
	s_nop 1
	v_cndmask_b32_e32 v14, v66, v14, vcc

.LBB0_1008:
	s_or_b64 exec, exec, s[0:1]
	v_lshlrev_b32_e32 v12, 16, v65
	v_cndmask_b32_e64 v13, 0, v12, s[52:53]
	v_lshlrev_b32_e32 v12, 16, v64
	v_lshlrev_b32_e32 v14, 16, v63
	v_mul_f32_e32 v64, v18, v10
	v_mul_f32_e32 v10, v21, v15
	v_cndmask_b32_e64 v63, 0, v14, s[52:53]
	v_fmac_f32_e32 v10, v20, v74
	v_fmac_f32_e32 v10, v22, v63
	v_mul_f32_e32 v65, v16, v11
	v_mul_f32_e32 v11, 0xbfb8aa3b, v10
	v_exp_f32_e32 v11, v11
	s_waitcnt vmcnt(42)
	v_mul_f32_e32 v67, v17, v9
	s_waitcnt vmcnt(41)
	v_mul_f32_e32 v66, v19, v8
	v_cndmask_b32_e64 v12, 0, v12, s[52:53]
	v_add_f32_e32 v11, 1.0, v11
	v_div_scale_f32 v14, s[0:1], v11, v11, v10
	v_rcp_f32_e32 v68, v14
	v_pk_add_f32 v[64:65], v[64:65], v[66:67]
	s_lshl_b64 s[0:1], s[70:71], 8
	v_pk_fma_f32 v[64:65], v[2:3], v[12:13], v[64:65]
	v_fma_f32 v69, -v14, v68, 1.0
	v_mul_f32_e32 v66, 0xbfb8aa3b, v65
	v_fmac_f32_e32 v68, v69, v68
	v_div_scale_f32 v69, vcc, v10, v11, v10
	v_exp_f32_e32 v67, v66
	v_mul_f32_e32 v66, 0xbfb8aa3b, v64
	v_mul_f32_e32 v70, v69, v68
	v_exp_f32_e32 v66, v66
	v_fma_f32 v71, -v14, v70, v69
	v_fmac_f32_e32 v70, v71, v68
	v_fma_f32 v14, -v14, v70, v69
	v_div_fmas_f32 v14, v14, v68, v70
	v_pk_add_f32 v[66:67], v[66:67], 1.0 op_sel_hi:[1,0]
	v_div_fixup_f32 v14, v14, v11, v10
	v_lshl_add_u64 v[10:11], s[0:1], 0, v[0:1]
	v_div_scale_f32 v72, s[0:1], v67, v67, v65
	v_rcp_f32_e32 v73, v72
	v_lshlrev_b64 v[68:69], 1, v[10:11]
	v_lshl_add_u64 v[70:71], s[78:79], 0, v[68:69]
	v_fma_f32 v74, -v72, v73, 1.0
	v_fmac_f32_e32 v73, v74, v73
	v_div_scale_f32 v74, vcc, v65, v67, v65
	v_mul_f32_e32 v75, v74, v73
	v_fma_f32 v76, -v72, v75, v74
	v_fmac_f32_e32 v75, v76, v73
	v_fma_f32 v72, -v72, v75, v74
	v_div_fmas_f32 v72, v72, v73, v75
	v_div_fixup_f32 v65, v72, v67, v65
	v_div_scale_f32 v67, s[0:1], v66, v66, v64
	v_rcp_f32_e32 v72, v67
	s_nop 0
	v_fma_f32 v73, -v67, v72, 1.0
	v_fmac_f32_e32 v72, v73, v72
	v_div_scale_f32 v73, vcc, v64, v66, v64
	v_mul_f32_e32 v74, v73, v72
	v_fma_f32 v75, -v67, v74, v73
	v_fmac_f32_e32 v74, v75, v72
	v_fma_f32 v67, -v67, v74, v73
	v_div_fmas_f32 v67, v67, v72, v74
	v_div_fixup_f32 v64, v67, v66, v64
	v_pk_mul_f32 v[66:67], v[64:65], v[64:65]
	v_cmp_gt_u32_e64 s[98:99], 32, v176
	v_mov_b32_e32 v72, v66
	v_mov_b32_e32 v73, v67
	s_nop 1
	v_permlane32_swap_b32_e32 v72, v66
	v_permlane32_swap_b32_e32 v73, v67
	v_cndmask_b32_e64 v72, v72, v66, s[98:99]
	v_cndmask_b32_e64 v73, v73, v67, s[98:99]
	v_pk_fma_f32 v[66:67], v[64:65], v[64:65], v[72:73]
	v_mov_b32_e32 v72, v66
	v_mov_b32_e32 v73, v67
	s_nop 1
	v_permlane16_swap_b32_e32 v72, v66
	v_permlane16_swap_b32_e32 v73, v67
	v_pk_add_f32 v[66:67], v[66:67], v[72:73]
	s_nop 1
	v_add_f32_dpp v66, v66, v66 row_ror:8 row_mask:0xf bank_mask:0xf
	v_add_f32_dpp v67, v67, v67 row_ror:8 row_mask:0xf bank_mask:0xf
	s_nop 0
	v_add_f32_dpp v66, v66, v66 row_ror:4 row_mask:0xf bank_mask:0xf
	v_add_f32_dpp v67, v67, v67 row_ror:4 row_mask:0xf bank_mask:0xf
	s_nop 0
	v_add_f32_dpp v66, v66, v66 row_ror:2 row_mask:0xf bank_mask:0xf
	v_add_f32_dpp v67, v67, v67 row_ror:2 row_mask:0xf bank_mask:0xf
	s_nop 0
	v_add_f32_dpp v66, v66, v66 row_ror:1 row_mask:0xf bank_mask:0xf
	v_add_f32_dpp v67, v67, v67 row_ror:1 row_mask:0xf bank_mask:0xf
	s_nop 0
	v_pk_add_f32 v[66:67], v[66:67], s[22:23] op_sel_hi:[1,0]
	s_nop 0
	v_mul_f32_e32 v72, 0x4b800000, v67
	v_cmp_gt_f32_e64 s[0:1], s33, v67
	v_cmp_gt_f32_e32 vcc, s33, v66
	s_nop 0
	v_cndmask_b32_e64 v67, v67, v72, s[0:1]
	v_rsq_f32_e32 v67, v67
	v_cvt_pk_bf16_f32 v14, v14, s0
	v_mul_f32_e32 v72, 0x45800000, v67
	v_cndmask_b32_e64 v67, v67, v72, s[0:1]
	v_mul_f32_e32 v65, v65, v67
	v_mul_f32_e32 v65, 0x3e000000, v65
	v_cvt_pk_bf16_f32 v65, v65, s0
	global_store_short v[70:71], v65, off
	v_mul_f32_e32 v65, 0x4b800000, v66
	v_cndmask_b32_e32 v65, v66, v65, vcc
	v_rsq_f32_e32 v65, v65
	s_nop 0
	v_mul_f32_e32 v66, 0x45800000, v65
	v_cndmask_b32_e32 v65, v65, v66, vcc
	v_mul_f32_e32 v64, v64, v65
	v_cvt_pk_bf16_f32 v66, v64, s0
	v_lshl_add_u64 v[64:65], s[80:81], 0, v[68:69]
	global_store_short v[64:65], v66, off
	v_lshl_add_u64 v[64:65], s[82:83], 0, v[68:69]
	global_store_short v[64:65], v14, off
	s_and_saveexec_b64 s[0:1], s[38:39]
	s_cbranch_execz .LBB0_1012
	s_waitcnt vmcnt(43)
	v_lshlrev_b32_e32 v14, 16, v62
	v_mul_f32_e32 v14, 0xbfb8aa3b, v14
	v_exp_f32_e32 v14, v14
	v_mad_i64_i32 v[10:11], s[4:5], s70, v199, v[10:11]
	s_waitcnt vmcnt(42)
	v_lshlrev_b32_e32 v61, 16, v61
	v_add_f32_e32 v14, 1.0, v14
	v_div_scale_f32 v62, s[4:5], v14, v14, 1.0
	v_rcp_f32_e32 v64, v62
	v_div_scale_f32 v65, vcc, 1.0, v14, 1.0
	s_mov_b32 s4, 0x41a00000
	v_fma_f32 v66, -v62, v64, 1.0
	v_fmac_f32_e32 v64, v66, v64
	v_mul_f32_e32 v66, v65, v64
	v_fma_f32 v67, -v62, v66, v65
	v_fmac_f32_e32 v66, v67, v64
	v_fma_f32 v62, -v62, v66, v65
	v_div_fmas_f32 v62, v62, v64, v66
	v_div_fixup_f32 v14, v62, v14, 1.0
	v_lshl_add_u64 v[64:65], v[10:11], 2, s[84:85]
	global_store_dword v[64:65], v14, off
	v_add_f32_e32 v14, v24, v61
	v_cmp_nlt_f32_e32 vcc, s4, v14
	s_and_saveexec_b64 s[4:5], vcc
	s_cbranch_execz .LBB0_1011
	v_mul_f32_e32 v14, 0x3fb8aa3b, v14
	v_exp_f32_e32 v14, v14
	s_mov_b32 s6, 0x3f2aaaab
	v_add_f32_e32 v61, 1.0, v14
	v_frexp_mant_f32_e32 v66, v61
	v_cvt_f64_f32_e32 v[64:65], v61
	v_add_f32_e32 v62, -1.0, v61
	v_frexp_exp_i32_f64_e32 v64, v[64:65]
	v_cmp_gt_f32_e32 vcc, s6, v66
	v_sub_f32_e32 v67, v62, v61
	v_sub_f32_e32 v62, v14, v62
	v_subbrev_co_u32_e32 v72, vcc, 0, v64, vcc
	v_add_f32_e32 v67, 1.0, v67
	v_sub_u32_e32 v64, 0, v72
	v_add_f32_e32 v62, v62, v67
	v_ldexp_f32 v61, v61, v64
	v_ldexp_f32 v62, v62, v64
	v_add_f32_e32 v64, -1.0, v61
	v_add_f32_e32 v65, 1.0, v64
	v_sub_f32_e32 v65, v61, v65
	v_add_f32_e32 v66, v62, v65
	v_add_f32_e32 v65, 1.0, v61
	v_add_f32_e32 v67, -1.0, v65
	v_sub_f32_e32 v61, v61, v67
	v_add_f32_e32 v61, v62, v61
	v_add_f32_e32 v62, v65, v61
	v_rcp_f32_e32 v73, v62
	v_sub_f32_e32 v65, v62, v65
	v_sub_f32_e32 v61, v61, v65
	v_add_f32_e32 v65, v64, v66
	v_sub_f32_e32 v64, v65, v64
	v_mul_f32_e32 v75, v65, v73
	v_sub_f32_e32 v74, v66, v64
	v_mul_f32_e32 v66, v62, v75
	v_fma_f32 v68, v75, v62, -v66
	v_fmac_f32_e32 v68, v75, v61
	v_add_f32_e32 v64, v66, v68
	v_sub_f32_e32 v67, v65, v64
	v_pk_add_f32 v[70:71], v[64:65], v[66:67] neg_lo:[0,1] neg_hi:[0,1]
	v_mov_b32_e32 v69, v64
	v_pk_add_f32 v[64:65], v[70:71], v[68:69] neg_lo:[0,1] neg_hi:[0,1]
	s_mov_b32 s6, 0x3f317218
	v_add_f32_e32 v65, v74, v65
	v_add_f32_e32 v64, v64, v65
	v_add_f32_e32 v65, v67, v64
	v_mul_f32_e32 v74, v73, v65
	v_mul_f32_e32 v66, v62, v74
	v_fma_f32 v68, v74, v62, -v66
	v_fmac_f32_e32 v68, v74, v61
	v_sub_f32_e32 v61, v67, v65
	v_add_f32_e32 v61, v64, v61
	v_add_f32_e32 v64, v66, v68
	v_sub_f32_e32 v67, v65, v64
	v_pk_add_f32 v[70:71], v[64:65], v[66:67] neg_lo:[0,1] neg_hi:[0,1]
	v_mov_b32_e32 v69, v64
	v_pk_add_f32 v[64:65], v[70:71], v[68:69] neg_lo:[0,1] neg_hi:[0,1]
	v_add_f32_e32 v62, v75, v74
	v_add_f32_e32 v61, v61, v65
	v_add_f32_e32 v61, v64, v61
	v_add_f32_e32 v61, v67, v61
	v_sub_f32_e32 v64, v62, v75
	v_mul_f32_e32 v61, v73, v61
	v_sub_f32_e32 v64, v74, v64
	v_add_f32_e32 v61, v64, v61
	v_add_f32_e32 v65, v62, v61
	v_mul_f32_e32 v66, v65, v65
	v_fmamk_f32 v64, v66, 0x3e9b6dac, v172
	v_fmaak_f32 v143, v66, v64, 0x3f2aaada
	v_cvt_f32_i32_e32 v64, v72
	v_sub_f32_e32 v62, v65, v62
	v_ldexp_f32 v67, v65, 1
	v_mul_f32_e32 v65, v65, v66
	v_pk_mul_f32 v[68:69], v[64:65], v[142:143]
	v_sub_f32_e32 v61, v61, v62
	v_fma_f32 v66, v64, s6, -v68
	v_fmac_f32_e32 v66, 0xb102e308, v64
	v_pk_add_f32 v[64:65], v[68:69], v[66:67]
	v_ldexp_f32 v61, v61, 1
	v_sub_f32_e32 v62, v65, v67
	v_sub_f32_e32 v62, v69, v62
	v_add_f32_e32 v71, v61, v62
	v_mov_b32_e32 v70, v68
	v_pk_add_f32 v[68:69], v[64:65], v[68:69] neg_lo:[0,1] neg_hi:[0,1]
	v_pk_add_f32 v[72:73], v[64:65], v[70:71]
	v_mov_b32_e32 v67, v64
	v_mov_b32_e32 v69, v73
	v_pk_add_f32 v[74:75], v[66:67], v[68:69] neg_lo:[0,1] neg_hi:[0,1]
	v_pk_add_f32 v[66:67], v[66:67], v[68:69]
	v_mov_b32_e32 v70, v71
	v_pk_add_f32 v[68:69], v[66:67], v[64:65] op_sel:[1,0] op_sel_hi:[0,1] neg_lo:[0,1] neg_hi:[0,1]
	v_pk_add_f32 v[76:77], v[72:73], v[68:69] op_sel_hi:[1,0] neg_lo:[0,1] neg_hi:[0,1]
	v_mov_b32_e32 v72, v73
	v_mov_b32_e32 v73, v67
	v_pk_mov_b32 v[68:69], v[64:65], v[68:69] op_sel:[1,0]
	v_mov_b32_e32 v71, v64
	v_pk_add_f32 v[68:69], v[72:73], v[68:69] neg_lo:[0,1] neg_hi:[0,1]
	v_mov_b32_e32 v76, v74
	v_pk_add_f32 v[64:65], v[70:71], v[68:69] neg_lo:[0,1] neg_hi:[0,1]
	v_mov_b32_e32 v75, v67
	v_pk_add_f32 v[68:69], v[76:77], v[64:65]
	v_cmp_neq_f32_e32 vcc, s36, v14
	v_pk_add_f32 v[70:71], v[68:69], v[68:69] op_sel:[0,1] op_sel_hi:[1,0]
	s_mov_b32 s6, 0x33800000
	v_pk_add_f32 v[66:67], v[66:67], v[70:71] op_sel:[1,0] op_sel_hi:[0,1]
	v_mov_b32_e32 v69, v66
	v_pk_add_f32 v[72:73], v[68:69], v[74:75] neg_lo:[0,1] neg_hi:[0,1]
	v_mov_b32_e32 v65, v70
	v_sub_f32_e32 v61, v68, v72
	v_pk_add_f32 v[64:65], v[64:65], v[72:73] neg_lo:[0,1] neg_hi:[0,1]
	v_sub_f32_e32 v61, v74, v61
	v_add_f32_e32 v61, v64, v61
	v_add_f32_e32 v61, v61, v65
	v_add_f32_e32 v61, v66, v61
	v_cndmask_b32_e32 v61, v185, v61, vcc
	v_cmp_ngt_f32_e32 vcc, -1.0, v14
	s_nop 1
	v_cndmask_b32_e32 v61, v196, v61, vcc
	v_cmp_neq_f32_e32 vcc, -1.0, v14
	s_nop 1
	v_cndmask_b32_e32 v61, v197, v61, vcc
	v_cmp_lt_f32_e64 vcc, |v14|, s6
	s_nop 1
	v_cndmask_b32_e32 v14, v61, v14, vcc

.LBB0_1012:
	s_or_b64 exec, exec, s[0:1]
	v_lshlrev_b32_e32 v14, 16, v58
	v_mul_f32_e32 v58, v18, v8
	v_mul_f32_e32 v8, v21, v63
	v_cndmask_b32_e64 v14, 0, v14, s[50:51]
	v_fmac_f32_e32 v8, v20, v15
	v_lshlrev_b32_e32 v10, 16, v60
	v_fmac_f32_e32 v8, v22, v14
	v_cndmask_b32_e64 v11, 0, v10, s[50:51]
	v_lshlrev_b32_e32 v10, 16, v59
	v_mul_f32_e32 v59, v16, v9
	v_mul_f32_e32 v9, 0xbfb8aa3b, v8
	v_exp_f32_e32 v9, v9
	s_waitcnt vmcnt(42)
	v_mul_f32_e32 v61, v17, v13
	v_mul_f32_e32 v60, v19, v12
	v_cndmask_b32_e64 v10, 0, v10, s[50:51]
	v_add_f32_e32 v9, 1.0, v9
	v_div_scale_f32 v15, s[0:1], v9, v9, v8
	v_rcp_f32_e32 v62, v15
	v_pk_add_f32 v[58:59], v[58:59], v[60:61]
	s_lshl_b64 s[0:1], s[96:97], 8
	v_pk_fma_f32 v[58:59], v[2:3], v[10:11], v[58:59]
	v_fma_f32 v64, -v15, v62, 1.0
	v_mul_f32_e32 v60, 0xbfb8aa3b, v59
	v_fmac_f32_e32 v62, v64, v62
	v_div_scale_f32 v64, vcc, v8, v9, v8
	v_exp_f32_e32 v61, v60
	v_mul_f32_e32 v60, 0xbfb8aa3b, v58
	v_mul_f32_e32 v65, v64, v62
	v_exp_f32_e32 v60, v60
	v_fma_f32 v66, -v15, v65, v64
	v_fmac_f32_e32 v65, v66, v62
	v_fma_f32 v15, -v15, v65, v64
	v_div_fmas_f32 v15, v15, v62, v65
	v_pk_add_f32 v[60:61], v[60:61], 1.0 op_sel_hi:[1,0]
	v_div_fixup_f32 v15, v15, v9, v8
	v_lshl_add_u64 v[8:9], s[0:1], 0, v[0:1]
	v_div_scale_f32 v62, s[0:1], v61, v61, v59
	v_rcp_f32_e32 v68, v62
	v_lshlrev_b64 v[64:65], 1, v[8:9]
	v_lshl_add_u64 v[66:67], s[78:79], 0, v[64:65]
	v_fma_f32 v69, -v62, v68, 1.0
	v_fmac_f32_e32 v68, v69, v68
	v_div_scale_f32 v69, vcc, v59, v61, v59
	v_mul_f32_e32 v70, v69, v68
	v_fma_f32 v71, -v62, v70, v69
	v_fmac_f32_e32 v70, v71, v68
	v_fma_f32 v62, -v62, v70, v69
	v_div_fmas_f32 v62, v62, v68, v70
	v_div_fixup_f32 v59, v62, v61, v59
	v_div_scale_f32 v61, s[0:1], v60, v60, v58
	v_rcp_f32_e32 v62, v61
	s_nop 0
	v_fma_f32 v68, -v61, v62, 1.0
	v_fmac_f32_e32 v62, v68, v62
	v_div_scale_f32 v68, vcc, v58, v60, v58
	v_mul_f32_e32 v69, v68, v62
	v_fma_f32 v70, -v61, v69, v68
	v_fmac_f32_e32 v69, v70, v62
	v_fma_f32 v61, -v61, v69, v68
	v_div_fmas_f32 v61, v61, v62, v69
	v_div_fixup_f32 v58, v61, v60, v58
	v_pk_mul_f32 v[60:61], v[58:59], v[58:59]
	v_cmp_gt_u32_e64 s[98:99], 32, v176
	v_mov_b32_e32 v68, v60
	v_mov_b32_e32 v69, v61
	s_nop 1
	v_permlane32_swap_b32_e32 v68, v60
	v_permlane32_swap_b32_e32 v69, v61
	v_cndmask_b32_e64 v68, v68, v60, s[98:99]
	v_cndmask_b32_e64 v69, v69, v61, s[98:99]
	v_pk_fma_f32 v[60:61], v[58:59], v[58:59], v[68:69]
	v_mov_b32_e32 v68, v60
	v_mov_b32_e32 v69, v61
	s_nop 1
	v_permlane16_swap_b32_e32 v68, v60
	v_permlane16_swap_b32_e32 v69, v61
	v_pk_add_f32 v[60:61], v[60:61], v[68:69]
	s_nop 1
	v_add_f32_dpp v60, v60, v60 row_ror:8 row_mask:0xf bank_mask:0xf
	v_add_f32_dpp v61, v61, v61 row_ror:8 row_mask:0xf bank_mask:0xf
	s_nop 0
	v_add_f32_dpp v60, v60, v60 row_ror:4 row_mask:0xf bank_mask:0xf
	v_add_f32_dpp v61, v61, v61 row_ror:4 row_mask:0xf bank_mask:0xf
	s_nop 0
	v_add_f32_dpp v60, v60, v60 row_ror:2 row_mask:0xf bank_mask:0xf
	v_add_f32_dpp v61, v61, v61 row_ror:2 row_mask:0xf bank_mask:0xf
	s_nop 0
	v_add_f32_dpp v60, v60, v60 row_ror:1 row_mask:0xf bank_mask:0xf
	v_add_f32_dpp v61, v61, v61 row_ror:1 row_mask:0xf bank_mask:0xf
	s_nop 0
	v_pk_add_f32 v[60:61], v[60:61], s[22:23] op_sel_hi:[1,0]
	s_nop 0
	v_mul_f32_e32 v62, 0x4b800000, v61
	v_cmp_gt_f32_e64 s[0:1], s33, v61
	v_cmp_gt_f32_e32 vcc, s33, v60
	s_nop 0
	v_cndmask_b32_e64 v61, v61, v62, s[0:1]
	v_rsq_f32_e32 v61, v61
	v_cvt_pk_bf16_f32 v15, v15, s0
	v_mul_f32_e32 v62, 0x45800000, v61
	v_cndmask_b32_e64 v61, v61, v62, s[0:1]
	v_mul_f32_e32 v59, v59, v61
	v_mul_f32_e32 v59, 0x3e000000, v59
	v_cvt_pk_bf16_f32 v59, v59, s0
	global_store_short v[66:67], v59, off
	v_mul_f32_e32 v59, 0x4b800000, v60
	v_cndmask_b32_e32 v59, v60, v59, vcc
	v_rsq_f32_e32 v59, v59
	s_nop 0
	v_mul_f32_e32 v60, 0x45800000, v59
	v_cndmask_b32_e32 v59, v59, v60, vcc
	v_mul_f32_e32 v58, v58, v59
	v_cvt_pk_bf16_f32 v60, v58, s0
	v_lshl_add_u64 v[58:59], s[80:81], 0, v[64:65]
	global_store_short v[58:59], v60, off
	v_lshl_add_u64 v[58:59], s[82:83], 0, v[64:65]
	global_store_short v[58:59], v15, off
	s_and_saveexec_b64 s[0:1], s[38:39]
	s_cbranch_execz .LBB0_1016
	s_waitcnt vmcnt(44)
	v_lshlrev_b32_e32 v15, 16, v57
	v_mul_f32_e32 v15, 0xbfb8aa3b, v15
	v_exp_f32_e32 v15, v15
	s_waitcnt vmcnt(43)
	v_lshlrev_b32_e32 v59, 16, v56
	v_mad_i64_i32 v[8:9], s[4:5], s96, v199, v[8:9]
	v_add_f32_e32 v15, 1.0, v15
	v_div_scale_f32 v57, s[4:5], v15, v15, 1.0
	v_rcp_f32_e32 v58, v57
	v_div_scale_f32 v56, vcc, 1.0, v15, 1.0
	s_mov_b32 s4, 0x41a00000
	v_fma_f32 v60, -v57, v58, 1.0
	v_fmac_f32_e32 v58, v60, v58
	v_mul_f32_e32 v60, v56, v58
	v_fma_f32 v61, -v57, v60, v56
	v_fmac_f32_e32 v60, v61, v58
	v_fma_f32 v56, -v57, v60, v56
	v_div_fmas_f32 v56, v56, v58, v60
	v_div_fixup_f32 v15, v56, v15, 1.0
	v_lshl_add_u64 v[56:57], v[8:9], 2, s[84:85]
	global_store_dword v[56:57], v15, off
	v_add_f32_e32 v15, v24, v59
	v_cmp_nlt_f32_e32 vcc, s4, v15
	s_and_saveexec_b64 s[4:5], vcc
	s_cbranch_execz .LBB0_1015
	v_mul_f32_e32 v15, 0x3fb8aa3b, v15
	v_exp_f32_e32 v15, v15
	s_mov_b32 s6, 0x3f2aaaab
	v_add_f32_e32 v58, 1.0, v15
	v_frexp_mant_f32_e32 v60, v58
	v_cvt_f64_f32_e32 v[56:57], v58
	v_frexp_exp_i32_f64_e32 v56, v[56:57]
	v_cmp_gt_f32_e32 vcc, s6, v60
	v_add_f32_e32 v59, -1.0, v58
	v_sub_f32_e32 v61, v59, v58
	v_subbrev_co_u32_e32 v62, vcc, 0, v56, vcc
	v_sub_u32_e32 v56, 0, v62
	v_sub_f32_e32 v59, v15, v59
	v_add_f32_e32 v61, 1.0, v61
	v_ldexp_f32 v57, v58, v56
	v_add_f32_e32 v59, v59, v61
	v_add_f32_e32 v58, -1.0, v57
	v_add_f32_e32 v60, 1.0, v57
	v_ldexp_f32 v56, v59, v56
	v_add_f32_e32 v59, 1.0, v58
	v_add_f32_e32 v61, -1.0, v60
	v_sub_f32_e32 v59, v57, v59
	v_sub_f32_e32 v57, v57, v61
	v_add_f32_e32 v59, v56, v59
	v_add_f32_e32 v56, v56, v57
	v_add_f32_e32 v66, v60, v56
	v_rcp_f32_e32 v68, v66
	v_sub_f32_e32 v57, v66, v60
	v_sub_f32_e32 v67, v56, v57
	v_add_f32_e32 v57, v58, v59
	v_mul_f32_e32 v70, v57, v68
	v_sub_f32_e32 v56, v57, v58
	v_mul_f32_e32 v58, v66, v70
	v_fma_f32 v60, v70, v66, -v58
	v_fmac_f32_e32 v60, v70, v67
	v_sub_f32_e32 v69, v59, v56
	v_add_f32_e32 v56, v58, v60
	v_sub_f32_e32 v59, v57, v56
	v_pk_add_f32 v[64:65], v[56:57], v[58:59] neg_lo:[0,1] neg_hi:[0,1]
	v_mov_b32_e32 v61, v56
	v_pk_add_f32 v[56:57], v[64:65], v[60:61] neg_lo:[0,1] neg_hi:[0,1]
	s_mov_b32 s6, 0x3f317218
	v_add_f32_e32 v57, v69, v57
	v_add_f32_e32 v56, v56, v57
	v_add_f32_e32 v57, v59, v56
	v_mul_f32_e32 v69, v68, v57
	v_mul_f32_e32 v58, v66, v69
	v_fma_f32 v60, v69, v66, -v58
	v_fmac_f32_e32 v60, v69, v67
	v_sub_f32_e32 v59, v59, v57
	v_add_f32_e32 v66, v56, v59
	v_add_f32_e32 v56, v58, v60
	v_sub_f32_e32 v59, v57, v56
	v_pk_add_f32 v[64:65], v[56:57], v[58:59] neg_lo:[0,1] neg_hi:[0,1]
	v_mov_b32_e32 v61, v56
	v_pk_add_f32 v[56:57], v[64:65], v[60:61] neg_lo:[0,1] neg_hi:[0,1]
	v_cmp_neq_f32_e32 vcc, s36, v15
	v_add_f32_e32 v57, v66, v57
	v_add_f32_e32 v56, v56, v57
	v_add_f32_e32 v57, v70, v69
	v_add_f32_e32 v56, v59, v56
	v_sub_f32_e32 v58, v57, v70
	v_mul_f32_e32 v56, v68, v56
	v_sub_f32_e32 v58, v69, v58
	v_add_f32_e32 v58, v58, v56
	v_add_f32_e32 v60, v57, v58
	v_mul_f32_e32 v61, v60, v60
	v_fmamk_f32 v56, v61, 0x3e9b6dac, v172
	v_fmaak_f32 v143, v61, v56, 0x3f2aaada
	v_cvt_f32_i32_e32 v56, v62
	v_sub_f32_e32 v57, v60, v57
	v_sub_f32_e32 v57, v58, v57
	v_ldexp_f32 v62, v57, 1
	v_mul_f32_e32 v57, v60, v61
	v_ldexp_f32 v59, v60, 1
	v_pk_mul_f32 v[60:61], v[56:57], v[142:143]
	s_nop 0
	v_fma_f32 v58, v56, s6, -v60
	v_fmac_f32_e32 v58, 0xb102e308, v56
	v_pk_add_f32 v[56:57], v[60:61], v[58:59]
	v_mov_b32_e32 v64, v60
	v_sub_f32_e32 v59, v57, v59
	v_sub_f32_e32 v59, v61, v59
	v_add_f32_e32 v65, v62, v59
	v_pk_add_f32 v[60:61], v[56:57], v[60:61] neg_lo:[0,1] neg_hi:[0,1]
	v_pk_add_f32 v[66:67], v[56:57], v[64:65]
	v_mov_b32_e32 v59, v56
	v_mov_b32_e32 v61, v67
	v_pk_add_f32 v[68:69], v[58:59], v[60:61] neg_lo:[0,1] neg_hi:[0,1]
	v_pk_add_f32 v[58:59], v[58:59], v[60:61]
	v_mov_b32_e32 v64, v65
	v_pk_add_f32 v[60:61], v[58:59], v[56:57] op_sel:[1,0] op_sel_hi:[0,1] neg_lo:[0,1] neg_hi:[0,1]
	v_pk_add_f32 v[70:71], v[66:67], v[60:61] op_sel_hi:[1,0] neg_lo:[0,1] neg_hi:[0,1]
	v_mov_b32_e32 v66, v67
	v_mov_b32_e32 v67, v59
	v_pk_mov_b32 v[60:61], v[56:57], v[60:61] op_sel:[1,0]
	v_mov_b32_e32 v65, v56
	v_pk_add_f32 v[60:61], v[66:67], v[60:61] neg_lo:[0,1] neg_hi:[0,1]
	v_mov_b32_e32 v70, v68
	v_pk_add_f32 v[56:57], v[64:65], v[60:61] neg_lo:[0,1] neg_hi:[0,1]
	v_mov_b32_e32 v69, v59
	v_pk_add_f32 v[60:61], v[70:71], v[56:57]
	s_mov_b32 s6, 0x33800000
	v_pk_add_f32 v[64:65], v[60:61], v[60:61] op_sel:[0,1] op_sel_hi:[1,0]
	s_nop 0
	v_pk_add_f32 v[58:59], v[58:59], v[64:65] op_sel:[1,0] op_sel_hi:[0,1]
	v_mov_b32_e32 v61, v58
	v_pk_add_f32 v[66:67], v[60:61], v[68:69] neg_lo:[0,1] neg_hi:[0,1]
	v_mov_b32_e32 v57, v64
	v_sub_f32_e32 v59, v60, v66
	v_pk_add_f32 v[56:57], v[56:57], v[66:67] neg_lo:[0,1] neg_hi:[0,1]
	v_sub_f32_e32 v59, v68, v59
	v_add_f32_e32 v56, v56, v59
	v_add_f32_e32 v56, v56, v57
	v_add_f32_e32 v56, v58, v56
	v_cndmask_b32_e32 v56, v185, v56, vcc
	v_cmp_ngt_f32_e32 vcc, -1.0, v15
	s_nop 1
	v_cndmask_b32_e32 v56, v196, v56, vcc
	v_cmp_neq_f32_e32 vcc, -1.0, v15
	s_nop 1
	v_cndmask_b32_e32 v56, v197, v56, vcc
	v_cmp_lt_f32_e64 vcc, |v15|, s6
	s_nop 1
	v_cndmask_b32_e32 v15, v56, v15, vcc

.LBB0_1016:
	s_or_b64 exec, exec, s[0:1]
	v_lshlrev_b32_e32 v15, 16, v54
	v_mul_f32_e32 v54, v18, v12
	v_mul_f32_e32 v12, v21, v14
	v_cndmask_b32_e64 v15, 0, v15, s[48:49]
	v_fmac_f32_e32 v12, v20, v63
	v_lshlrev_b32_e32 v8, 16, v53
	v_fmac_f32_e32 v12, v22, v15
	v_cndmask_b32_e64 v9, 0, v8, s[48:49]
	v_lshlrev_b32_e32 v8, 16, v55
	v_mul_f32_e32 v55, v16, v13
	v_mul_f32_e32 v13, 0xbfb8aa3b, v12
	v_exp_f32_e32 v13, v13
	s_waitcnt vmcnt(44)
	v_mul_f32_e32 v57, v17, v11
	s_waitcnt vmcnt(43)
	v_mul_f32_e32 v56, v19, v10
	v_cndmask_b32_e64 v8, 0, v8, s[48:49]
	v_add_f32_e32 v13, 1.0, v13
	v_div_scale_f32 v53, s[0:1], v13, v13, v12
	v_rcp_f32_e32 v58, v53
	v_pk_add_f32 v[54:55], v[54:55], v[56:57]
	s_lshl_b64 s[0:1], s[2:3], 8
	v_pk_fma_f32 v[54:55], v[2:3], v[8:9], v[54:55]
	v_fma_f32 v59, -v53, v58, 1.0
	v_mul_f32_e32 v56, 0xbfb8aa3b, v55
	v_fmac_f32_e32 v58, v59, v58
	v_div_scale_f32 v59, vcc, v12, v13, v12
	v_exp_f32_e32 v57, v56
	v_mul_f32_e32 v56, 0xbfb8aa3b, v54
	v_mul_f32_e32 v60, v59, v58
	v_exp_f32_e32 v56, v56
	v_fma_f32 v61, -v53, v60, v59
	v_fmac_f32_e32 v60, v61, v58
	v_fma_f32 v53, -v53, v60, v59
	v_div_fmas_f32 v53, v53, v58, v60
	v_pk_add_f32 v[56:57], v[56:57], 1.0 op_sel_hi:[1,0]
	v_div_fixup_f32 v53, v53, v13, v12
	v_lshl_add_u64 v[12:13], s[0:1], 0, v[0:1]
	v_div_scale_f32 v62, s[0:1], v57, v57, v55
	v_rcp_f32_e32 v63, v62
	v_lshlrev_b64 v[58:59], 1, v[12:13]
	v_lshl_add_u64 v[60:61], s[78:79], 0, v[58:59]
	v_fma_f32 v64, -v62, v63, 1.0
	v_fmac_f32_e32 v63, v64, v63
	v_div_scale_f32 v64, vcc, v55, v57, v55
	v_mul_f32_e32 v65, v64, v63
	v_fma_f32 v66, -v62, v65, v64
	v_fmac_f32_e32 v65, v66, v63
	v_fma_f32 v62, -v62, v65, v64
	v_div_fmas_f32 v62, v62, v63, v65
	v_div_fixup_f32 v55, v62, v57, v55
	v_div_scale_f32 v57, s[0:1], v56, v56, v54
	v_rcp_f32_e32 v62, v57
	s_nop 0
	v_fma_f32 v63, -v57, v62, 1.0
	v_fmac_f32_e32 v62, v63, v62
	v_div_scale_f32 v63, vcc, v54, v56, v54
	v_mul_f32_e32 v64, v63, v62
	v_fma_f32 v65, -v57, v64, v63
	v_fmac_f32_e32 v64, v65, v62
	v_fma_f32 v57, -v57, v64, v63
	v_div_fmas_f32 v57, v57, v62, v64
	v_div_fixup_f32 v54, v57, v56, v54
	v_pk_mul_f32 v[56:57], v[54:55], v[54:55]
	v_cmp_gt_u32_e64 s[98:99], 32, v176
	v_mov_b32_e32 v62, v56
	v_mov_b32_e32 v63, v57
	s_nop 1
	v_permlane32_swap_b32_e32 v62, v56
	v_permlane32_swap_b32_e32 v63, v57
	v_cndmask_b32_e64 v62, v62, v56, s[98:99]
	v_cndmask_b32_e64 v63, v63, v57, s[98:99]
	v_pk_fma_f32 v[56:57], v[54:55], v[54:55], v[62:63]
	v_mov_b32_e32 v62, v56
	v_mov_b32_e32 v63, v57
	s_nop 1
	v_permlane16_swap_b32_e32 v62, v56
	v_permlane16_swap_b32_e32 v63, v57
	v_pk_add_f32 v[56:57], v[56:57], v[62:63]
	s_nop 1
	v_add_f32_dpp v56, v56, v56 row_ror:8 row_mask:0xf bank_mask:0xf
	v_add_f32_dpp v57, v57, v57 row_ror:8 row_mask:0xf bank_mask:0xf
	s_nop 0
	v_add_f32_dpp v56, v56, v56 row_ror:4 row_mask:0xf bank_mask:0xf
	v_add_f32_dpp v57, v57, v57 row_ror:4 row_mask:0xf bank_mask:0xf
	s_nop 0
	v_add_f32_dpp v56, v56, v56 row_ror:2 row_mask:0xf bank_mask:0xf
	v_add_f32_dpp v57, v57, v57 row_ror:2 row_mask:0xf bank_mask:0xf
	s_nop 0
	v_add_f32_dpp v56, v56, v56 row_ror:1 row_mask:0xf bank_mask:0xf
	v_add_f32_dpp v57, v57, v57 row_ror:1 row_mask:0xf bank_mask:0xf
	s_nop 0
	v_pk_add_f32 v[56:57], v[56:57], s[22:23] op_sel_hi:[1,0]
	s_nop 0
	v_mul_f32_e32 v62, 0x4b800000, v57
	v_cmp_gt_f32_e64 s[0:1], s33, v57
	v_cmp_gt_f32_e32 vcc, s33, v56
	s_nop 0
	v_cndmask_b32_e64 v57, v57, v62, s[0:1]
	v_rsq_f32_e32 v57, v57
	v_cvt_pk_bf16_f32 v53, v53, s0
	v_mul_f32_e32 v62, 0x45800000, v57
	v_cndmask_b32_e64 v57, v57, v62, s[0:1]
	v_mul_f32_e32 v55, v55, v57
	v_mul_f32_e32 v55, 0x3e000000, v55
	v_cvt_pk_bf16_f32 v55, v55, s0
	global_store_short v[60:61], v55, off
	v_mul_f32_e32 v55, 0x4b800000, v56
	v_cndmask_b32_e32 v55, v56, v55, vcc
	v_rsq_f32_e32 v55, v55
	s_nop 0
	v_mul_f32_e32 v56, 0x45800000, v55
	v_cndmask_b32_e32 v55, v55, v56, vcc
	v_mul_f32_e32 v54, v54, v55
	v_cvt_pk_bf16_f32 v56, v54, s0
	v_lshl_add_u64 v[54:55], s[80:81], 0, v[58:59]
	global_store_short v[54:55], v56, off
	v_lshl_add_u64 v[54:55], s[82:83], 0, v[58:59]
	global_store_short v[54:55], v53, off
	s_and_saveexec_b64 s[0:1], s[38:39]
	v_readlane_b32 s96, v243, 19
	v_readlane_b32 s97, v243, 20
	s_cbranch_execz .LBB0_1020
	s_waitcnt vmcnt(45)
	v_lshlrev_b32_e32 v52, 16, v52
	v_mul_f32_e32 v52, 0xbfb8aa3b, v52
	v_exp_f32_e32 v52, v52
	s_waitcnt vmcnt(44)
	v_lshlrev_b32_e32 v51, 16, v51
	v_mad_i64_i32 v[12:13], s[2:3], s2, v199, v[12:13]
	v_add_f32_e32 v52, 1.0, v52
	v_div_scale_f32 v53, s[4:5], v52, v52, 1.0
	v_rcp_f32_e32 v54, v53
	v_div_scale_f32 v55, vcc, 1.0, v52, 1.0
	v_add_f32_e32 v51, v24, v51
	v_fma_f32 v56, -v53, v54, 1.0
	v_fmac_f32_e32 v54, v56, v54
	v_mul_f32_e32 v56, v55, v54
	v_fma_f32 v57, -v53, v56, v55
	v_fmac_f32_e32 v56, v57, v54
	v_fma_f32 v53, -v53, v56, v55
	v_div_fmas_f32 v53, v53, v54, v56
	s_mov_b32 s2, 0x41a00000
	v_div_fixup_f32 v54, v53, v52, 1.0
	v_lshl_add_u64 v[52:53], v[12:13], 2, s[84:85]
	v_cmp_nlt_f32_e32 vcc, s2, v51
	global_store_dword v[52:53], v54, off
	s_and_saveexec_b64 s[2:3], vcc
	s_cbranch_execz .LBB0_1019
	v_mul_f32_e32 v51, 0x3fb8aa3b, v51
	v_exp_f32_e32 v51, v51
	s_mov_b32 s4, 0x3f2aaaab
	v_add_f32_e32 v54, 1.0, v51
	v_frexp_mant_f32_e32 v56, v54
	v_cvt_f64_f32_e32 v[52:53], v54
	v_frexp_exp_i32_f64_e32 v52, v[52:53]
	v_cmp_gt_f32_e32 vcc, s4, v56
	v_add_f32_e32 v55, -1.0, v54
	v_sub_f32_e32 v57, v55, v54
	v_subbrev_co_u32_e32 v60, vcc, 0, v52, vcc
	v_sub_u32_e32 v52, 0, v60
	v_sub_f32_e32 v55, v51, v55
	v_add_f32_e32 v57, 1.0, v57
	v_ldexp_f32 v53, v54, v52
	v_add_f32_e32 v55, v55, v57
	v_add_f32_e32 v54, -1.0, v53
	v_add_f32_e32 v56, 1.0, v53
	v_ldexp_f32 v52, v55, v52
	v_add_f32_e32 v55, 1.0, v54
	v_add_f32_e32 v57, -1.0, v56
	v_sub_f32_e32 v55, v53, v55
	v_sub_f32_e32 v53, v53, v57
	v_add_f32_e32 v55, v52, v55
	v_add_f32_e32 v52, v52, v53
	v_add_f32_e32 v61, v56, v52
	v_rcp_f32_e32 v63, v61
	v_sub_f32_e32 v53, v61, v56
	v_sub_f32_e32 v62, v52, v53
	v_add_f32_e32 v53, v54, v55
	v_mul_f32_e32 v65, v53, v63
	v_sub_f32_e32 v52, v53, v54
	v_mul_f32_e32 v54, v61, v65
	v_fma_f32 v56, v65, v61, -v54
	v_fmac_f32_e32 v56, v65, v62
	v_sub_f32_e32 v64, v55, v52
	v_add_f32_e32 v52, v54, v56
	v_sub_f32_e32 v55, v53, v52
	v_pk_add_f32 v[58:59], v[52:53], v[54:55] neg_lo:[0,1] neg_hi:[0,1]
	v_mov_b32_e32 v57, v52
	v_pk_add_f32 v[52:53], v[58:59], v[56:57] neg_lo:[0,1] neg_hi:[0,1]
	s_mov_b32 s4, 0x3f317218
	v_add_f32_e32 v53, v64, v53
	v_add_f32_e32 v52, v52, v53
	v_add_f32_e32 v53, v55, v52
	v_mul_f32_e32 v64, v63, v53
	v_mul_f32_e32 v54, v61, v64
	v_fma_f32 v56, v64, v61, -v54
	v_fmac_f32_e32 v56, v64, v62
	v_sub_f32_e32 v55, v55, v53
	v_add_f32_e32 v61, v52, v55
	v_add_f32_e32 v52, v54, v56
	v_sub_f32_e32 v55, v53, v52
	v_pk_add_f32 v[58:59], v[52:53], v[54:55] neg_lo:[0,1] neg_hi:[0,1]
	v_mov_b32_e32 v57, v52
	v_pk_add_f32 v[52:53], v[58:59], v[56:57] neg_lo:[0,1] neg_hi:[0,1]
	v_cmp_neq_f32_e32 vcc, s36, v51
	v_add_f32_e32 v53, v61, v53
	v_add_f32_e32 v52, v52, v53
	v_add_f32_e32 v53, v65, v64
	v_add_f32_e32 v52, v55, v52
	v_sub_f32_e32 v54, v53, v65
	v_mul_f32_e32 v52, v63, v52
	v_sub_f32_e32 v54, v64, v54
	v_add_f32_e32 v54, v54, v52
	v_add_f32_e32 v56, v53, v54
	v_mul_f32_e32 v57, v56, v56
	v_fmamk_f32 v52, v57, 0x3e9b6dac, v172
	v_fmaak_f32 v143, v57, v52, 0x3f2aaada
	v_cvt_f32_i32_e32 v52, v60
	v_sub_f32_e32 v53, v56, v53
	v_sub_f32_e32 v53, v54, v53
	v_ldexp_f32 v58, v53, 1
	v_mul_f32_e32 v53, v56, v57
	v_ldexp_f32 v55, v56, 1
	v_pk_mul_f32 v[56:57], v[52:53], v[142:143]
	s_nop 0
	v_fma_f32 v54, v52, s4, -v56
	v_fmac_f32_e32 v54, 0xb102e308, v52
	v_pk_add_f32 v[52:53], v[56:57], v[54:55]
	s_mov_b32 s4, 0x33800000
	v_sub_f32_e32 v55, v53, v55
	v_sub_f32_e32 v55, v57, v55
	v_add_f32_e32 v59, v58, v55
	v_mov_b32_e32 v58, v56
	v_pk_add_f32 v[56:57], v[52:53], v[56:57] neg_lo:[0,1] neg_hi:[0,1]
	v_pk_add_f32 v[60:61], v[52:53], v[58:59]
	v_mov_b32_e32 v55, v52
	v_mov_b32_e32 v57, v61
	v_pk_add_f32 v[62:63], v[54:55], v[56:57] neg_lo:[0,1] neg_hi:[0,1]
	v_pk_add_f32 v[54:55], v[54:55], v[56:57]
	v_mov_b32_e32 v58, v59
	v_pk_add_f32 v[56:57], v[54:55], v[52:53] op_sel:[1,0] op_sel_hi:[0,1] neg_lo:[0,1] neg_hi:[0,1]
	v_pk_add_f32 v[64:65], v[60:61], v[56:57] op_sel_hi:[1,0] neg_lo:[0,1] neg_hi:[0,1]
	v_mov_b32_e32 v60, v61
	v_mov_b32_e32 v61, v55
	v_pk_mov_b32 v[56:57], v[52:53], v[56:57] op_sel:[1,0]
	v_mov_b32_e32 v59, v52
	v_pk_add_f32 v[56:57], v[60:61], v[56:57] neg_lo:[0,1] neg_hi:[0,1]
	v_mov_b32_e32 v64, v62
	v_pk_add_f32 v[52:53], v[58:59], v[56:57] neg_lo:[0,1] neg_hi:[0,1]
	v_mov_b32_e32 v63, v55
	v_pk_add_f32 v[56:57], v[64:65], v[52:53]
	s_nop 0
	v_pk_add_f32 v[58:59], v[56:57], v[56:57] op_sel:[0,1] op_sel_hi:[1,0]
	s_nop 0
	v_pk_add_f32 v[54:55], v[54:55], v[58:59] op_sel:[1,0] op_sel_hi:[0,1]
	v_mov_b32_e32 v57, v54
	v_pk_add_f32 v[60:61], v[56:57], v[62:63] neg_lo:[0,1] neg_hi:[0,1]
	v_mov_b32_e32 v53, v58
	v_sub_f32_e32 v55, v56, v60
	v_pk_add_f32 v[52:53], v[52:53], v[60:61] neg_lo:[0,1] neg_hi:[0,1]
	v_sub_f32_e32 v55, v62, v55
	v_add_f32_e32 v52, v52, v55
	v_add_f32_e32 v52, v52, v53
	v_add_f32_e32 v52, v54, v52
	v_cndmask_b32_e32 v52, v185, v52, vcc
	v_cmp_ngt_f32_e32 vcc, -1.0, v51
	s_nop 1
	v_cndmask_b32_e32 v52, v196, v52, vcc
	v_cmp_neq_f32_e32 vcc, -1.0, v51
	s_nop 1
	v_cndmask_b32_e32 v52, v197, v52, vcc
	v_cmp_lt_f32_e64 vcc, |v51|, s4
	s_nop 1
	v_cndmask_b32_e32 v51, v52, v51, vcc

.LBB0_1020:
	s_or_b64 exec, exec, s[0:1]
	v_lshlrev_b32_e32 v12, 16, v50
	v_lshlrev_b32_e32 v48, 16, v48
	v_mul_f32_e32 v50, v18, v10
	v_mul_f32_e32 v10, v21, v15
	v_cndmask_b32_e64 v48, 0, v48, s[46:47]
	v_fmac_f32_e32 v10, v20, v14
	v_fmac_f32_e32 v10, v22, v48
	s_waitcnt vmcnt(44)
	v_mul_f32_e32 v51, v16, v11
	v_mul_f32_e32 v11, 0xbfb8aa3b, v10
	v_exp_f32_e32 v11, v11
	v_cndmask_b32_e64 v13, 0, v12, s[46:47]
	v_lshlrev_b32_e32 v12, 16, v49
	v_mul_f32_e32 v53, v17, v9
	v_add_f32_e32 v11, 1.0, v11
	v_div_scale_f32 v14, s[0:1], v11, v11, v10
	v_rcp_f32_e32 v49, v14
	v_mul_f32_e32 v52, v19, v8
	v_cndmask_b32_e64 v12, 0, v12, s[46:47]
	v_pk_add_f32 v[50:51], v[50:51], v[52:53]
	v_fma_f32 v54, -v14, v49, 1.0
	v_fmac_f32_e32 v49, v54, v49
	v_div_scale_f32 v54, vcc, v10, v11, v10
	v_mul_f32_e32 v55, v54, v49
	v_fma_f32 v56, -v14, v55, v54
	v_fmac_f32_e32 v55, v56, v49
	v_fma_f32 v14, -v14, v55, v54
	v_pk_fma_f32 v[50:51], v[2:3], v[12:13], v[50:51]
	v_div_fmas_f32 v14, v14, v49, v55
	v_mul_f32_e32 v49, 0xbfb8aa3b, v51
	v_exp_f32_e32 v53, v49
	v_mul_f32_e32 v49, 0xbfb8aa3b, v50
	v_exp_f32_e32 v52, v49
	s_lshl_b64 s[0:1], s[26:27], 8
	v_div_fixup_f32 v14, v14, v11, v10
	v_lshl_add_u64 v[10:11], s[0:1], 0, v[0:1]
	v_pk_add_f32 v[52:53], v[52:53], 1.0 op_sel_hi:[1,0]
	v_lshlrev_b64 v[54:55], 1, v[10:11]
	v_div_scale_f32 v49, s[0:1], v53, v53, v51
	v_rcp_f32_e32 v58, v49
	v_lshl_add_u64 v[56:57], s[78:79], 0, v[54:55]
	v_fma_f32 v59, -v49, v58, 1.0
	v_fmac_f32_e32 v58, v59, v58
	v_div_scale_f32 v59, vcc, v51, v53, v51
	v_mul_f32_e32 v60, v59, v58
	v_fma_f32 v61, -v49, v60, v59
	v_fmac_f32_e32 v60, v61, v58
	v_fma_f32 v49, -v49, v60, v59
	v_div_fmas_f32 v49, v49, v58, v60
	v_div_fixup_f32 v51, v49, v53, v51
	v_div_scale_f32 v49, s[0:1], v52, v52, v50
	v_rcp_f32_e32 v53, v49
	s_nop 0
	v_fma_f32 v58, -v49, v53, 1.0
	v_fmac_f32_e32 v53, v58, v53
	v_div_scale_f32 v58, vcc, v50, v52, v50
	v_mul_f32_e32 v59, v58, v53
	v_fma_f32 v60, -v49, v59, v58
	v_fmac_f32_e32 v59, v60, v53
	v_fma_f32 v49, -v49, v59, v58
	v_div_fmas_f32 v49, v49, v53, v59
	v_div_fixup_f32 v50, v49, v52, v50
	v_pk_mul_f32 v[52:53], v[50:51], v[50:51]
	v_cmp_gt_u32_e64 s[98:99], 32, v176
	v_mov_b32_e32 v58, v52
	v_mov_b32_e32 v59, v53
	s_nop 1
	v_permlane32_swap_b32_e32 v58, v52
	v_permlane32_swap_b32_e32 v59, v53
	v_cndmask_b32_e64 v58, v58, v52, s[98:99]
	v_cndmask_b32_e64 v59, v59, v53, s[98:99]
	v_pk_fma_f32 v[52:53], v[50:51], v[50:51], v[58:59]
	v_mov_b32_e32 v58, v52
	v_mov_b32_e32 v59, v53
	s_nop 1
	v_permlane16_swap_b32_e32 v58, v52
	v_permlane16_swap_b32_e32 v59, v53
	v_pk_add_f32 v[52:53], v[52:53], v[58:59]
	s_nop 1
	v_add_f32_dpp v52, v52, v52 row_ror:8 row_mask:0xf bank_mask:0xf
	v_add_f32_dpp v53, v53, v53 row_ror:8 row_mask:0xf bank_mask:0xf
	s_nop 0
	v_add_f32_dpp v52, v52, v52 row_ror:4 row_mask:0xf bank_mask:0xf
	v_add_f32_dpp v53, v53, v53 row_ror:4 row_mask:0xf bank_mask:0xf
	s_nop 0
	v_add_f32_dpp v52, v52, v52 row_ror:2 row_mask:0xf bank_mask:0xf
	v_add_f32_dpp v53, v53, v53 row_ror:2 row_mask:0xf bank_mask:0xf
	s_nop 0
	v_add_f32_dpp v52, v52, v52 row_ror:1 row_mask:0xf bank_mask:0xf
	v_add_f32_dpp v53, v53, v53 row_ror:1 row_mask:0xf bank_mask:0xf
	s_nop 0
	v_pk_add_f32 v[52:53], v[52:53], s[22:23] op_sel_hi:[1,0]
	s_nop 0
	v_mul_f32_e32 v49, 0x4b800000, v53
	v_cmp_gt_f32_e64 s[0:1], s33, v53
	v_cmp_gt_f32_e32 vcc, s33, v52
	s_nop 0
	v_cndmask_b32_e64 v49, v53, v49, s[0:1]
	v_rsq_f32_e32 v49, v49
	v_cvt_pk_bf16_f32 v14, v14, s0
	v_mul_f32_e32 v53, 0x45800000, v49
	v_cndmask_b32_e64 v49, v49, v53, s[0:1]
	v_mul_f32_e32 v49, v51, v49
	v_mul_f32_e32 v49, 0x3e000000, v49
	v_cvt_pk_bf16_f32 v49, v49, s0
	global_store_short v[56:57], v49, off
	v_mul_f32_e32 v49, 0x4b800000, v52
	v_cndmask_b32_e32 v49, v52, v49, vcc
	v_rsq_f32_e32 v49, v49
	s_nop 0
	v_mul_f32_e32 v51, 0x45800000, v49
	v_cndmask_b32_e32 v49, v49, v51, vcc
	v_mul_f32_e32 v49, v50, v49
	v_cvt_pk_bf16_f32 v49, v49, s0
	v_lshl_add_u64 v[50:51], s[80:81], 0, v[54:55]
	global_store_short v[50:51], v49, off
	v_lshl_add_u64 v[50:51], s[82:83], 0, v[54:55]
	global_store_short v[50:51], v14, off
	s_and_saveexec_b64 s[0:1], s[38:39]
	s_cbranch_execz .LBB0_1024
	s_waitcnt vmcnt(46)
	v_lshlrev_b32_e32 v14, 16, v47
	v_mul_f32_e32 v14, 0xbfb8aa3b, v14
	v_exp_f32_e32 v14, v14
	s_waitcnt vmcnt(45)
	v_lshlrev_b32_e32 v50, 16, v46
	v_mad_i64_i32 v[10:11], s[2:3], s26, v199, v[10:11]
	v_add_f32_e32 v14, 1.0, v14
	v_div_scale_f32 v47, s[2:3], v14, v14, 1.0
	v_rcp_f32_e32 v49, v47
	v_div_scale_f32 v46, vcc, 1.0, v14, 1.0
	s_mov_b32 s2, 0x41a00000
	v_fma_f32 v51, -v47, v49, 1.0
	v_fmac_f32_e32 v49, v51, v49
	v_mul_f32_e32 v51, v46, v49
	v_fma_f32 v52, -v47, v51, v46
	v_fmac_f32_e32 v51, v52, v49
	v_fma_f32 v46, -v47, v51, v46
	v_div_fmas_f32 v46, v46, v49, v51
	v_div_fixup_f32 v14, v46, v14, 1.0
	v_lshl_add_u64 v[46:47], v[10:11], 2, s[84:85]
	global_store_dword v[46:47], v14, off
	v_add_f32_e32 v14, v24, v50
	v_cmp_nlt_f32_e32 vcc, s2, v14
	s_and_saveexec_b64 s[2:3], vcc
	s_cbranch_execz .LBB0_1023
	v_mul_f32_e32 v14, 0x3fb8aa3b, v14
	v_exp_f32_e32 v14, v14
	s_mov_b32 s4, 0x3f2aaaab
	v_add_f32_e32 v49, 1.0, v14
	v_frexp_mant_f32_e32 v51, v49
	v_cvt_f64_f32_e32 v[46:47], v49
	v_frexp_exp_i32_f64_e32 v46, v[46:47]
	v_cmp_gt_f32_e32 vcc, s4, v51
	v_add_f32_e32 v50, -1.0, v49
	v_sub_f32_e32 v52, v50, v49
	v_subbrev_co_u32_e32 v56, vcc, 0, v46, vcc
	v_sub_u32_e32 v46, 0, v56
	v_sub_f32_e32 v50, v14, v50
	v_add_f32_e32 v52, 1.0, v52
	v_ldexp_f32 v47, v49, v46
	v_add_f32_e32 v50, v50, v52
	v_add_f32_e32 v49, -1.0, v47
	v_add_f32_e32 v51, 1.0, v47
	v_ldexp_f32 v46, v50, v46
	v_add_f32_e32 v50, 1.0, v49
	v_add_f32_e32 v52, -1.0, v51
	v_sub_f32_e32 v50, v47, v50
	v_sub_f32_e32 v47, v47, v52
	v_add_f32_e32 v50, v46, v50
	v_add_f32_e32 v46, v46, v47
	v_add_f32_e32 v57, v51, v46
	v_rcp_f32_e32 v59, v57
	v_sub_f32_e32 v47, v57, v51
	v_sub_f32_e32 v58, v46, v47
	v_add_f32_e32 v47, v49, v50
	v_sub_f32_e32 v46, v47, v49
	v_mul_f32_e32 v60, v47, v59
	v_sub_f32_e32 v49, v50, v46
	v_mul_f32_e32 v50, v57, v60
	v_fma_f32 v52, v60, v57, -v50
	v_fmac_f32_e32 v52, v60, v58
	v_add_f32_e32 v46, v50, v52
	v_sub_f32_e32 v51, v47, v46
	v_pk_add_f32 v[54:55], v[46:47], v[50:51] neg_lo:[0,1] neg_hi:[0,1]
	v_mov_b32_e32 v53, v46
	v_pk_add_f32 v[46:47], v[54:55], v[52:53] neg_lo:[0,1] neg_hi:[0,1]
	s_mov_b32 s4, 0x3f317218
	v_add_f32_e32 v47, v49, v47
	v_add_f32_e32 v46, v46, v47
	v_add_f32_e32 v47, v51, v46
	v_mul_f32_e32 v49, v59, v47
	v_mul_f32_e32 v50, v57, v49
	v_fma_f32 v52, v49, v57, -v50
	v_fmac_f32_e32 v52, v49, v58
	v_sub_f32_e32 v51, v51, v47
	v_add_f32_e32 v57, v46, v51
	v_add_f32_e32 v46, v50, v52
	v_sub_f32_e32 v51, v47, v46
	v_pk_add_f32 v[54:55], v[46:47], v[50:51] neg_lo:[0,1] neg_hi:[0,1]
	v_mov_b32_e32 v53, v46
	v_pk_add_f32 v[46:47], v[54:55], v[52:53] neg_lo:[0,1] neg_hi:[0,1]
	v_cmp_neq_f32_e32 vcc, s36, v14
	v_add_f32_e32 v47, v57, v47
	v_add_f32_e32 v46, v46, v47
	v_add_f32_e32 v47, v60, v49
	v_add_f32_e32 v46, v51, v46
	v_sub_f32_e32 v50, v47, v60
	v_mul_f32_e32 v46, v59, v46
	v_sub_f32_e32 v49, v49, v50
	v_add_f32_e32 v49, v49, v46
	v_add_f32_e32 v50, v47, v49
	v_mul_f32_e32 v52, v50, v50
	v_fmamk_f32 v46, v52, 0x3e9b6dac, v172
	v_fmaak_f32 v143, v52, v46, 0x3f2aaada
	v_cvt_f32_i32_e32 v46, v56
	v_sub_f32_e32 v47, v50, v47
	v_sub_f32_e32 v47, v49, v47
	v_ldexp_f32 v49, v47, 1
	v_mul_f32_e32 v47, v50, v52
	v_pk_mul_f32 v[52:53], v[46:47], v[142:143]
	v_ldexp_f32 v51, v50, 1
	v_fma_f32 v50, v46, s4, -v52
	v_fmac_f32_e32 v50, 0xb102e308, v46
	v_pk_add_f32 v[46:47], v[52:53], v[50:51]
	v_mov_b32_e32 v54, v52
	v_sub_f32_e32 v51, v47, v51
	v_sub_f32_e32 v51, v53, v51
	v_add_f32_e32 v55, v49, v51
	v_pk_add_f32 v[52:53], v[46:47], v[52:53] neg_lo:[0,1] neg_hi:[0,1]
	v_pk_add_f32 v[56:57], v[46:47], v[54:55]
	v_mov_b32_e32 v51, v46
	v_mov_b32_e32 v53, v57
	v_pk_add_f32 v[58:59], v[50:51], v[52:53] neg_lo:[0,1] neg_hi:[0,1]
	v_pk_add_f32 v[50:51], v[50:51], v[52:53]
	v_mov_b32_e32 v54, v55
	v_pk_add_f32 v[52:53], v[50:51], v[46:47] op_sel:[1,0] op_sel_hi:[0,1] neg_lo:[0,1] neg_hi:[0,1]
	v_pk_add_f32 v[60:61], v[56:57], v[52:53] op_sel_hi:[1,0] neg_lo:[0,1] neg_hi:[0,1]
	v_mov_b32_e32 v56, v57
	v_mov_b32_e32 v57, v51
	v_pk_mov_b32 v[52:53], v[46:47], v[52:53] op_sel:[1,0]
	v_mov_b32_e32 v55, v46
	v_pk_add_f32 v[52:53], v[56:57], v[52:53] neg_lo:[0,1] neg_hi:[0,1]
	v_mov_b32_e32 v60, v58
	v_pk_add_f32 v[46:47], v[54:55], v[52:53] neg_lo:[0,1] neg_hi:[0,1]
	v_mov_b32_e32 v59, v51
	v_pk_add_f32 v[52:53], v[60:61], v[46:47]
	s_mov_b32 s4, 0x33800000
	v_pk_add_f32 v[54:55], v[52:53], v[52:53] op_sel:[0,1] op_sel_hi:[1,0]
	s_nop 0
	v_pk_add_f32 v[50:51], v[50:51], v[54:55] op_sel:[1,0] op_sel_hi:[0,1]
	v_mov_b32_e32 v53, v50
	v_pk_add_f32 v[56:57], v[52:53], v[58:59] neg_lo:[0,1] neg_hi:[0,1]
	v_mov_b32_e32 v47, v54
	v_sub_f32_e32 v49, v52, v56
	v_pk_add_f32 v[46:47], v[46:47], v[56:57] neg_lo:[0,1] neg_hi:[0,1]
	v_sub_f32_e32 v49, v58, v49
	v_add_f32_e32 v46, v46, v49
	v_add_f32_e32 v46, v46, v47
	v_add_f32_e32 v46, v50, v46
	v_cndmask_b32_e32 v46, v185, v46, vcc
	v_cmp_ngt_f32_e32 vcc, -1.0, v14
	s_nop 1
	v_cndmask_b32_e32 v46, v196, v46, vcc
	v_cmp_neq_f32_e32 vcc, -1.0, v14
	s_nop 1
	v_cndmask_b32_e32 v46, v197, v46, vcc
	v_cmp_lt_f32_e64 vcc, |v14|, s4
	s_nop 1
	v_cndmask_b32_e32 v14, v46, v14, vcc

.LBB0_1028:
	s_or_b64 exec, exec, s[0:1]
	v_lshlrev_b32_e32 v15, 16, v38
	v_mul_f32_e32 v38, v18, v12
	v_mul_f32_e32 v12, v21, v14
	v_cndmask_b32_e64 v15, 0, v15, s[42:43]
	v_fmac_f32_e32 v12, v20, v48
	v_lshlrev_b32_e32 v8, 16, v40
	v_fmac_f32_e32 v12, v22, v15
	v_cndmask_b32_e64 v9, 0, v8, s[42:43]
	v_lshlrev_b32_e32 v8, 16, v39
	v_mul_f32_e32 v39, v16, v13
	v_mul_f32_e32 v13, 0xbfb8aa3b, v12
	v_exp_f32_e32 v13, v13
	s_waitcnt vmcnt(46)
	v_mul_f32_e32 v41, v17, v11
	v_mul_f32_e32 v40, v19, v10
	v_cndmask_b32_e64 v8, 0, v8, s[42:43]
	v_add_f32_e32 v13, 1.0, v13
	v_div_scale_f32 v42, s[0:1], v13, v13, v12
	v_rcp_f32_e32 v43, v42
	v_pk_add_f32 v[38:39], v[38:39], v[40:41]
	s_lshl_b64 s[0:1], s[30:31], 8
	v_pk_fma_f32 v[38:39], v[2:3], v[8:9], v[38:39]
	v_fma_f32 v44, -v42, v43, 1.0
	v_mul_f32_e32 v40, 0xbfb8aa3b, v39
	v_fmac_f32_e32 v43, v44, v43
	v_div_scale_f32 v44, vcc, v12, v13, v12
	v_exp_f32_e32 v41, v40
	v_mul_f32_e32 v40, 0xbfb8aa3b, v38
	v_mul_f32_e32 v45, v44, v43
	v_exp_f32_e32 v40, v40
	v_fma_f32 v46, -v42, v45, v44
	v_fmac_f32_e32 v45, v46, v43
	v_fma_f32 v42, -v42, v45, v44
	v_div_fmas_f32 v42, v42, v43, v45
	v_pk_add_f32 v[40:41], v[40:41], 1.0 op_sel_hi:[1,0]
	v_div_fixup_f32 v48, v42, v13, v12
	v_lshl_add_u64 v[12:13], s[0:1], 0, v[0:1]
	v_div_scale_f32 v46, s[0:1], v41, v41, v39
	v_rcp_f32_e32 v47, v46
	v_lshlrev_b64 v[42:43], 1, v[12:13]
	v_lshl_add_u64 v[44:45], s[78:79], 0, v[42:43]
	v_fma_f32 v49, -v46, v47, 1.0
	v_fmac_f32_e32 v47, v49, v47
	v_div_scale_f32 v49, vcc, v39, v41, v39
	v_mul_f32_e32 v50, v49, v47
	v_fma_f32 v51, -v46, v50, v49
	v_fmac_f32_e32 v50, v51, v47
	v_fma_f32 v46, -v46, v50, v49
	v_div_fmas_f32 v46, v46, v47, v50
	v_div_fixup_f32 v39, v46, v41, v39
	v_div_scale_f32 v41, s[0:1], v40, v40, v38
	v_rcp_f32_e32 v46, v41
	s_nop 0
	v_fma_f32 v47, -v41, v46, 1.0
	v_fmac_f32_e32 v46, v47, v46
	v_div_scale_f32 v47, vcc, v38, v40, v38
	v_mul_f32_e32 v49, v47, v46
	v_fma_f32 v50, -v41, v49, v47
	v_fmac_f32_e32 v49, v50, v46
	v_fma_f32 v41, -v41, v49, v47
	v_div_fmas_f32 v41, v41, v46, v49
	v_div_fixup_f32 v38, v41, v40, v38
	v_pk_mul_f32 v[40:41], v[38:39], v[38:39]
	v_cmp_gt_u32_e64 s[98:99], 32, v176
	v_mov_b32_e32 v46, v40
	v_mov_b32_e32 v47, v41
	s_nop 1
	v_permlane32_swap_b32_e32 v46, v40
	v_permlane32_swap_b32_e32 v47, v41
	v_cndmask_b32_e64 v46, v46, v40, s[98:99]
	v_cndmask_b32_e64 v47, v47, v41, s[98:99]
	v_pk_fma_f32 v[40:41], v[38:39], v[38:39], v[46:47]
	v_mov_b32_e32 v46, v40
	v_mov_b32_e32 v47, v41
	s_nop 1
	v_permlane16_swap_b32_e32 v46, v40
	v_permlane16_swap_b32_e32 v47, v41
	v_pk_add_f32 v[40:41], v[40:41], v[46:47]
	s_nop 1
	v_add_f32_dpp v40, v40, v40 row_ror:8 row_mask:0xf bank_mask:0xf
	v_add_f32_dpp v41, v41, v41 row_ror:8 row_mask:0xf bank_mask:0xf
	s_nop 0
	v_add_f32_dpp v40, v40, v40 row_ror:4 row_mask:0xf bank_mask:0xf
	v_add_f32_dpp v41, v41, v41 row_ror:4 row_mask:0xf bank_mask:0xf
	s_nop 0
	v_add_f32_dpp v40, v40, v40 row_ror:2 row_mask:0xf bank_mask:0xf
	v_add_f32_dpp v41, v41, v41 row_ror:2 row_mask:0xf bank_mask:0xf
	s_nop 0
	v_add_f32_dpp v40, v40, v40 row_ror:1 row_mask:0xf bank_mask:0xf
	v_add_f32_dpp v41, v41, v41 row_ror:1 row_mask:0xf bank_mask:0xf
	s_nop 0
	v_pk_add_f32 v[40:41], v[40:41], s[22:23] op_sel_hi:[1,0]
	s_nop 0
	v_mul_f32_e32 v46, 0x4b800000, v41
	v_cmp_gt_f32_e64 s[0:1], s33, v41
	v_cmp_gt_f32_e32 vcc, s33, v40
	s_nop 0
	v_cndmask_b32_e64 v41, v41, v46, s[0:1]
	v_rsq_f32_e32 v41, v41
	s_nop 0
	v_mul_f32_e32 v46, 0x45800000, v41
	v_cndmask_b32_e64 v41, v41, v46, s[0:1]
	v_mul_f32_e32 v39, v39, v41
	v_mul_f32_e32 v39, 0x3e000000, v39
	v_cvt_pk_bf16_f32 v39, v39, s0
	global_store_short v[44:45], v39, off
	v_mul_f32_e32 v39, 0x4b800000, v40
	v_cndmask_b32_e32 v39, v40, v39, vcc
	v_rsq_f32_e32 v39, v39
	s_nop 0
	v_mul_f32_e32 v40, 0x45800000, v39
	v_cndmask_b32_e32 v39, v39, v40, vcc
	v_mul_f32_e32 v38, v38, v39
	v_cvt_pk_bf16_f32 v40, v38, s0
	v_lshl_add_u64 v[38:39], s[80:81], 0, v[42:43]
	global_store_short v[38:39], v40, off
	v_cvt_pk_bf16_f32 v40, v48, s0
	v_lshl_add_u64 v[38:39], s[82:83], 0, v[42:43]
	global_store_short v[38:39], v40, off
	s_and_saveexec_b64 s[0:1], s[38:39]
	s_cbranch_execz .LBB0_1032
	s_waitcnt vmcnt(48)
	v_lshlrev_b32_e32 v37, 16, v37
	v_mul_f32_e32 v37, 0xbfb8aa3b, v37
	v_exp_f32_e32 v37, v37
	s_waitcnt vmcnt(47)
	v_lshlrev_b32_e32 v40, 16, v36
	v_mad_i64_i32 v[12:13], s[2:3], s30, v199, v[12:13]
	v_add_f32_e32 v37, 1.0, v37
	v_div_scale_f32 v38, s[2:3], v37, v37, 1.0
	v_rcp_f32_e32 v39, v38
	v_div_scale_f32 v36, vcc, 1.0, v37, 1.0
	s_mov_b32 s2, 0x41a00000
	v_fma_f32 v41, -v38, v39, 1.0
	v_fmac_f32_e32 v39, v41, v39
	v_mul_f32_e32 v41, v36, v39
	v_fma_f32 v42, -v38, v41, v36
	v_fmac_f32_e32 v41, v42, v39
	v_fma_f32 v36, -v38, v41, v36
	v_div_fmas_f32 v36, v36, v39, v41
	v_div_fixup_f32 v38, v36, v37, 1.0
	v_lshl_add_u64 v[36:37], v[12:13], 2, s[84:85]
	global_store_dword v[36:37], v38, off
	v_add_f32_e32 v36, v24, v40
	v_cmp_nlt_f32_e32 vcc, s2, v36
	s_and_saveexec_b64 s[2:3], vcc
	s_cbranch_execz .LBB0_1031
	v_mul_f32_e32 v36, 0x3fb8aa3b, v36
	v_exp_f32_e32 v50, v36
	s_mov_b32 s4, 0x3f2aaaab
	v_add_f32_e32 v38, 1.0, v50
	v_frexp_mant_f32_e32 v40, v38
	v_cvt_f64_f32_e32 v[36:37], v38
	v_frexp_exp_i32_f64_e32 v36, v[36:37]
	v_cmp_gt_f32_e32 vcc, s4, v40
	v_add_f32_e32 v39, -1.0, v38
	v_sub_f32_e32 v41, v39, v38
	v_subbrev_co_u32_e32 v44, vcc, 0, v36, vcc
	v_sub_u32_e32 v36, 0, v44
	v_sub_f32_e32 v39, v50, v39
	v_add_f32_e32 v41, 1.0, v41
	v_ldexp_f32 v37, v38, v36
	v_add_f32_e32 v39, v39, v41
	v_add_f32_e32 v38, -1.0, v37
	v_add_f32_e32 v40, 1.0, v37
	v_ldexp_f32 v36, v39, v36
	v_add_f32_e32 v39, 1.0, v38
	v_add_f32_e32 v41, -1.0, v40
	v_sub_f32_e32 v39, v37, v39
	v_sub_f32_e32 v37, v37, v41
	v_add_f32_e32 v39, v36, v39
	v_add_f32_e32 v36, v36, v37
	v_add_f32_e32 v45, v40, v36
	v_rcp_f32_e32 v47, v45
	v_sub_f32_e32 v37, v45, v40
	v_sub_f32_e32 v46, v36, v37
	v_add_f32_e32 v37, v38, v39
	v_mul_f32_e32 v49, v37, v47
	v_sub_f32_e32 v36, v37, v38
	v_mul_f32_e32 v38, v45, v49
	v_fma_f32 v40, v49, v45, -v38
	v_fmac_f32_e32 v40, v49, v46
	v_sub_f32_e32 v48, v39, v36
	v_add_f32_e32 v36, v38, v40
	v_sub_f32_e32 v39, v37, v36
	v_pk_add_f32 v[42:43], v[36:37], v[38:39] neg_lo:[0,1] neg_hi:[0,1]
	v_mov_b32_e32 v41, v36
	v_pk_add_f32 v[36:37], v[42:43], v[40:41] neg_lo:[0,1] neg_hi:[0,1]
	s_mov_b32 s4, 0x3f317218
	v_add_f32_e32 v37, v48, v37
	v_add_f32_e32 v36, v36, v37
	v_add_f32_e32 v37, v39, v36
	v_mul_f32_e32 v48, v47, v37
	v_mul_f32_e32 v38, v45, v48
	v_fma_f32 v40, v48, v45, -v38
	v_fmac_f32_e32 v40, v48, v46
	v_sub_f32_e32 v39, v39, v37
	v_add_f32_e32 v45, v36, v39
	v_add_f32_e32 v36, v38, v40
	v_sub_f32_e32 v39, v37, v36
	v_pk_add_f32 v[42:43], v[36:37], v[38:39] neg_lo:[0,1] neg_hi:[0,1]
	v_mov_b32_e32 v41, v36
	v_pk_add_f32 v[36:37], v[42:43], v[40:41] neg_lo:[0,1] neg_hi:[0,1]
	v_cmp_neq_f32_e32 vcc, s36, v50
	v_add_f32_e32 v37, v45, v37
	v_add_f32_e32 v36, v36, v37
	v_add_f32_e32 v37, v49, v48
	v_add_f32_e32 v36, v39, v36
	v_sub_f32_e32 v38, v37, v49
	v_mul_f32_e32 v36, v47, v36
	v_sub_f32_e32 v38, v48, v38
	v_add_f32_e32 v38, v38, v36
	v_add_f32_e32 v40, v37, v38
	v_mul_f32_e32 v41, v40, v40
	v_fmamk_f32 v36, v41, 0x3e9b6dac, v172
	v_fmaak_f32 v143, v41, v36, 0x3f2aaada
	v_cvt_f32_i32_e32 v36, v44
	v_sub_f32_e32 v37, v40, v37
	v_sub_f32_e32 v37, v38, v37
	v_ldexp_f32 v42, v37, 1
	v_mul_f32_e32 v37, v40, v41
	v_ldexp_f32 v39, v40, 1
	v_pk_mul_f32 v[40:41], v[36:37], v[142:143]
	s_nop 0
	v_fma_f32 v38, v36, s4, -v40
	v_fmac_f32_e32 v38, 0xb102e308, v36
	v_pk_add_f32 v[36:37], v[40:41], v[38:39]
	s_mov_b32 s4, 0x33800000
	v_sub_f32_e32 v39, v37, v39
	v_sub_f32_e32 v39, v41, v39
	v_add_f32_e32 v43, v42, v39
	v_mov_b32_e32 v42, v40
	v_pk_add_f32 v[40:41], v[36:37], v[40:41] neg_lo:[0,1] neg_hi:[0,1]
	v_pk_add_f32 v[44:45], v[36:37], v[42:43]
	v_mov_b32_e32 v39, v36
	v_mov_b32_e32 v41, v45
	v_pk_add_f32 v[46:47], v[38:39], v[40:41] neg_lo:[0,1] neg_hi:[0,1]
	v_pk_add_f32 v[38:39], v[38:39], v[40:41]
	v_mov_b32_e32 v42, v43
	v_pk_add_f32 v[40:41], v[38:39], v[36:37] op_sel:[1,0] op_sel_hi:[0,1] neg_lo:[0,1] neg_hi:[0,1]
	v_pk_add_f32 v[48:49], v[44:45], v[40:41] op_sel_hi:[1,0] neg_lo:[0,1] neg_hi:[0,1]
	v_mov_b32_e32 v44, v45
	v_mov_b32_e32 v45, v39
	v_pk_mov_b32 v[40:41], v[36:37], v[40:41] op_sel:[1,0]
	v_mov_b32_e32 v43, v36
	v_pk_add_f32 v[40:41], v[44:45], v[40:41] neg_lo:[0,1] neg_hi:[0,1]
	v_mov_b32_e32 v48, v46
	v_pk_add_f32 v[36:37], v[42:43], v[40:41] neg_lo:[0,1] neg_hi:[0,1]
	v_mov_b32_e32 v47, v39
	v_pk_add_f32 v[40:41], v[48:49], v[36:37]
	s_nop 0
	v_pk_add_f32 v[42:43], v[40:41], v[40:41] op_sel:[0,1] op_sel_hi:[1,0]
	s_nop 0
	v_pk_add_f32 v[38:39], v[38:39], v[42:43] op_sel:[1,0] op_sel_hi:[0,1]
	v_mov_b32_e32 v41, v38
	v_pk_add_f32 v[44:45], v[40:41], v[46:47] neg_lo:[0,1] neg_hi:[0,1]
	v_mov_b32_e32 v37, v42
	v_sub_f32_e32 v39, v40, v44
	v_pk_add_f32 v[36:37], v[36:37], v[44:45] neg_lo:[0,1] neg_hi:[0,1]
	v_sub_f32_e32 v39, v46, v39
	v_add_f32_e32 v36, v36, v39
	v_add_f32_e32 v36, v36, v37
	v_add_f32_e32 v36, v38, v36
	v_cndmask_b32_e32 v36, v185, v36, vcc
	v_cmp_ngt_f32_e32 vcc, -1.0, v50
	s_nop 1
	v_cndmask_b32_e32 v36, v196, v36, vcc
	v_cmp_neq_f32_e32 vcc, -1.0, v50
	s_nop 1
	v_cndmask_b32_e32 v36, v197, v36, vcc
	v_cmp_lt_f32_e64 vcc, |v50|, s4
	s_nop 1
	v_cndmask_b32_e32 v36, v36, v50, vcc

.LBB0_1032:
	s_or_b64 exec, exec, s[0:1]
	v_lshlrev_b32_e32 v12, 16, v35
	v_cndmask_b32_e64 v13, 0, v12, s[40:41]
	v_lshlrev_b32_e32 v12, 16, v34
	v_mul_f32_e32 v15, v21, v15
	v_cndmask_b32_e64 v12, 0, v12, s[40:41]
	v_fmac_f32_e32 v15, v20, v14
	v_fmac_f32_e32 v15, v22, v12
	v_mul_f32_e32 v12, 0xbfb8aa3b, v15
	v_exp_f32_e32 v14, v12
	v_lshlrev_b32_e32 v12, 16, v33
	v_mul_f32_e32 v11, v16, v11
	v_mul_f32_e32 v9, v17, v9
	v_add_f32_e32 v14, 1.0, v14
	v_mul_f32_e32 v10, v18, v10
	v_mul_f32_e32 v8, v19, v8
	v_cndmask_b32_e64 v12, 0, v12, s[40:41]
	v_div_scale_f32 v33, s[0:1], v14, v14, v15
	v_pk_add_f32 v[8:9], v[10:11], v[8:9]
	v_rcp_f32_e32 v34, v33
	v_pk_fma_f32 v[8:9], v[2:3], v[12:13], v[8:9]
	v_fma_f32 v35, -v33, v34, 1.0
	v_mul_f32_e32 v10, 0xbfb8aa3b, v9
	v_exp_f32_e32 v11, v10
	v_mul_f32_e32 v10, 0xbfb8aa3b, v8
	v_exp_f32_e32 v10, v10
	v_fmac_f32_e32 v34, v35, v34
	v_div_scale_f32 v35, vcc, v15, v14, v15
	v_mul_f32_e32 v12, v35, v34
	v_fma_f32 v13, -v33, v12, v35
	v_pk_add_f32 v[10:11], v[10:11], 1.0 op_sel_hi:[1,0]
	v_fmac_f32_e32 v12, v13, v34
	v_div_scale_f32 v13, s[0:1], v11, v11, v9
	s_waitcnt vmcnt(47)
	v_rcp_f32_e32 v36, v13
	v_fma_f32 v33, -v33, v12, v35
	v_div_fmas_f32 v33, v33, v34, v12
	v_div_fixup_f32 v33, v33, v14, v15
	v_fma_f32 v12, -v13, v36, 1.0
	v_fmac_f32_e32 v36, v12, v36
	v_div_scale_f32 v12, vcc, v9, v11, v9
	v_mul_f32_e32 v34, v12, v36
	v_fma_f32 v35, -v13, v34, v12
	v_fmac_f32_e32 v34, v35, v36
	v_fma_f32 v12, -v13, v34, v12
	v_div_scale_f32 v13, s[0:1], v10, v10, v8
	v_rcp_f32_e32 v35, v13
	v_div_fmas_f32 v12, v12, v36, v34
	v_div_fixup_f32 v11, v12, v11, v9
	s_lshl_b64 s[0:1], s[34:35], 8
	v_fma_f32 v9, -v13, v35, 1.0
	v_fmac_f32_e32 v35, v9, v35
	v_div_scale_f32 v9, vcc, v8, v10, v8
	v_mul_f32_e32 v12, v9, v35
	v_fma_f32 v34, -v13, v12, v9
	v_fmac_f32_e32 v12, v34, v35
	v_fma_f32 v9, -v13, v12, v9
	v_div_fmas_f32 v9, v9, v35, v12
	v_div_fixup_f32 v10, v9, v10, v8
	v_pk_mul_f32 v[8:9], v[10:11], v[10:11]
	v_cmp_gt_u32_e64 s[98:99], 32, v176
	v_mov_b32_e32 v12, v8
	v_mov_b32_e32 v13, v9
	s_nop 1
	v_permlane32_swap_b32_e32 v12, v8
	v_permlane32_swap_b32_e32 v13, v9
	v_cndmask_b32_e64 v12, v12, v8, s[98:99]
	v_cndmask_b32_e64 v13, v13, v9, s[98:99]
	v_pk_fma_f32 v[8:9], v[10:11], v[10:11], v[12:13]
	v_mov_b32_e32 v12, v8
	v_mov_b32_e32 v13, v9
	s_nop 1
	v_permlane16_swap_b32_e32 v12, v8
	v_permlane16_swap_b32_e32 v13, v9
	v_pk_add_f32 v[8:9], v[8:9], v[12:13]
	s_nop 1
	v_add_f32_dpp v8, v8, v8 row_ror:8 row_mask:0xf bank_mask:0xf
	v_add_f32_dpp v9, v9, v9 row_ror:8 row_mask:0xf bank_mask:0xf
	s_nop 0
	v_add_f32_dpp v8, v8, v8 row_ror:4 row_mask:0xf bank_mask:0xf
	v_add_f32_dpp v9, v9, v9 row_ror:4 row_mask:0xf bank_mask:0xf
	s_nop 0
	v_add_f32_dpp v8, v8, v8 row_ror:2 row_mask:0xf bank_mask:0xf
	v_add_f32_dpp v9, v9, v9 row_ror:2 row_mask:0xf bank_mask:0xf
	s_nop 0
	v_add_f32_dpp v8, v8, v8 row_ror:1 row_mask:0xf bank_mask:0xf
	v_add_f32_dpp v9, v9, v9 row_ror:1 row_mask:0xf bank_mask:0xf
	s_nop 0
	v_pk_add_f32 v[12:13], v[8:9], s[22:23] op_sel_hi:[1,0]
	s_nop 0
	v_mul_f32_e32 v8, 0x4b800000, v13
	v_cmp_gt_f32_e32 vcc, s33, v13
	s_nop 1
	v_cndmask_b32_e32 v8, v13, v8, vcc
	v_rsq_f32_e32 v13, v8
	v_lshl_add_u64 v[8:9], s[0:1], 0, v[0:1]
	v_lshlrev_b64 v[14:15], 1, v[8:9]
	v_lshl_add_u64 v[34:35], s[78:79], 0, v[14:15]
	v_mul_f32_e32 v36, 0x45800000, v13
	v_cndmask_b32_e32 v13, v13, v36, vcc
	v_mul_f32_e32 v11, v11, v13
	v_mul_f32_e32 v13, 0x4b800000, v12
	v_cmp_gt_f32_e32 vcc, s33, v12
	v_mul_f32_e32 v11, 0x3e000000, v11
	v_cvt_pk_bf16_f32 v11, v11, s0
	v_cndmask_b32_e32 v12, v12, v13, vcc
	v_rsq_f32_e32 v12, v12
	global_store_short v[34:35], v11, off
	v_mul_f32_e32 v11, 0x45800000, v12
	v_cndmask_b32_e32 v11, v12, v11, vcc
	v_mul_f32_e32 v10, v10, v11
	v_cvt_pk_bf16_f32 v12, v10, s0
	v_lshl_add_u64 v[10:11], s[80:81], 0, v[14:15]
	global_store_short v[10:11], v12, off
	v_cvt_pk_bf16_f32 v12, v33, s0
	v_lshl_add_u64 v[10:11], s[82:83], 0, v[14:15]
	global_store_short v[10:11], v12, off
	s_and_saveexec_b64 s[0:1], s[38:39]
	s_cbranch_execz .LBB0_971
	s_waitcnt vmcnt(49)
	v_lshlrev_b32_e32 v10, 16, v32
	v_mul_f32_e32 v10, 0xbfb8aa3b, v10
	v_exp_f32_e32 v10, v10
	s_waitcnt vmcnt(48)
	v_lshlrev_b32_e32 v13, 16, v31
	v_mad_i64_i32 v[8:9], s[2:3], s34, v199, v[8:9]
	v_add_f32_e32 v10, 1.0, v10
	v_div_scale_f32 v11, s[2:3], v10, v10, 1.0
	v_rcp_f32_e32 v12, v11
	v_div_scale_f32 v14, vcc, 1.0, v10, 1.0
	s_mov_b32 s2, 0x41a00000
	v_fma_f32 v15, -v11, v12, 1.0
	v_fmac_f32_e32 v12, v15, v12
	v_mul_f32_e32 v15, v14, v12
	v_fma_f32 v31, -v11, v15, v14
	v_fmac_f32_e32 v15, v31, v12
	v_fma_f32 v11, -v11, v15, v14
	v_div_fmas_f32 v11, v11, v12, v15
	v_div_fixup_f32 v12, v11, v10, 1.0
	v_lshl_add_u64 v[10:11], v[8:9], 2, s[84:85]
	global_store_dword v[10:11], v12, off
	v_add_f32_e32 v10, v24, v13
	v_cmp_nlt_f32_e32 vcc, s2, v10
	s_and_saveexec_b64 s[2:3], vcc
	s_cbranch_execz .LBB0_970
	v_mul_f32_e32 v10, 0x3fb8aa3b, v10
	v_exp_f32_e32 v31, v10
	s_mov_b32 s4, 0x3f2aaaab
	v_add_f32_e32 v12, 1.0, v31
	v_frexp_mant_f32_e32 v14, v12
	v_cvt_f64_f32_e32 v[10:11], v12
	v_frexp_exp_i32_f64_e32 v10, v[10:11]
	v_cmp_gt_f32_e32 vcc, s4, v14
	v_add_f32_e32 v13, -1.0, v12
	v_sub_f32_e32 v15, v13, v12
	v_subbrev_co_u32_e32 v34, vcc, 0, v10, vcc
	v_sub_u32_e32 v10, 0, v34
	v_sub_f32_e32 v13, v31, v13
	v_add_f32_e32 v15, 1.0, v15
	v_ldexp_f32 v11, v12, v10
	v_add_f32_e32 v13, v13, v15
	v_add_f32_e32 v12, -1.0, v11
	v_add_f32_e32 v14, 1.0, v11
	v_ldexp_f32 v10, v13, v10
	v_add_f32_e32 v13, 1.0, v12
	v_add_f32_e32 v15, -1.0, v14
	v_sub_f32_e32 v13, v11, v13
	v_sub_f32_e32 v11, v11, v15
	v_add_f32_e32 v13, v10, v13
	v_add_f32_e32 v10, v10, v11
	v_add_f32_e32 v35, v14, v10
	v_rcp_f32_e32 v37, v35
	v_sub_f32_e32 v11, v35, v14
	v_sub_f32_e32 v36, v10, v11
	v_add_f32_e32 v11, v12, v13
	v_mul_f32_e32 v39, v11, v37
	v_sub_f32_e32 v10, v11, v12
	v_mul_f32_e32 v12, v35, v39
	v_fma_f32 v14, v39, v35, -v12
	v_fmac_f32_e32 v14, v39, v36
	v_sub_f32_e32 v38, v13, v10
	v_add_f32_e32 v10, v12, v14
	v_sub_f32_e32 v13, v11, v10
	v_pk_add_f32 v[32:33], v[10:11], v[12:13] neg_lo:[0,1] neg_hi:[0,1]
	v_mov_b32_e32 v15, v10
	v_pk_add_f32 v[10:11], v[32:33], v[14:15] neg_lo:[0,1] neg_hi:[0,1]
	s_mov_b32 s4, 0x3f317218
	v_add_f32_e32 v11, v38, v11
	v_add_f32_e32 v10, v10, v11
	v_add_f32_e32 v11, v13, v10
	v_mul_f32_e32 v38, v37, v11
	v_mul_f32_e32 v12, v35, v38
	v_fma_f32 v14, v38, v35, -v12
	v_fmac_f32_e32 v14, v38, v36
	v_sub_f32_e32 v13, v13, v11
	v_add_f32_e32 v35, v10, v13
	v_add_f32_e32 v10, v12, v14
	v_sub_f32_e32 v13, v11, v10
	v_pk_add_f32 v[32:33], v[10:11], v[12:13] neg_lo:[0,1] neg_hi:[0,1]
	v_mov_b32_e32 v15, v10
	v_pk_add_f32 v[10:11], v[32:33], v[14:15] neg_lo:[0,1] neg_hi:[0,1]
	v_cmp_neq_f32_e32 vcc, s36, v31
	v_add_f32_e32 v11, v35, v11
	v_add_f32_e32 v10, v10, v11
	v_add_f32_e32 v11, v39, v38
	v_add_f32_e32 v10, v13, v10
	v_sub_f32_e32 v12, v11, v39
	v_mul_f32_e32 v10, v37, v10
	v_sub_f32_e32 v12, v38, v12
	v_add_f32_e32 v12, v12, v10
	v_add_f32_e32 v14, v11, v12
	v_mul_f32_e32 v15, v14, v14
	v_fmamk_f32 v10, v15, 0x3e9b6dac, v172
	v_fmaak_f32 v143, v15, v10, 0x3f2aaada
	v_cvt_f32_i32_e32 v10, v34
	v_sub_f32_e32 v11, v14, v11
	v_sub_f32_e32 v11, v12, v11
	v_ldexp_f32 v32, v11, 1
	v_mul_f32_e32 v11, v14, v15
	v_ldexp_f32 v13, v14, 1
	v_pk_mul_f32 v[14:15], v[10:11], v[142:143]
	s_nop 0
	v_fma_f32 v12, v10, s4, -v14
	v_fmac_f32_e32 v12, 0xb102e308, v10
	v_pk_add_f32 v[10:11], v[14:15], v[12:13]
	s_mov_b32 s4, 0x33800000
	v_sub_f32_e32 v13, v11, v13
	v_sub_f32_e32 v13, v15, v13
	v_add_f32_e32 v33, v32, v13
	v_mov_b32_e32 v32, v14
	v_pk_add_f32 v[14:15], v[10:11], v[14:15] neg_lo:[0,1] neg_hi:[0,1]
	v_pk_add_f32 v[34:35], v[10:11], v[32:33]
	v_mov_b32_e32 v13, v10
	v_mov_b32_e32 v15, v35
	v_pk_add_f32 v[36:37], v[12:13], v[14:15] neg_lo:[0,1] neg_hi:[0,1]
	v_pk_add_f32 v[12:13], v[12:13], v[14:15]
	v_mov_b32_e32 v32, v33
	v_pk_add_f32 v[14:15], v[12:13], v[10:11] op_sel:[1,0] op_sel_hi:[0,1] neg_lo:[0,1] neg_hi:[0,1]
	v_pk_add_f32 v[38:39], v[34:35], v[14:15] op_sel_hi:[1,0] neg_lo:[0,1] neg_hi:[0,1]
	v_mov_b32_e32 v34, v35
	v_mov_b32_e32 v35, v13
	v_pk_mov_b32 v[14:15], v[10:11], v[14:15] op_sel:[1,0]
	v_mov_b32_e32 v33, v10
	v_pk_add_f32 v[14:15], v[34:35], v[14:15] neg_lo:[0,1] neg_hi:[0,1]
	v_mov_b32_e32 v38, v36
	v_pk_add_f32 v[10:11], v[32:33], v[14:15] neg_lo:[0,1] neg_hi:[0,1]
	v_mov_b32_e32 v37, v13
	v_pk_add_f32 v[14:15], v[38:39], v[10:11]
	s_nop 0
	v_pk_add_f32 v[32:33], v[14:15], v[14:15] op_sel:[0,1] op_sel_hi:[1,0]
	s_nop 0
	v_pk_add_f32 v[12:13], v[12:13], v[32:33] op_sel:[1,0] op_sel_hi:[0,1]
	v_mov_b32_e32 v15, v12
	v_pk_add_f32 v[34:35], v[14:15], v[36:37] neg_lo:[0,1] neg_hi:[0,1]
	v_mov_b32_e32 v11, v32
	v_sub_f32_e32 v13, v14, v34
	v_pk_add_f32 v[10:11], v[10:11], v[34:35] neg_lo:[0,1] neg_hi:[0,1]
	v_sub_f32_e32 v13, v36, v13
	v_add_f32_e32 v10, v10, v13
	v_add_f32_e32 v10, v10, v11
	v_add_f32_e32 v10, v12, v10
	v_cndmask_b32_e32 v10, v185, v10, vcc
	v_cmp_ngt_f32_e32 vcc, -1.0, v31
	s_nop 1
	v_cndmask_b32_e32 v10, v196, v10, vcc
	v_cmp_neq_f32_e32 vcc, -1.0, v31
	s_nop 1
	v_cndmask_b32_e32 v10, v197, v10, vcc
	v_cmp_lt_f32_e64 vcc, |v31|, s4
	s_nop 1
	v_cndmask_b32_e32 v10, v10, v31, vcc
	s_branch .LBB0_970

.LBB0_1056:
	v_mov_b32_e32 v0, v139
	v_cmp_lt_i32_e32 vcc, v179, v178
	v_ashrrev_i32_e32 v1, 5, v0
	v_and_b32_e32 v1, -2, v1
	v_add_u32_e32 v38, s11, v1
	v_lshlrev_b32_e32 v0, 2, v0
	v_ashrrev_i32_e32 v39, 31, v38
	s_waitcnt lgkmcnt(0)
	v_and_b32_e32 v2, 0xfc, v0
	v_lshlrev_b64 v[0:1], 12, v[38:39]
	v_lshl_add_u64 v[0:1], s[46:47], 0, v[0:1]
	v_lshlrev_b32_e32 v136, 1, v2
	v_lshl_add_u64 v[36:37], v[0:1], 0, v[136:137]
	global_load_dwordx2 v[42:43], v[36:37], off offset:2048
	global_load_dwordx2 v[44:45], v[36:37], off offset:2560
	global_load_dwordx2 v[46:47], v[36:37], off offset:3072
	global_load_dwordx2 v[48:49], v[36:37], off offset:3584
	s_waitcnt vmcnt(12)
	v_add_u32_e32 v34, 1, v38
	v_ashrrev_i32_e32 v35, 31, v34
	v_lshlrev_b64 v[0:1], 12, v[34:35]
	v_lshl_add_u64 v[0:1], s[46:47], 0, v[0:1]
	v_lshl_add_u64 v[32:33], v[0:1], 0, v[136:137]
	global_load_dwordx2 v[50:51], v[32:33], off offset:2048
	global_load_dwordx2 v[52:53], v[32:33], off offset:2560
	global_load_dwordx2 v[54:55], v[32:33], off offset:3072
	global_load_dwordx2 v[56:57], v[32:33], off offset:3584
	v_cndmask_b32_e32 v35, v176, v179, vcc
	v_cmp_lt_i32_e32 vcc, v180, v178
	v_lshlrev_b32_e32 v35, 2, v35
	v_lshlrev_b32_e32 v40, 2, v2
	v_cndmask_b32_e32 v39, v176, v180, vcc
	v_cmp_lt_i32_e32 vcc, v181, v178
	v_lshlrev_b32_e32 v39, 2, v39
	global_load_dwordx4 v[24:27], v40, s[4:5]
	global_load_dwordx4 v[28:31], v40, s[6:7]
	global_load_dwordx4 v[16:19], v40, s[4:5] offset:1024
	global_load_dwordx4 v[20:23], v40, s[6:7] offset:1024
	global_load_dwordx4 v[8:11], v40, s[4:5] offset:2048
	global_load_dwordx4 v[12:15], v40, s[6:7] offset:2048
	global_load_dwordx4 v[0:3], v40, s[4:5] offset:3072
	global_load_dwordx4 v[4:7], v40, s[6:7] offset:3072
	v_cndmask_b32_e32 v58, v176, v181, vcc
	v_cmp_lt_i32_e32 vcc, v182, v178
	v_lshlrev_b32_e32 v86, 2, v58
	v_mov_b32_e32 v41, v137
	v_cndmask_b32_e32 v58, v176, v182, vcc
	v_cmp_lt_i32_e32 vcc, v183, v178
	v_lshlrev_b32_e32 v87, 2, v58
	s_add_i32 s12, s12, s90
	v_cndmask_b32_e32 v58, v176, v183, vcc
	v_cmp_lt_i32_e32 vcc, v184, v178
	v_lshlrev_b32_e32 v88, 2, v58
	s_add_i32 s11, s11, s10
	v_cndmask_b32_e32 v58, v176, v184, vcc
	v_lshlrev_b32_e32 v89, 2, v58
	s_cmpk_gt_i32 s12, 0xbf
	s_waitcnt vmcnt(15)
	v_lshlrev_b32_e32 v68, 16, v42
	s_waitcnt vmcnt(14)
	v_lshlrev_b32_e32 v66, 16, v44
	s_waitcnt vmcnt(13)
	v_lshlrev_b32_e32 v62, 16, v46
	s_waitcnt vmcnt(12)
	v_lshlrev_b32_e32 v60, 16, v48
	v_and_b32_e32 v61, 0xffff0000, v48
	v_and_b32_e32 v63, 0xffff0000, v46
	v_lshlrev_b32_e32 v58, 16, v49
	v_and_b32_e32 v59, 0xffff0000, v49
	v_lshlrev_b32_e32 v48, 16, v47
	v_and_b32_e32 v49, 0xffff0000, v47
	v_mov_b32_e32 v46, v62
	v_mov_b32_e32 v47, v60
	v_mov_b32_e32 v64, v63
	v_mov_b32_e32 v65, v61
	v_pk_add_f32 v[46:47], v[46:47], v[64:65]
	v_mov_b32_e32 v64, v48
	v_mov_b32_e32 v65, v58
	v_pk_add_f32 v[46:47], v[46:47], v[64:65]
	v_mov_b32_e32 v64, v49
	v_mov_b32_e32 v65, v59
	v_and_b32_e32 v67, 0xffff0000, v44
	v_and_b32_e32 v69, 0xffff0000, v42
	v_pk_add_f32 v[46:47], v[46:47], v[64:65]
	v_lshlrev_b32_e32 v64, 16, v45
	v_and_b32_e32 v65, 0xffff0000, v45
	v_lshlrev_b32_e32 v44, 16, v43
	v_and_b32_e32 v45, 0xffff0000, v43
	v_mov_b32_e32 v42, v68
	v_mov_b32_e32 v43, v66
	v_mov_b32_e32 v70, v69
	v_mov_b32_e32 v71, v67
	v_pk_add_f32 v[42:43], v[42:43], v[70:71]
	v_mov_b32_e32 v70, v44
	v_mov_b32_e32 v71, v64
	v_pk_add_f32 v[42:43], v[42:43], v[70:71]
	v_mov_b32_e32 v70, v45
	v_mov_b32_e32 v71, v65
	s_waitcnt vmcnt(8)
	v_lshlrev_b32_e32 v72, 16, v56
	v_and_b32_e32 v73, 0xffff0000, v56
	v_lshlrev_b32_e32 v74, 16, v54
	v_and_b32_e32 v75, 0xffff0000, v54
	v_pk_add_f32 v[42:43], v[42:43], v[70:71]
	v_lshlrev_b32_e32 v70, 16, v57
	v_and_b32_e32 v71, 0xffff0000, v57
	v_lshlrev_b32_e32 v56, 16, v55
	v_and_b32_e32 v57, 0xffff0000, v55
	v_mov_b32_e32 v54, v74
	v_mov_b32_e32 v55, v72
	v_mov_b32_e32 v76, v75
	v_mov_b32_e32 v77, v73
	v_pk_add_f32 v[54:55], v[54:55], v[76:77]
	v_mov_b32_e32 v76, v56
	v_mov_b32_e32 v77, v70
	v_pk_add_f32 v[54:55], v[54:55], v[76:77]
	v_mov_b32_e32 v76, v57
	v_mov_b32_e32 v77, v71
	v_lshlrev_b32_e32 v78, 16, v52
	v_and_b32_e32 v79, 0xffff0000, v52
	v_lshlrev_b32_e32 v80, 16, v50
	v_and_b32_e32 v81, 0xffff0000, v50
	v_pk_add_f32 v[54:55], v[54:55], v[76:77]
	v_lshlrev_b32_e32 v76, 16, v53
	v_and_b32_e32 v77, 0xffff0000, v53
	v_lshlrev_b32_e32 v52, 16, v51
	v_and_b32_e32 v53, 0xffff0000, v51
	v_mov_b32_e32 v50, v80
	v_mov_b32_e32 v51, v78
	v_mov_b32_e32 v82, v81
	v_mov_b32_e32 v83, v79
	v_pk_add_f32 v[50:51], v[50:51], v[82:83]
	v_mov_b32_e32 v82, v52
	v_mov_b32_e32 v83, v76
	v_pk_add_f32 v[50:51], v[50:51], v[82:83]
	v_mov_b32_e32 v82, v53
	v_mov_b32_e32 v83, v77
	v_pk_add_f32 v[50:51], v[50:51], v[82:83]
	v_add_f32_e32 v42, 0, v42
	v_add_f32_e32 v50, 0, v50
	v_add_f32_e32 v42, v42, v43
	v_add_f32_e32 v50, v50, v51
	v_add_f32_e32 v42, v42, v46
	v_add_f32_e32 v50, v50, v54
	v_add_f32_e32 v42, v42, v47
	v_add_f32_e32 v50, v50, v55
	ds_bpermute_b32 v43, v35, v42
	ds_bpermute_b32 v51, v35, v50
	s_waitcnt lgkmcnt(1)
	v_add_f32_e32 v42, v42, v43
	s_waitcnt lgkmcnt(0)
	v_add_f32_e32 v50, v50, v51
	ds_bpermute_b32 v43, v39, v42
	ds_bpermute_b32 v51, v39, v50
	s_waitcnt lgkmcnt(1)
	v_add_f32_e32 v42, v42, v43
	s_waitcnt lgkmcnt(0)
	v_add_f32_e32 v50, v50, v51
	ds_bpermute_b32 v43, v86, v42
	ds_bpermute_b32 v51, v86, v50
	s_waitcnt lgkmcnt(1)
	v_add_f32_e32 v42, v42, v43
	s_waitcnt lgkmcnt(0)
	v_add_f32_e32 v50, v50, v51
	ds_bpermute_b32 v43, v87, v42
	ds_bpermute_b32 v51, v87, v50
	s_waitcnt lgkmcnt(1)
	v_add_f32_e32 v42, v42, v43
	s_waitcnt lgkmcnt(0)
	v_add_f32_e32 v50, v50, v51
	ds_bpermute_b32 v43, v88, v42
	ds_bpermute_b32 v51, v88, v50
	s_waitcnt lgkmcnt(1)
	v_add_f32_e32 v42, v42, v43
	s_waitcnt lgkmcnt(0)
	v_add_f32_e32 v50, v50, v51
	ds_bpermute_b32 v43, v89, v42
	ds_bpermute_b32 v51, v89, v50
	s_waitcnt lgkmcnt(1)
	v_add_f32_e32 v42, v42, v43
	s_waitcnt lgkmcnt(0)
	v_add_f32_e32 v50, v50, v51
	v_mul_f32_e32 v42, 0x3a800000, v42
	v_mul_f32_e32 v50, 0x3a800000, v50
	v_pk_add_f32 v[46:47], v[68:69], v[42:43] op_sel_hi:[1,0] neg_lo:[0,1] neg_hi:[0,1]
	v_pk_add_f32 v[80:81], v[80:81], v[50:51] op_sel_hi:[1,0] neg_lo:[0,1] neg_hi:[0,1]
	v_mov_b32_e32 v83, v47
	v_mov_b32_e32 v82, v81
	v_mov_b32_e32 v54, v80
	v_mov_b32_e32 v55, v46
	v_pk_mul_f32 v[82:83], v[82:83], v[82:83]
	v_pk_add_f32 v[44:45], v[44:45], v[42:43] op_sel_hi:[1,0] neg_lo:[0,1] neg_hi:[0,1]
	v_pk_fma_f32 v[54:55], v[54:55], v[54:55], v[82:83]
	v_pk_add_f32 v[82:83], v[52:53], v[50:51] op_sel_hi:[1,0] neg_lo:[0,1] neg_hi:[0,1]
	v_mov_b32_e32 v53, v44
	v_mov_b32_e32 v52, v82
	v_pk_add_f32 v[66:67], v[66:67], v[42:43] op_sel_hi:[1,0] neg_lo:[0,1] neg_hi:[0,1]
	v_pk_add_f32 v[78:79], v[78:79], v[50:51] op_sel_hi:[1,0] neg_lo:[0,1] neg_hi:[0,1]
	v_pk_fma_f32 v[52:53], v[52:53], v[52:53], v[54:55]
	v_mov_b32_e32 v54, v83
	v_mov_b32_e32 v55, v45
	v_pk_fma_f32 v[52:53], v[54:55], v[54:55], v[52:53]
	v_mov_b32_e32 v54, v78
	v_mov_b32_e32 v55, v66
	v_pk_add_f32 v[64:65], v[64:65], v[42:43] op_sel_hi:[1,0] neg_lo:[0,1] neg_hi:[0,1]
	v_pk_add_f32 v[76:77], v[76:77], v[50:51] op_sel_hi:[1,0] neg_lo:[0,1] neg_hi:[0,1]
	v_pk_fma_f32 v[52:53], v[54:55], v[54:55], v[52:53]
	v_mov_b32_e32 v54, v79
	v_mov_b32_e32 v55, v67
	v_pk_fma_f32 v[52:53], v[54:55], v[54:55], v[52:53]
	v_mov_b32_e32 v54, v76
	v_mov_b32_e32 v55, v64
	v_pk_add_f32 v[62:63], v[62:63], v[42:43] op_sel_hi:[1,0] neg_lo:[0,1] neg_hi:[0,1]
	v_pk_add_f32 v[74:75], v[74:75], v[50:51] op_sel_hi:[1,0] neg_lo:[0,1] neg_hi:[0,1]
	v_pk_fma_f32 v[52:53], v[54:55], v[54:55], v[52:53]
	v_mov_b32_e32 v54, v77
	v_mov_b32_e32 v55, v65
	v_pk_fma_f32 v[52:53], v[54:55], v[54:55], v[52:53]
	v_mov_b32_e32 v54, v74
	v_mov_b32_e32 v55, v62
	v_pk_add_f32 v[68:69], v[48:49], v[42:43] op_sel_hi:[1,0] neg_lo:[0,1] neg_hi:[0,1]
	v_pk_add_f32 v[84:85], v[56:57], v[50:51] op_sel_hi:[1,0] neg_lo:[0,1] neg_hi:[0,1]
	v_pk_fma_f32 v[52:53], v[54:55], v[54:55], v[52:53]
	v_mov_b32_e32 v54, v75
	v_mov_b32_e32 v55, v63
	v_pk_add_f32 v[60:61], v[60:61], v[42:43] op_sel_hi:[1,0] neg_lo:[0,1] neg_hi:[0,1]
	v_pk_add_f32 v[72:73], v[72:73], v[50:51] op_sel_hi:[1,0] neg_lo:[0,1] neg_hi:[0,1]
	v_pk_fma_f32 v[52:53], v[54:55], v[54:55], v[52:53]
	v_mov_b32_e32 v54, v84
	v_mov_b32_e32 v55, v68
	v_pk_mul_f32 v[48:49], v[60:61], v[60:61]
	v_pk_mul_f32 v[56:57], v[72:73], v[72:73]
	v_pk_fma_f32 v[52:53], v[54:55], v[54:55], v[52:53]
	v_mov_b32_e32 v54, v85
	v_mov_b32_e32 v55, v69
	v_pk_add_f32 v[42:43], v[58:59], v[42:43] op_sel_hi:[1,0] neg_lo:[0,1] neg_hi:[0,1]
	v_pk_fma_f32 v[52:53], v[54:55], v[54:55], v[52:53]
	v_mov_b32_e32 v54, v56
	v_mov_b32_e32 v55, v48
	v_pk_add_f32 v[70:71], v[70:71], v[50:51] op_sel_hi:[1,0] neg_lo:[0,1] neg_hi:[0,1]
	v_pk_mul_f32 v[58:59], v[42:43], v[42:43]
	v_pk_add_f32 v[52:53], v[54:55], v[52:53]
	v_pk_mul_f32 v[50:51], v[70:71], v[70:71]
	v_mov_b32_e32 v48, v57
	v_pk_add_f32 v[48:49], v[48:49], v[52:53]
	v_mov_b32_e32 v52, v50
	v_mov_b32_e32 v53, v58
	v_pk_add_f32 v[48:49], v[52:53], v[48:49]
	v_mov_b32_e32 v58, v51
	v_pk_add_f32 v[48:49], v[58:59], v[48:49]
	v_mov_b32_e32 v50, v48
	v_mov_b32_e32 v51, v49
	s_nop 1
	v_permlane32_swap_b32_e32 v50, v48
	v_permlane32_swap_b32_e32 v51, v49
	v_pk_add_f32 v[48:49], v[48:49], v[50:51]
	v_mov_b32_e32 v50, v48
	v_mov_b32_e32 v51, v49
	s_nop 1
	v_permlane16_swap_b32_e32 v50, v48
	v_permlane16_swap_b32_e32 v51, v49
	v_pk_add_f32 v[48:49], v[48:49], v[50:51]
	s_nop 1
	v_add_f32_dpp v48, v48, v48 row_ror:8 row_mask:0xf bank_mask:0xf
	v_add_f32_dpp v49, v49, v49 row_ror:8 row_mask:0xf bank_mask:0xf
	s_nop 0
	v_add_f32_dpp v48, v48, v48 row_ror:4 row_mask:0xf bank_mask:0xf
	v_add_f32_dpp v49, v49, v49 row_ror:4 row_mask:0xf bank_mask:0xf
	s_nop 0
	v_add_f32_dpp v48, v48, v48 row_ror:2 row_mask:0xf bank_mask:0xf
	v_add_f32_dpp v49, v49, v49 row_ror:2 row_mask:0xf bank_mask:0xf
	s_nop 0
	v_add_f32_dpp v48, v48, v48 row_ror:1 row_mask:0xf bank_mask:0xf
	v_add_f32_dpp v49, v49, v49 row_ror:1 row_mask:0xf bank_mask:0xf
	s_nop 0
	v_pk_fma_f32 v[58:59], v[48:49], s[24:25], v[138:139] op_sel_hi:[1,0,0]
	s_nop 0
	v_mul_f32_e32 v35, 0x4b800000, v59
	v_cmp_gt_f32_e64 s[0:1], s33, v59
	v_cmp_gt_f32_e32 vcc, s33, v58
	s_nop 0
	v_cndmask_b32_e64 v35, v59, v35, s[0:1]
	v_rsq_f32_e32 v35, v35
	s_nop 0
	v_mul_f32_e32 v39, 0x45800000, v35
	v_cndmask_b32_e64 v86, v35, v39, s[0:1]
	v_mul_f32_e32 v35, 0x4b800000, v58
	v_cndmask_b32_e32 v35, v58, v35, vcc
	v_rsq_f32_e32 v35, v35
	v_pk_mul_f32 v[44:45], v[44:45], v[86:87] op_sel_hi:[1,0]
	v_pk_mul_f32 v[46:47], v[46:47], v[86:87] op_sel_hi:[1,0]
	s_waitcnt vmcnt(6)
	v_pk_fma_f32 v[54:55], v[26:27], v[44:45], v[30:31]
	v_pk_mul_f32 v[44:45], v[66:67], v[86:87] op_sel_hi:[1,0]
	v_mul_f32_e32 v39, 0x45800000, v35
	s_waitcnt vmcnt(4)
	v_pk_fma_f32 v[52:53], v[16:17], v[44:45], v[20:21]
	v_pk_mul_f32 v[44:45], v[64:65], v[86:87] op_sel_hi:[1,0]
	v_cndmask_b32_e32 v58, v35, v39, vcc
	v_pk_fma_f32 v[50:51], v[18:19], v[44:45], v[22:23]
	v_pk_mul_f32 v[44:45], v[62:63], v[86:87] op_sel_hi:[1,0]
	v_pk_fma_f32 v[56:57], v[24:25], v[46:47], v[28:29]
	s_waitcnt vmcnt(2)
	v_pk_fma_f32 v[48:49], v[8:9], v[44:45], v[12:13]
	v_pk_mul_f32 v[44:45], v[68:69], v[86:87] op_sel_hi:[1,0]
	v_pk_mul_f32 v[42:43], v[42:43], v[86:87] op_sel_hi:[1,0]
	v_pk_fma_f32 v[46:47], v[10:11], v[44:45], v[14:15]
	v_pk_mul_f32 v[44:45], v[60:61], v[86:87] op_sel_hi:[1,0]
	v_pk_mul_f32 v[60:61], v[80:81], v[58:59] op_sel_hi:[1,0]
	s_waitcnt vmcnt(0)
	v_pk_fma_f32 v[44:45], v[0:1], v[44:45], v[4:5]
	v_pk_fma_f32 v[24:25], v[24:25], v[60:61], v[28:29]
	v_pk_mul_f32 v[28:29], v[82:83], v[58:59] op_sel_hi:[1,0]
	v_pk_fma_f32 v[42:43], v[2:3], v[42:43], v[6:7]
	v_pk_fma_f32 v[26:27], v[26:27], v[28:29], v[30:31]
	v_pk_mul_f32 v[28:29], v[78:79], v[58:59] op_sel_hi:[1,0]
	v_cmp_lt_i32_e32 vcc, s17, v38
	v_pk_fma_f32 v[16:17], v[16:17], v[28:29], v[20:21]
	v_pk_mul_f32 v[20:21], v[76:77], v[58:59] op_sel_hi:[1,0]
	s_nop 0
	v_pk_fma_f32 v[18:19], v[18:19], v[20:21], v[22:23]
	v_pk_mul_f32 v[20:21], v[74:75], v[58:59] op_sel_hi:[1,0]
	s_nop 0
	v_pk_fma_f32 v[8:9], v[8:9], v[20:21], v[12:13]
	v_pk_mul_f32 v[12:13], v[84:85], v[58:59] op_sel_hi:[1,0]
	s_nop 0
	v_pk_fma_f32 v[10:11], v[10:11], v[12:13], v[14:15]
	v_pk_mul_f32 v[12:13], v[72:73], v[58:59] op_sel_hi:[1,0]
	s_nop 0
	v_pk_fma_f32 v[0:1], v[0:1], v[12:13], v[4:5]
	v_pk_mul_f32 v[4:5], v[70:71], v[58:59] op_sel_hi:[1,0]
	s_nop 0
	v_pk_fma_f32 v[2:3], v[2:3], v[4:5], v[6:7]
	v_add_u32_e32 v4, 0xfffff000, v38
	v_lshrrev_b32_e32 v4, 12, v4
	v_add_u32_e32 v4, 1, v4
	v_cndmask_b32_e32 v4, 0, v4, vcc
	v_mov_b32_e32 v5, v137
	v_lshl_add_u64 v[4:5], v[4:5], 0, s[8:9]
	v_mov_b64_e32 v[6:7], s[56:57]
	v_mad_u64_u32 v[6:7], s[0:1], v4, s16, v[6:7]
	v_mad_i32_i24 v7, v5, s16, v7
	v_lshl_add_u64 v[40:41], v[6:7], 0, v[40:41]
	global_load_dwordx4 v[4:7], v[40:41], off
	v_add_co_u32_e32 v12, vcc, s13, v40
	v_lshl_add_u64 v[70:71], v[40:41], 0, s[18:19]
	s_nop 0
	v_addc_co_u32_e32 v13, vcc, 0, v41, vcc
	global_load_dwordx4 v[12:15], v[12:13], off
	s_nop 0
	global_load_dwordx4 v[20:23], v[40:41], off offset:1024
	global_load_dwordx4 v[28:31], v[70:71], off offset:1024
	global_load_dwordx4 v[58:61], v[40:41], off offset:2048
	global_load_dwordx4 v[62:65], v[70:71], off offset:2048
	global_load_dwordx4 v[66:69], v[40:41], off offset:3072
	s_nop 0
	global_load_dwordx4 v[70:73], v[70:71], off offset:3072
	v_cvt_pk_bf16_f32 v40, v56, v57
	v_cvt_pk_bf16_f32 v41, v54, v55
	global_store_dwordx2 v[36:37], v[40:41], off
	s_waitcnt vmcnt(7)
	v_pk_add_f32 v[12:13], v[12:13], 1.0 op_sel_hi:[1,0]
	v_pk_add_f32 v[14:15], v[14:15], 1.0 op_sel_hi:[1,0]
	v_pk_fma_f32 v[40:41], v[12:13], v[56:57], v[4:5]
	v_pk_fma_f32 v[54:55], v[14:15], v[54:55], v[6:7]
	v_cvt_pk_bf16_f32 v40, v40, v41
	v_cvt_pk_bf16_f32 v41, v54, v55
	v_mov_b64_e32 v[54:55], s[62:63]
	v_mad_i64_i32 v[38:39], s[0:1], v38, s36, v[54:55]
	v_lshl_add_u64 v[38:39], v[38:39], 0, v[136:137]
	global_store_dwordx2 v[38:39], v[40:41], off
	v_cvt_pk_bf16_f32 v40, v52, v53
	v_cvt_pk_bf16_f32 v41, v50, v51
	s_waitcnt vmcnt(6)
	v_pk_add_f32 v[28:29], v[28:29], 1.0 op_sel_hi:[1,0]
	v_pk_add_f32 v[30:31], v[30:31], 1.0 op_sel_hi:[1,0]
	global_store_dwordx2 v[36:37], v[40:41], off offset:512
	v_pk_fma_f32 v[40:41], v[28:29], v[52:53], v[20:21]
	v_pk_fma_f32 v[50:51], v[30:31], v[50:51], v[22:23]
	v_cvt_pk_bf16_f32 v40, v40, v41
	v_cvt_pk_bf16_f32 v41, v50, v51
	global_store_dwordx2 v[38:39], v[40:41], off offset:512
	v_cvt_pk_bf16_f32 v40, v48, v49
	v_cvt_pk_bf16_f32 v41, v46, v47
	global_store_dwordx2 v[36:37], v[40:41], off offset:1024
	s_waitcnt vmcnt(7)
	v_pk_add_f32 v[40:41], v[62:63], 1.0 op_sel_hi:[1,0]
	v_pk_add_f32 v[50:51], v[64:65], 1.0 op_sel_hi:[1,0]
	v_pk_fma_f32 v[48:49], v[40:41], v[48:49], v[58:59]
	v_pk_fma_f32 v[46:47], v[50:51], v[46:47], v[60:61]
	v_cvt_pk_bf16_f32 v48, v48, v49
	v_cvt_pk_bf16_f32 v49, v46, v47
	v_cvt_pk_bf16_f32 v46, v44, v45
	v_cvt_pk_bf16_f32 v47, v42, v43
	global_store_dwordx2 v[38:39], v[48:49], off offset:1024
	global_store_dwordx2 v[36:37], v[46:47], off offset:1536
	s_waitcnt vmcnt(7)
	v_pk_add_f32 v[36:37], v[70:71], 1.0 op_sel_hi:[1,0]
	v_pk_add_f32 v[46:47], v[72:73], 1.0 op_sel_hi:[1,0]
	v_pk_fma_f32 v[44:45], v[36:37], v[44:45], v[66:67]
	v_pk_fma_f32 v[42:43], v[46:47], v[42:43], v[68:69]
	v_pk_fma_f32 v[4:5], v[12:13], v[24:25], v[4:5]
	v_pk_fma_f32 v[6:7], v[14:15], v[26:27], v[6:7]
	v_cvt_pk_bf16_f32 v44, v44, v45
	v_cvt_pk_bf16_f32 v45, v42, v43
	v_cvt_pk_bf16_f32 v4, v4, v5
	v_cvt_pk_bf16_f32 v5, v6, v7
	v_mad_i64_i32 v[6:7], s[0:1], v34, s36, v[54:55]
	global_store_dwordx2 v[38:39], v[44:45], off offset:1536
	v_cvt_pk_bf16_f32 v38, v24, v25
	v_cvt_pk_bf16_f32 v39, v26, v27
	v_lshl_add_u64 v[6:7], v[6:7], 0, v[136:137]
	global_store_dwordx2 v[32:33], v[38:39], off
	global_store_dwordx2 v[6:7], v[4:5], off
	v_cvt_pk_bf16_f32 v4, v16, v17
	v_cvt_pk_bf16_f32 v5, v18, v19
	global_store_dwordx2 v[32:33], v[4:5], off offset:512
	v_pk_fma_f32 v[4:5], v[28:29], v[16:17], v[20:21]
	v_pk_fma_f32 v[12:13], v[30:31], v[18:19], v[22:23]
	v_cvt_pk_bf16_f32 v4, v4, v5
	v_cvt_pk_bf16_f32 v5, v12, v13
	global_store_dwordx2 v[6:7], v[4:5], off offset:512
	v_cvt_pk_bf16_f32 v4, v8, v9
	v_cvt_pk_bf16_f32 v5, v10, v11
	global_store_dwordx2 v[32:33], v[4:5], off offset:1024
	v_pk_fma_f32 v[4:5], v[40:41], v[8:9], v[58:59]
	v_pk_fma_f32 v[8:9], v[50:51], v[10:11], v[60:61]
	v_cvt_pk_bf16_f32 v4, v4, v5
	v_cvt_pk_bf16_f32 v5, v8, v9
	global_store_dwordx2 v[6:7], v[4:5], off offset:1024
	v_cvt_pk_bf16_f32 v4, v0, v1
	v_cvt_pk_bf16_f32 v5, v2, v3
	v_pk_fma_f32 v[0:1], v[36:37], v[0:1], v[66:67]
	v_pk_fma_f32 v[2:3], v[46:47], v[2:3], v[68:69]
	v_cvt_pk_bf16_f32 v0, v0, v1
	v_cvt_pk_bf16_f32 v1, v2, v3
	global_store_dwordx2 v[32:33], v[4:5], off offset:1536
	global_store_dwordx2 v[6:7], v[0:1], off offset:1536
	s_cbranch_scc0 .LBB0_1056
